# v59 + scan waves issue the next chunk's first-step vector reads one step before the chunk boundary (after the progress-flag check), consumers renamed to v224-239, all lgkmcnt waits recomputed
# speedup vs baseline: 1.0017x; 1.0017x over previous
.Lw_fwd:
	global_load_dwordx4 v[192:195], v118, s[56:57]
	s_add_u32 s56, s56, s58
	s_addc_u32 s57, s57, s59
	global_load_dwordx4 v[196:199], v118, s[56:57]
	s_add_u32 s56, s56, s58
	s_addc_u32 s57, s57, s59
	global_load_dwordx4 v[200:203], v118, s[56:57]
	s_add_u32 s56, s56, s58
	s_addc_u32 s57, s57, s59
	global_load_dwordx4 v[204:207], v118, s[56:57]
	s_add_u32 s56, s56, s58
	s_addc_u32 s57, s57, s59
	ds_read_b128 v[224:227], v118
	ds_read_b128 v[228:231], v118 offset:512
	ds_read_b128 v[232:235], v118 offset:768
	ds_read_b128 v[236:239], v118 offset:1024
	s_waitcnt lgkmcnt(0)
.LBB0_833:
	global_load_dwordx4 v[208:211], v118, s[56:57]
	s_add_u32 s56, s56, s58
	s_addc_u32 s57, s57, s59
	s_waitcnt lgkmcnt(5)
	v_pk_mul_f32 v[64:65], v[22:23], v[226:227]
	v_pk_mul_f32 v[36:37], v[8:9], v[226:227]
	v_pk_fma_f32 v[64:65], v[24:25], v[224:225], v[64:65]
	v_pk_fma_f32 v[34:35], v[6:7], v[224:225], v[36:37]
	v_add_f32_e32 v36, v64, v65
	v_add_f32_e32 v34, v34, v35
	v_add_u32_e32 v121, 0xa000, v110
	v_add_f32_dpp v36, v36, v36 row_ror:8 row_mask:0xf bank_mask:0xf bound_ctrl:1
	v_add_f32_dpp v34, v34, v34 row_ror:8 row_mask:0xf bank_mask:0xf bound_ctrl:1
	ds_read2_b32 v[62:63], v121 offset1:4
	ds_read_b128 v[66:69], v118 offset:1280
	global_load_dwordx4 v[212:215], v118, s[56:57]
	s_add_u32 s56, s56, s58
	s_addc_u32 s57, s57, s59
	ds_read_b128 v[90:93], v118 offset:1792
	ds_read_b128 v[94:97], v118 offset:2048
	ds_read_b128 v[102:105], v118 offset:2304
	ds_read2_b32 v[98:99], v121 offset0:32 offset1:36
	ds_read_b128 v[78:81], v118 offset:2560
	global_load_dwordx4 v[216:219], v118, s[56:57]
	s_add_u32 s56, s56, s58
	s_addc_u32 s57, s57, s59
	ds_read_b128 v[46:49], v118 offset:3072
	ds_read_b128 v[50:53], v118 offset:3328
	ds_read_b128 v[10:13], v118 offset:3584
	ds_read2_b32 v[84:85], v121 offset0:64 offset1:68
	ds_read_b128 v[70:73], v118 offset:3840
	global_load_dwordx4 v[220:223], v118, s[56:57]
	s_add_u32 s56, s56, s58
	s_addc_u32 s57, s57, s59
	ds_read_b128 v[26:29], v118 offset:4352
	ds_read_b128 v[30:33], v118 offset:4608
	ds_read_b128 v[2:5], v118 offset:4864
	ds_read2_b32 v[82:83], v121 offset0:96 offset1:100
	v_add_f32_dpp v36, v36, v36 row_ror:4 row_mask:0xf bank_mask:0xf bound_ctrl:1
	v_add_f32_dpp v34, v34, v34 row_ror:4 row_mask:0xf bank_mask:0xf bound_ctrl:1
	s_waitcnt lgkmcnt(12)
	v_mov_b32_e32 v64, v63
	v_add_f32_dpp v36, v36, v36 row_ror:2 row_mask:0xf bank_mask:0xf bound_ctrl:1
	v_add_f32_dpp v34, v34, v34 row_ror:2 row_mask:0xf bank_mask:0xf bound_ctrl:1
	v_add_u32_e32 v117, 0xa400, v110
	v_add_f32_dpp v36, v36, v36 row_ror:1 row_mask:0xf bank_mask:0xf bound_ctrl:1
	v_pk_mul_f32 v[74:75], v[228:229], v[36:37] op_sel_hi:[1,0]
	v_add_f32_dpp v34, v34, v34 row_ror:1 row_mask:0xf bank_mask:0xf bound_ctrl:1
	v_pk_fma_f32 v[74:75], v[232:233], v[62:63], v[74:75] op_sel_hi:[1,0,1]
	v_add_u32_e32 v120, 0xa800, v110
	s_waitcnt vmcnt(7)
	v_pk_fma_f32 v[106:107], v[24:25], v[192:193], v[74:75]
	v_pk_mul_f32 v[24:25], v[230:231], v[36:37] op_sel_hi:[1,0]
	v_add_u32_e32 v114, 0xac00, v110
	v_pk_fma_f32 v[24:25], v[234:235], v[62:63], v[24:25] op_sel_hi:[1,0,1]
	s_add_i32 s4, s4, 4
	v_pk_fma_f32 v[36:37], v[22:23], v[194:195], v[24:25]
	v_pk_mul_f32 v[22:23], v[228:229], v[34:35] op_sel_hi:[1,0]
	s_cmpk_gt_u32 s4, 0x1fb
	v_pk_fma_f32 v[22:23], v[232:233], v[64:65], v[22:23] op_sel_hi:[1,0,1]
	s_nop 0
	v_pk_fma_f32 v[42:43], v[6:7], v[192:193], v[22:23]
	v_pk_mul_f32 v[6:7], v[230:231], v[34:35] op_sel_hi:[1,0]
	v_pk_mul_f32 v[44:45], v[68:69], v[36:37]
	v_pk_fma_f32 v[6:7], v[234:235], v[64:65], v[6:7] op_sel_hi:[1,0,1]
	v_pk_fma_f32 v[44:45], v[66:67], v[106:107], v[44:45]
	v_pk_fma_f32 v[34:35], v[8:9], v[194:195], v[6:7]
	v_add_f32_e32 v44, v44, v45
	v_pk_mul_f32 v[54:55], v[68:69], v[34:35]
	v_pk_mul_f32 v[6:7], v[238:239], v[36:37]
	v_pk_fma_f32 v[54:55], v[66:67], v[42:43], v[54:55]
	v_add_f32_dpp v44, v44, v44 row_ror:8 row_mask:0xf bank_mask:0xf bound_ctrl:1
	v_add_f32_e32 v45, v54, v55
	v_pk_mul_f32 v[8:9], v[238:239], v[34:35]
	v_add_f32_dpp v44, v44, v44 row_ror:4 row_mask:0xf bank_mask:0xf bound_ctrl:1
	v_add_f32_dpp v45, v45, v45 row_ror:8 row_mask:0xf bank_mask:0xf bound_ctrl:1
	v_pk_fma_f32 v[6:7], v[236:237], v[106:107], v[6:7]
	v_add_f32_dpp v44, v44, v44 row_ror:2 row_mask:0xf bank_mask:0xf bound_ctrl:1
	v_add_f32_dpp v45, v45, v45 row_ror:4 row_mask:0xf bank_mask:0xf bound_ctrl:1
	v_pk_fma_f32 v[8:9], v[236:237], v[42:43], v[8:9]
	v_add_f32_dpp v44, v44, v44 row_ror:1 row_mask:0xf bank_mask:0xf bound_ctrl:1
	v_add_f32_dpp v45, v45, v45 row_ror:2 row_mask:0xf bank_mask:0xf bound_ctrl:1
	v_pk_mul_f32 v[58:59], v[90:91], v[44:45] op_sel_hi:[1,0]
	s_waitcnt lgkmcnt(10)
	v_mov_b32_e32 v56, v99
	v_add_f32_dpp v54, v45, v45 row_ror:1 row_mask:0xf bank_mask:0xf bound_ctrl:1
	v_pk_mul_f32 v[44:45], v[92:93], v[44:45] op_sel_hi:[1,0]
	v_pk_fma_f32 v[58:59], v[94:95], v[98:99], v[58:59] op_sel_hi:[1,0,1]
	v_pk_fma_f32 v[44:45], v[96:97], v[98:99], v[44:45] op_sel_hi:[1,0,1]
	s_waitcnt vmcnt(6)
	v_pk_fma_f32 v[106:107], v[196:197], v[106:107], v[58:59]
	v_pk_fma_f32 v[108:109], v[198:199], v[36:37], v[44:45]
	v_pk_mul_f32 v[36:37], v[90:91], v[54:55] op_sel_hi:[1,0]
	s_waitcnt lgkmcnt(9)
	v_pk_mul_f32 v[90:91], v[80:81], v[108:109]
	v_pk_fma_f32 v[36:37], v[94:95], v[56:57], v[36:37] op_sel_hi:[1,0,1]
	v_pk_fma_f32 v[90:91], v[78:79], v[106:107], v[90:91]
	v_pk_fma_f32 v[86:87], v[196:197], v[42:43], v[36:37]
	v_pk_mul_f32 v[36:37], v[92:93], v[54:55] op_sel_hi:[1,0]
	v_add_f32_e32 v6, v6, v7
	v_pk_fma_f32 v[36:37], v[96:97], v[56:57], v[36:37] op_sel_hi:[1,0,1]
	v_add_f32_e32 v7, v8, v9
	v_pk_fma_f32 v[88:89], v[198:199], v[34:35], v[36:37]
	v_pk_mul_f32 v[34:35], v[104:105], v[108:109]
	v_pk_mul_f32 v[80:81], v[80:81], v[88:89]
	v_pk_mul_f32 v[36:37], v[104:105], v[88:89]
	v_pk_fma_f32 v[78:79], v[78:79], v[86:87], v[80:81]
	v_add_f32_e32 v80, v90, v91
	v_add_f32_e32 v78, v78, v79
	s_waitcnt lgkmcnt(5)
	v_mov_b32_e32 v90, v85
	v_add_f32_dpp v80, v80, v80 row_ror:8 row_mask:0xf bank_mask:0xf bound_ctrl:1
	v_add_f32_dpp v78, v78, v78 row_ror:8 row_mask:0xf bank_mask:0xf bound_ctrl:1
	v_pk_fma_f32 v[36:37], v[102:103], v[86:87], v[36:37]
	v_add_f32_dpp v80, v80, v80 row_ror:4 row_mask:0xf bank_mask:0xf bound_ctrl:1
	v_add_f32_dpp v78, v78, v78 row_ror:4 row_mask:0xf bank_mask:0xf bound_ctrl:1
	v_pk_fma_f32 v[34:35], v[102:103], v[106:107], v[34:35]
	v_add_f32_dpp v80, v80, v80 row_ror:2 row_mask:0xf bank_mask:0xf bound_ctrl:1
	v_add_f32_dpp v78, v78, v78 row_ror:2 row_mask:0xf bank_mask:0xf bound_ctrl:1
	ds_write2st64_b32 v111, v6, v7 offset0:176 offset1:177
	v_add_f32_dpp v80, v80, v80 row_ror:1 row_mask:0xf bank_mask:0xf bound_ctrl:1
	v_add_f32_dpp v78, v78, v78 row_ror:1 row_mask:0xf bank_mask:0xf bound_ctrl:1
	v_pk_mul_f32 v[92:93], v[46:47], v[80:81] op_sel_hi:[1,0]
	v_pk_mul_f32 v[46:47], v[46:47], v[78:79] op_sel_hi:[1,0]
	v_pk_fma_f32 v[92:93], v[50:51], v[84:85], v[92:93] op_sel_hi:[1,0,1]
	v_pk_mul_f32 v[80:81], v[48:49], v[80:81] op_sel_hi:[1,0]
	v_pk_fma_f32 v[46:47], v[50:51], v[90:91], v[46:47] op_sel_hi:[1,0,1]
	s_waitcnt vmcnt(5)
	v_pk_fma_f32 v[94:95], v[200:201], v[106:107], v[92:93]
	v_pk_fma_f32 v[80:81], v[52:53], v[84:85], v[80:81] op_sel_hi:[1,0,1]
	v_pk_fma_f32 v[84:85], v[200:201], v[86:87], v[46:47]
	v_pk_mul_f32 v[18:19], v[48:49], v[78:79] op_sel_hi:[1,0]
	v_pk_fma_f32 v[80:81], v[202:203], v[108:109], v[80:81]
	v_pk_fma_f32 v[18:19], v[52:53], v[90:91], v[18:19] op_sel_hi:[1,0,1]
	s_waitcnt lgkmcnt(5)
	v_pk_mul_f32 v[86:87], v[72:73], v[80:81]
	v_pk_fma_f32 v[78:79], v[202:203], v[88:89], v[18:19]
	v_pk_fma_f32 v[86:87], v[70:71], v[94:95], v[86:87]
	v_pk_mul_f32 v[72:73], v[72:73], v[78:79]
	v_pk_mul_f32 v[18:19], v[12:13], v[80:81]
	v_pk_fma_f32 v[70:71], v[70:71], v[84:85], v[72:73]
	v_add_f32_e32 v72, v86, v87
	v_add_f32_e32 v70, v70, v71
	s_waitcnt lgkmcnt(1)
	v_mov_b32_e32 v86, v83
	v_add_f32_dpp v72, v72, v72 row_ror:8 row_mask:0xf bank_mask:0xf bound_ctrl:1
	v_add_f32_dpp v70, v70, v70 row_ror:8 row_mask:0xf bank_mask:0xf bound_ctrl:1
	v_pk_mul_f32 v[12:13], v[12:13], v[78:79]
	v_add_f32_dpp v72, v72, v72 row_ror:4 row_mask:0xf bank_mask:0xf bound_ctrl:1
	v_add_f32_dpp v70, v70, v70 row_ror:4 row_mask:0xf bank_mask:0xf bound_ctrl:1
	v_add_f32_e32 v34, v34, v35
	v_add_f32_dpp v72, v72, v72 row_ror:2 row_mask:0xf bank_mask:0xf bound_ctrl:1
	v_add_f32_dpp v70, v70, v70 row_ror:2 row_mask:0xf bank_mask:0xf bound_ctrl:1
	v_add_f32_e32 v35, v36, v37
	v_add_f32_dpp v72, v72, v72 row_ror:1 row_mask:0xf bank_mask:0xf bound_ctrl:1
	v_add_f32_dpp v70, v70, v70 row_ror:1 row_mask:0xf bank_mask:0xf bound_ctrl:1
	v_pk_mul_f32 v[88:89], v[26:27], v[72:73] op_sel_hi:[1,0]
	v_pk_mul_f32 v[26:27], v[26:27], v[70:71] op_sel_hi:[1,0]
	v_pk_fma_f32 v[88:89], v[30:31], v[82:83], v[88:89] op_sel_hi:[1,0,1]
	v_pk_fma_f32 v[26:27], v[30:31], v[86:87], v[26:27] op_sel_hi:[1,0,1]
	s_waitcnt vmcnt(4)
	v_pk_fma_f32 v[106:107], v[204:205], v[94:95], v[88:89]
	v_pk_mul_f32 v[72:73], v[28:29], v[72:73] op_sel_hi:[1,0]
	v_pk_fma_f32 v[26:27], v[204:205], v[84:85], v[26:27]
	v_pk_mul_f32 v[14:15], v[28:29], v[70:71] op_sel_hi:[1,0]
	v_pk_fma_f32 v[72:73], v[32:33], v[82:83], v[72:73] op_sel_hi:[1,0,1]
	v_pk_fma_f32 v[14:15], v[32:33], v[86:87], v[14:15] op_sel_hi:[1,0,1]
	v_pk_fma_f32 v[72:73], v[206:207], v[80:81], v[72:73]
	v_pk_fma_f32 v[28:29], v[206:207], v[78:79], v[14:15]
	v_pk_fma_f32 v[18:19], v[10:11], v[94:95], v[18:19]
	v_pk_fma_f32 v[10:11], v[10:11], v[84:85], v[12:13]
	v_pk_mul_f32 v[14:15], v[4:5], v[72:73]
	v_pk_mul_f32 v[4:5], v[4:5], v[28:29]
	ds_read_b128 v[74:77], v118 offset:5120
	global_load_dwordx4 v[192:195], v118, s[56:57]
	s_add_u32 s56, s56, s58
	s_addc_u32 s57, s57, s59
	ds_read_b128 v[38:41], v118 offset:5632
	ds_read_b128 v[62:65], v118 offset:5888
	ds_read_b128 v[6:9], v118 offset:6144
	ds_read2_b32 v[100:101], v121 offset0:128 offset1:132
	ds_write2st64_b32 v111, v34, v35 offset0:184 offset1:185
	v_add_f32_e32 v12, v18, v19
	v_add_f32_e32 v10, v10, v11
	v_pk_fma_f32 v[14:15], v[2:3], v[106:107], v[14:15]
	v_pk_fma_f32 v[2:3], v[2:3], v[26:27], v[4:5]
	ds_read_b128 v[66:69], v118 offset:6400
	global_load_dwordx4 v[196:199], v118, s[56:57]
	s_add_u32 s56, s56, s58
	s_addc_u32 s57, s57, s59
	ds_read_b128 v[54:57], v118 offset:6912
	ds_read_b128 v[58:61], v118 offset:7168
	ds_read_b128 v[34:37], v118 offset:7424
	ds_read2_b32 v[98:99], v121 offset0:160 offset1:164
	ds_write2st64_b32 v111, v12, v10 offset0:192 offset1:193
	v_add_f32_e32 v4, v14, v15
	v_add_f32_e32 v2, v2, v3
	ds_read_b128 v[90:93], v118 offset:7680
	global_load_dwordx4 v[200:203], v118, s[56:57]
	s_add_u32 s56, s56, s58
	s_addc_u32 s57, s57, s59
	ds_read_b128 v[46:49], v118 offset:8192
	ds_read_b128 v[50:53], v118 offset:8448
	ds_read_b128 v[10:13], v118 offset:8704
	ds_read2_b32 v[102:103], v121 offset0:192 offset1:196
	ds_write2st64_b32 v111, v4, v2 offset0:200 offset1:201
	s_waitcnt lgkmcnt(13)
	v_pk_mul_f32 v[2:3], v[76:77], v[72:73]
	v_pk_mul_f32 v[4:5], v[76:77], v[28:29]
	v_pk_fma_f32 v[2:3], v[74:75], v[106:107], v[2:3]
	v_pk_fma_f32 v[4:5], v[74:75], v[26:27], v[4:5]
	v_add_f32_e32 v2, v2, v3
	v_add_f32_e32 v3, v4, v5
	v_mov_b32_e32 v70, v101
	v_add_f32_dpp v2, v2, v2 row_ror:8 row_mask:0xf bank_mask:0xf bound_ctrl:1
	v_add_f32_dpp v3, v3, v3 row_ror:8 row_mask:0xf bank_mask:0xf bound_ctrl:1
	ds_read_b128 v[94:97], v118 offset:8960
	global_load_dwordx4 v[204:207], v118, s[56:57]
	s_add_u32 s56, s56, s58
	s_addc_u32 s57, s57, s59
	ds_read_b128 v[82:85], v118 offset:9472
	ds_read_b128 v[86:89], v118 offset:9728
	ds_read_b128 v[14:17], v118 offset:9984
	ds_read2_b32 v[104:105], v121 offset0:224 offset1:228
	v_add_f32_dpp v2, v2, v2 row_ror:4 row_mask:0xf bank_mask:0xf bound_ctrl:1
	v_add_f32_dpp v3, v3, v3 row_ror:4 row_mask:0xf bank_mask:0xf bound_ctrl:1
	s_nop 0
	v_add_f32_dpp v2, v2, v2 row_ror:2 row_mask:0xf bank_mask:0xf bound_ctrl:1
	v_add_f32_dpp v3, v3, v3 row_ror:2 row_mask:0xf bank_mask:0xf bound_ctrl:1
	s_nop 0
	v_add_f32_dpp v2, v2, v2 row_ror:1 row_mask:0xf bank_mask:0xf bound_ctrl:1
	v_add_f32_dpp v4, v3, v3 row_ror:1 row_mask:0xf bank_mask:0xf bound_ctrl:1
	v_pk_mul_f32 v[74:75], v[38:39], v[2:3] op_sel_hi:[1,0]
	v_pk_mul_f32 v[2:3], v[40:41], v[2:3] op_sel_hi:[1,0]
	v_pk_fma_f32 v[74:75], v[62:63], v[100:101], v[74:75] op_sel_hi:[1,0,1]
	v_pk_fma_f32 v[2:3], v[64:65], v[100:101], v[2:3] op_sel_hi:[1,0,1]
	s_waitcnt vmcnt(7)
	v_pk_fma_f32 v[74:75], v[208:209], v[106:107], v[74:75]
	v_pk_fma_f32 v[72:73], v[210:211], v[72:73], v[2:3]
	v_pk_mul_f32 v[2:3], v[38:39], v[4:5] op_sel_hi:[1,0]
	s_nop 0
	v_pk_fma_f32 v[2:3], v[62:63], v[70:71], v[2:3] op_sel_hi:[1,0,1]
	s_nop 0
	v_pk_fma_f32 v[62:63], v[208:209], v[26:27], v[2:3]
	v_pk_mul_f32 v[2:3], v[40:41], v[4:5] op_sel_hi:[1,0]
	s_nop 0
	v_pk_fma_f32 v[2:3], v[64:65], v[70:71], v[2:3] op_sel_hi:[1,0,1]
	s_waitcnt lgkmcnt(12)
	v_pk_mul_f32 v[70:71], v[68:69], v[72:73]
	v_pk_fma_f32 v[64:65], v[210:211], v[28:29], v[2:3]
	v_pk_fma_f32 v[70:71], v[66:67], v[74:75], v[70:71]
	v_pk_mul_f32 v[68:69], v[68:69], v[64:65]
	v_pk_mul_f32 v[2:3], v[8:9], v[72:73]
	v_pk_fma_f32 v[66:67], v[66:67], v[62:63], v[68:69]
	v_add_f32_e32 v68, v70, v71
	v_add_f32_e32 v66, v66, v67
	v_mov_b32_e32 v70, v99
	v_add_f32_dpp v68, v68, v68 row_ror:8 row_mask:0xf bank_mask:0xf bound_ctrl:1
	v_add_f32_dpp v66, v66, v66 row_ror:8 row_mask:0xf bank_mask:0xf bound_ctrl:1
	v_pk_mul_f32 v[4:5], v[8:9], v[64:65]
	v_add_f32_dpp v68, v68, v68 row_ror:4 row_mask:0xf bank_mask:0xf bound_ctrl:1
	v_add_f32_dpp v66, v66, v66 row_ror:4 row_mask:0xf bank_mask:0xf bound_ctrl:1
	v_pk_fma_f32 v[2:3], v[6:7], v[74:75], v[2:3]
	v_add_f32_dpp v68, v68, v68 row_ror:2 row_mask:0xf bank_mask:0xf bound_ctrl:1
	v_add_f32_dpp v66, v66, v66 row_ror:2 row_mask:0xf bank_mask:0xf bound_ctrl:1
	v_pk_fma_f32 v[4:5], v[6:7], v[62:63], v[4:5]
	v_add_f32_dpp v68, v68, v68 row_ror:1 row_mask:0xf bank_mask:0xf bound_ctrl:1
	v_add_f32_dpp v66, v66, v66 row_ror:1 row_mask:0xf bank_mask:0xf bound_ctrl:1
	v_pk_mul_f32 v[76:77], v[54:55], v[68:69] op_sel_hi:[1,0]
	v_pk_mul_f32 v[54:55], v[54:55], v[66:67] op_sel_hi:[1,0]
	v_pk_fma_f32 v[76:77], v[58:59], v[98:99], v[76:77] op_sel_hi:[1,0,1]
	v_pk_fma_f32 v[54:55], v[58:59], v[70:71], v[54:55] op_sel_hi:[1,0,1]
	s_waitcnt vmcnt(6)
	v_pk_fma_f32 v[106:107], v[212:213], v[74:75], v[76:77]
	v_pk_mul_f32 v[68:69], v[56:57], v[68:69] op_sel_hi:[1,0]
	v_pk_fma_f32 v[42:43], v[212:213], v[62:63], v[54:55]
	v_pk_mul_f32 v[54:55], v[56:57], v[66:67] op_sel_hi:[1,0]
	v_pk_fma_f32 v[68:69], v[60:61], v[98:99], v[68:69] op_sel_hi:[1,0,1]
	v_pk_fma_f32 v[54:55], v[60:61], v[70:71], v[54:55] op_sel_hi:[1,0,1]
	v_pk_fma_f32 v[108:109], v[214:215], v[72:73], v[68:69]
	v_pk_fma_f32 v[44:45], v[214:215], v[64:65], v[54:55]
	v_pk_mul_f32 v[54:55], v[36:37], v[108:109]
	v_pk_mul_f32 v[36:37], v[36:37], v[44:45]
	v_add_f32_e32 v2, v2, v3
	v_add_f32_e32 v3, v4, v5
	v_pk_fma_f32 v[54:55], v[34:35], v[106:107], v[54:55]
	v_pk_fma_f32 v[34:35], v[34:35], v[42:43], v[36:37]
	ds_write2st64_b32 v111, v2, v3 offset0:208 offset1:209
	v_add_f32_e32 v36, v54, v55
	v_add_f32_e32 v34, v34, v35
	ds_read_b128 v[38:41], v118 offset:10240
	global_load_dwordx4 v[208:211], v118, s[56:57]
	s_add_u32 s56, s56, s58
	s_addc_u32 s57, s57, s59
	ds_read_b128 v[22:25], v118 offset:10752
	ds_read_b128 v[26:29], v118 offset:11008
	ds_read_b128 v[2:5], v118 offset:11264
	ds_write2st64_b32 v111, v36, v34 offset0:216 offset1:217
	s_waitcnt lgkmcnt(12)
	v_pk_mul_f32 v[34:35], v[92:93], v[108:109]
	v_pk_mul_f32 v[36:37], v[92:93], v[44:45]
	v_pk_fma_f32 v[34:35], v[90:91], v[106:107], v[34:35]
	v_pk_fma_f32 v[36:37], v[90:91], v[42:43], v[36:37]
	v_add_f32_e32 v34, v34, v35
	v_add_f32_e32 v35, v36, v37
	v_mov_b32_e32 v54, v103
	v_add_f32_dpp v34, v34, v34 row_ror:8 row_mask:0xf bank_mask:0xf bound_ctrl:1
	v_add_f32_dpp v35, v35, v35 row_ror:8 row_mask:0xf bank_mask:0xf bound_ctrl:1
	ds_read2_b32 v[100:101], v117 offset1:4
	v_add_f32_dpp v34, v34, v34 row_ror:4 row_mask:0xf bank_mask:0xf bound_ctrl:1
	v_add_f32_dpp v35, v35, v35 row_ror:4 row_mask:0xf bank_mask:0xf bound_ctrl:1
	ds_read_b128 v[78:81], v118 offset:11520
	global_load_dwordx4 v[212:215], v118, s[56:57]
	s_add_u32 s56, s56, s58
	s_addc_u32 s57, s57, s59
	ds_read_b128 v[70:73], v118 offset:12032
	ds_read_b128 v[74:77], v118 offset:12288
	ds_read_b128 v[62:65], v118 offset:12544
	ds_read2_b32 v[98:99], v117 offset0:32 offset1:36
	v_add_f32_dpp v34, v34, v34 row_ror:2 row_mask:0xf bank_mask:0xf bound_ctrl:1
	v_add_f32_dpp v35, v35, v35 row_ror:2 row_mask:0xf bank_mask:0xf bound_ctrl:1
	s_nop 0
	v_add_f32_dpp v34, v34, v34 row_ror:1 row_mask:0xf bank_mask:0xf bound_ctrl:1
	v_add_f32_dpp v36, v35, v35 row_ror:1 row_mask:0xf bank_mask:0xf bound_ctrl:1
	v_pk_mul_f32 v[56:57], v[46:47], v[34:35] op_sel_hi:[1,0]
	v_pk_mul_f32 v[34:35], v[48:49], v[34:35] op_sel_hi:[1,0]
	v_pk_mul_f32 v[46:47], v[46:47], v[36:37] op_sel_hi:[1,0]
	v_pk_mul_f32 v[36:37], v[48:49], v[36:37] op_sel_hi:[1,0]
	v_pk_fma_f32 v[34:35], v[52:53], v[102:103], v[34:35] op_sel_hi:[1,0,1]
	v_pk_fma_f32 v[36:37], v[52:53], v[54:55], v[36:37] op_sel_hi:[1,0,1]
	v_pk_fma_f32 v[56:57], v[50:51], v[102:103], v[56:57] op_sel_hi:[1,0,1]
	s_waitcnt vmcnt(7)
	v_pk_fma_f32 v[34:35], v[218:219], v[108:109], v[34:35]
	v_pk_fma_f32 v[46:47], v[50:51], v[54:55], v[46:47] op_sel_hi:[1,0,1]
	v_pk_fma_f32 v[20:21], v[218:219], v[44:45], v[36:37]
	v_pk_fma_f32 v[92:93], v[216:217], v[106:107], v[56:57]
	v_pk_fma_f32 v[18:19], v[216:217], v[42:43], v[46:47]
	v_pk_mul_f32 v[36:37], v[12:13], v[34:35]
	v_pk_mul_f32 v[12:13], v[12:13], v[20:21]
	v_pk_fma_f32 v[36:37], v[10:11], v[92:93], v[36:37]
	v_pk_fma_f32 v[10:11], v[10:11], v[18:19], v[12:13]
	v_add_f32_e32 v12, v36, v37
	v_add_f32_e32 v10, v10, v11
	ds_write2st64_b32 v111, v12, v10 offset0:224 offset1:225
	s_waitcnt lgkmcnt(13)
	v_pk_mul_f32 v[10:11], v[96:97], v[34:35]
	v_pk_mul_f32 v[12:13], v[96:97], v[20:21]
	v_pk_fma_f32 v[10:11], v[94:95], v[92:93], v[10:11]
	v_pk_fma_f32 v[12:13], v[94:95], v[18:19], v[12:13]
	v_add_f32_e32 v10, v10, v11
	v_add_f32_e32 v11, v12, v13
	v_mov_b32_e32 v36, v105
	v_add_f32_dpp v10, v10, v10 row_ror:8 row_mask:0xf bank_mask:0xf bound_ctrl:1
	v_add_f32_dpp v11, v11, v11 row_ror:8 row_mask:0xf bank_mask:0xf bound_ctrl:1
	s_waitcnt lgkmcnt(6)
	v_mov_b32_e32 v102, v101
	v_add_f32_dpp v10, v10, v10 row_ror:4 row_mask:0xf bank_mask:0xf bound_ctrl:1
	v_add_f32_dpp v11, v11, v11 row_ror:4 row_mask:0xf bank_mask:0xf bound_ctrl:1
	ds_read_b128 v[58:61], v118 offset:12800
	global_load_dwordx4 v[216:219], v118, s[56:57]
	s_add_u32 s56, s56, s58
	s_addc_u32 s57, s57, s59
	ds_read_b128 v[50:53], v118 offset:13312
	ds_read_b128 v[54:57], v118 offset:13568
	ds_read_b128 v[42:45], v118 offset:13824
	ds_read2_b32 v[90:91], v117 offset0:64 offset1:68
	v_add_f32_dpp v10, v10, v10 row_ror:2 row_mask:0xf bank_mask:0xf bound_ctrl:1
	v_add_f32_dpp v11, v11, v11 row_ror:2 row_mask:0xf bank_mask:0xf bound_ctrl:1
	s_nop 0
	v_add_f32_dpp v10, v10, v10 row_ror:1 row_mask:0xf bank_mask:0xf bound_ctrl:1
	v_add_f32_dpp v12, v11, v11 row_ror:1 row_mask:0xf bank_mask:0xf bound_ctrl:1
	v_pk_mul_f32 v[94:95], v[82:83], v[10:11] op_sel_hi:[1,0]
	v_pk_mul_f32 v[10:11], v[84:85], v[10:11] op_sel_hi:[1,0]
	v_pk_fma_f32 v[94:95], v[86:87], v[104:105], v[94:95] op_sel_hi:[1,0,1]
	v_pk_fma_f32 v[10:11], v[88:89], v[104:105], v[10:11] op_sel_hi:[1,0,1]
	s_waitcnt vmcnt(7)
	v_pk_fma_f32 v[92:93], v[220:221], v[92:93], v[94:95]
	v_pk_fma_f32 v[94:95], v[222:223], v[34:35], v[10:11]
	v_pk_mul_f32 v[10:11], v[82:83], v[12:13] op_sel_hi:[1,0]
	s_nop 0
	v_pk_fma_f32 v[10:11], v[86:87], v[36:37], v[10:11] op_sel_hi:[1,0,1]
	v_pk_mul_f32 v[86:87], v[40:41], v[94:95]
	v_pk_fma_f32 v[96:97], v[220:221], v[18:19], v[10:11]
	v_pk_mul_f32 v[10:11], v[84:85], v[12:13] op_sel_hi:[1,0]
	v_pk_fma_f32 v[86:87], v[38:39], v[92:93], v[86:87]
	v_pk_fma_f32 v[10:11], v[88:89], v[36:37], v[10:11] op_sel_hi:[1,0,1]
	s_nop 0
	v_pk_fma_f32 v[84:85], v[222:223], v[20:21], v[10:11]
	v_pk_mul_f32 v[10:11], v[16:17], v[94:95]
	v_pk_mul_f32 v[40:41], v[40:41], v[84:85]
	v_pk_fma_f32 v[10:11], v[14:15], v[92:93], v[10:11]
	v_pk_fma_f32 v[38:39], v[38:39], v[96:97], v[40:41]
	v_add_f32_e32 v40, v86, v87
	v_add_f32_e32 v38, v38, v39
	v_pk_mul_f32 v[12:13], v[16:17], v[84:85]
	v_add_f32_dpp v40, v40, v40 row_ror:8 row_mask:0xf bank_mask:0xf bound_ctrl:1
	v_add_f32_dpp v38, v38, v38 row_ror:8 row_mask:0xf bank_mask:0xf bound_ctrl:1
	v_pk_fma_f32 v[12:13], v[14:15], v[96:97], v[12:13]
	v_add_f32_dpp v40, v40, v40 row_ror:4 row_mask:0xf bank_mask:0xf bound_ctrl:1
	v_add_f32_dpp v38, v38, v38 row_ror:4 row_mask:0xf bank_mask:0xf bound_ctrl:1
	v_add_f32_e32 v10, v10, v11
	v_add_f32_dpp v40, v40, v40 row_ror:2 row_mask:0xf bank_mask:0xf bound_ctrl:1
	v_add_f32_dpp v38, v38, v38 row_ror:2 row_mask:0xf bank_mask:0xf bound_ctrl:1
	v_add_f32_e32 v11, v12, v13
	v_add_f32_dpp v40, v40, v40 row_ror:1 row_mask:0xf bank_mask:0xf bound_ctrl:1
	v_add_f32_dpp v38, v38, v38 row_ror:1 row_mask:0xf bank_mask:0xf bound_ctrl:1
	v_pk_mul_f32 v[86:87], v[22:23], v[40:41] op_sel_hi:[1,0]
	v_pk_mul_f32 v[22:23], v[22:23], v[38:39] op_sel_hi:[1,0]
	v_pk_fma_f32 v[86:87], v[26:27], v[100:101], v[86:87] op_sel_hi:[1,0,1]
	v_pk_fma_f32 v[22:23], v[26:27], v[102:103], v[22:23] op_sel_hi:[1,0,1]
	s_waitcnt vmcnt(6)
	v_pk_fma_f32 v[86:87], v[192:193], v[92:93], v[86:87]
	v_pk_mul_f32 v[40:41], v[24:25], v[40:41] op_sel_hi:[1,0]
	v_pk_fma_f32 v[92:93], v[192:193], v[96:97], v[22:23]
	v_pk_mul_f32 v[6:7], v[24:25], v[38:39] op_sel_hi:[1,0]
	v_pk_fma_f32 v[40:41], v[28:29], v[100:101], v[40:41] op_sel_hi:[1,0,1]
	v_pk_fma_f32 v[6:7], v[28:29], v[102:103], v[6:7] op_sel_hi:[1,0,1]
	v_pk_fma_f32 v[88:89], v[194:195], v[94:95], v[40:41]
	v_pk_fma_f32 v[94:95], v[194:195], v[84:85], v[6:7]
	s_waitcnt lgkmcnt(10)
	v_pk_mul_f32 v[96:97], v[80:81], v[88:89]
	v_pk_mul_f32 v[80:81], v[80:81], v[94:95]
	v_pk_fma_f32 v[96:97], v[78:79], v[86:87], v[96:97]
	v_pk_fma_f32 v[78:79], v[78:79], v[92:93], v[80:81]
	v_add_f32_e32 v80, v96, v97
	v_add_f32_e32 v78, v78, v79
	s_waitcnt lgkmcnt(6)
	v_mov_b32_e32 v100, v99
	v_add_f32_dpp v80, v80, v80 row_ror:8 row_mask:0xf bank_mask:0xf bound_ctrl:1
	v_add_f32_dpp v78, v78, v78 row_ror:8 row_mask:0xf bank_mask:0xf bound_ctrl:1
	v_pk_mul_f32 v[6:7], v[4:5], v[88:89]
	v_add_f32_dpp v80, v80, v80 row_ror:4 row_mask:0xf bank_mask:0xf bound_ctrl:1
	v_add_f32_dpp v78, v78, v78 row_ror:4 row_mask:0xf bank_mask:0xf bound_ctrl:1
	v_pk_mul_f32 v[4:5], v[4:5], v[94:95]
	v_add_f32_dpp v80, v80, v80 row_ror:2 row_mask:0xf bank_mask:0xf bound_ctrl:1
	v_add_f32_dpp v78, v78, v78 row_ror:2 row_mask:0xf bank_mask:0xf bound_ctrl:1
	v_pk_fma_f32 v[6:7], v[2:3], v[86:87], v[6:7]
	v_add_f32_dpp v80, v80, v80 row_ror:1 row_mask:0xf bank_mask:0xf bound_ctrl:1
	v_add_f32_dpp v78, v78, v78 row_ror:1 row_mask:0xf bank_mask:0xf bound_ctrl:1
	v_pk_mul_f32 v[96:97], v[70:71], v[80:81] op_sel_hi:[1,0]
	v_pk_mul_f32 v[70:71], v[70:71], v[78:79] op_sel_hi:[1,0]
	v_pk_fma_f32 v[96:97], v[74:75], v[98:99], v[96:97] op_sel_hi:[1,0,1]
	v_pk_mul_f32 v[80:81], v[72:73], v[80:81] op_sel_hi:[1,0]
	v_pk_fma_f32 v[70:71], v[74:75], v[100:101], v[70:71] op_sel_hi:[1,0,1]
	s_waitcnt vmcnt(5)
	v_pk_fma_f32 v[96:97], v[196:197], v[86:87], v[96:97]
	v_pk_fma_f32 v[80:81], v[76:77], v[98:99], v[80:81] op_sel_hi:[1,0,1]
	v_pk_fma_f32 v[98:99], v[196:197], v[92:93], v[70:71]
	v_pk_mul_f32 v[66:67], v[72:73], v[78:79] op_sel_hi:[1,0]
	v_pk_fma_f32 v[88:89], v[198:199], v[88:89], v[80:81]
	v_pk_fma_f32 v[66:67], v[76:77], v[100:101], v[66:67] op_sel_hi:[1,0,1]
	v_pk_fma_f32 v[2:3], v[2:3], v[92:93], v[4:5]
	v_pk_fma_f32 v[100:101], v[198:199], v[94:95], v[66:67]
	s_waitcnt lgkmcnt(4)
	v_pk_mul_f32 v[92:93], v[60:61], v[88:89]
	v_pk_mul_f32 v[60:61], v[60:61], v[100:101]
	v_pk_fma_f32 v[92:93], v[58:59], v[96:97], v[92:93]
	v_pk_fma_f32 v[58:59], v[58:59], v[98:99], v[60:61]
	v_add_f32_e32 v60, v92, v93
	v_add_f32_e32 v58, v58, v59
	s_waitcnt lgkmcnt(0)
	v_mov_b32_e32 v102, v91
	v_add_f32_dpp v60, v60, v60 row_ror:8 row_mask:0xf bank_mask:0xf bound_ctrl:1
	v_add_f32_dpp v58, v58, v58 row_ror:8 row_mask:0xf bank_mask:0xf bound_ctrl:1
	ds_write2st64_b32 v111, v10, v11 offset0:232 offset1:233
	v_add_f32_dpp v60, v60, v60 row_ror:4 row_mask:0xf bank_mask:0xf bound_ctrl:1
	v_add_f32_dpp v58, v58, v58 row_ror:4 row_mask:0xf bank_mask:0xf bound_ctrl:1
	v_pk_mul_f32 v[66:67], v[64:65], v[88:89]
	v_add_f32_dpp v60, v60, v60 row_ror:2 row_mask:0xf bank_mask:0xf bound_ctrl:1
	v_add_f32_dpp v58, v58, v58 row_ror:2 row_mask:0xf bank_mask:0xf bound_ctrl:1
	ds_read_b128 v[10:13], v118 offset:14080
	global_load_dwordx4 v[220:223], v118, s[56:57]
	s_add_u32 s56, s56, s58
	s_addc_u32 s57, s57, s59
	ds_read_b128 v[18:21], v118 offset:14592
	ds_read_b128 v[34:37], v118 offset:14848
	ds_read_b128 v[30:33], v118 offset:15104
	ds_read2_b32 v[82:83], v117 offset0:96 offset1:100
	v_add_f32_dpp v60, v60, v60 row_ror:1 row_mask:0xf bank_mask:0xf bound_ctrl:1
	v_add_f32_dpp v58, v58, v58 row_ror:1 row_mask:0xf bank_mask:0xf bound_ctrl:1
	v_pk_mul_f32 v[92:93], v[50:51], v[60:61] op_sel_hi:[1,0]
	v_pk_mul_f32 v[50:51], v[50:51], v[58:59] op_sel_hi:[1,0]
	v_pk_fma_f32 v[92:93], v[54:55], v[90:91], v[92:93] op_sel_hi:[1,0,1]
	v_pk_fma_f32 v[50:51], v[54:55], v[102:103], v[50:51] op_sel_hi:[1,0,1]
	s_waitcnt vmcnt(5)
	v_pk_fma_f32 v[92:93], v[200:201], v[96:97], v[92:93]
	v_pk_mul_f32 v[60:61], v[52:53], v[60:61] op_sel_hi:[1,0]
	v_pk_fma_f32 v[94:95], v[200:201], v[98:99], v[50:51]
	v_pk_mul_f32 v[46:47], v[52:53], v[58:59] op_sel_hi:[1,0]
	v_pk_fma_f32 v[60:61], v[56:57], v[90:91], v[60:61] op_sel_hi:[1,0,1]
	v_pk_fma_f32 v[46:47], v[56:57], v[102:103], v[46:47] op_sel_hi:[1,0,1]
	v_pk_fma_f32 v[66:67], v[62:63], v[96:97], v[66:67]
	v_pk_mul_f32 v[64:65], v[64:65], v[100:101]
	v_pk_fma_f32 v[90:91], v[202:203], v[88:89], v[60:61]
	v_pk_fma_f32 v[96:97], v[202:203], v[100:101], v[46:47]
	v_pk_fma_f32 v[62:63], v[62:63], v[98:99], v[64:65]
	s_waitcnt lgkmcnt(4)
	v_pk_mul_f32 v[98:99], v[12:13], v[90:91]
	v_pk_mul_f32 v[12:13], v[12:13], v[96:97]
	v_pk_fma_f32 v[98:99], v[10:11], v[92:93], v[98:99]
	v_pk_fma_f32 v[10:11], v[10:11], v[94:95], v[12:13]
	v_add_f32_e32 v12, v98, v99
	v_add_f32_e32 v10, v10, v11
	s_waitcnt lgkmcnt(0)
	v_mov_b32_e32 v100, v83
	v_add_f32_dpp v12, v12, v12 row_ror:8 row_mask:0xf bank_mask:0xf bound_ctrl:1
	v_add_f32_dpp v10, v10, v10 row_ror:8 row_mask:0xf bank_mask:0xf bound_ctrl:1
	v_add_f32_e32 v4, v6, v7
	v_add_f32_dpp v12, v12, v12 row_ror:4 row_mask:0xf bank_mask:0xf bound_ctrl:1
	v_add_f32_dpp v10, v10, v10 row_ror:4 row_mask:0xf bank_mask:0xf bound_ctrl:1
	v_add_f32_e32 v2, v2, v3
	v_add_f32_dpp v12, v12, v12 row_ror:2 row_mask:0xf bank_mask:0xf bound_ctrl:1
	v_add_f32_dpp v10, v10, v10 row_ror:2 row_mask:0xf bank_mask:0xf bound_ctrl:1
	ds_write2st64_b32 v111, v4, v2 offset0:240 offset1:241
	v_add_f32_dpp v12, v12, v12 row_ror:1 row_mask:0xf bank_mask:0xf bound_ctrl:1
	v_add_f32_dpp v98, v10, v10 row_ror:1 row_mask:0xf bank_mask:0xf bound_ctrl:1
	v_pk_mul_f32 v[10:11], v[18:19], v[12:13] op_sel_hi:[1,0]
	v_pk_mul_f32 v[18:19], v[18:19], v[98:99] op_sel_hi:[1,0]
	v_pk_fma_f32 v[10:11], v[34:35], v[82:83], v[10:11] op_sel_hi:[1,0,1]
	v_pk_mul_f32 v[12:13], v[20:21], v[12:13] op_sel_hi:[1,0]
	v_pk_fma_f32 v[18:19], v[34:35], v[100:101], v[18:19] op_sel_hi:[1,0,1]
	s_waitcnt vmcnt(4)
	v_pk_fma_f32 v[10:11], v[204:205], v[92:93], v[10:11]
	v_pk_fma_f32 v[12:13], v[36:37], v[82:83], v[12:13] op_sel_hi:[1,0,1]
	v_pk_fma_f32 v[14:15], v[204:205], v[94:95], v[18:19]
	v_pk_mul_f32 v[18:19], v[20:21], v[98:99] op_sel_hi:[1,0]
	v_pk_fma_f32 v[12:13], v[206:207], v[90:91], v[12:13]
	v_pk_fma_f32 v[18:19], v[36:37], v[100:101], v[18:19] op_sel_hi:[1,0,1]
	ds_read_b128 v[6:9], v118 offset:15360
	global_load_dwordx4 v[192:195], v118, s[56:57]
	s_add_u32 s56, s56, s58
	s_addc_u32 s57, s57, s59
	ds_read_b128 v[22:25], v118 offset:15872
	ds_read_b128 v[26:29], v118 offset:16128
	ds_read_b128 v[38:41], v118 offset:16384
	ds_read2_b32 v[84:85], v117 offset0:128 offset1:132
	v_pk_fma_f32 v[16:17], v[206:207], v[96:97], v[18:19]
	s_waitcnt lgkmcnt(4)
	v_pk_mul_f32 v[98:99], v[8:9], v[12:13]
	v_pk_mul_f32 v[8:9], v[8:9], v[16:17]
	v_pk_fma_f32 v[98:99], v[6:7], v[10:11], v[98:99]
	v_pk_fma_f32 v[6:7], v[6:7], v[14:15], v[8:9]
	v_add_f32_e32 v8, v98, v99
	v_add_f32_e32 v6, v6, v7
	v_pk_mul_f32 v[18:19], v[32:33], v[12:13]
	v_add_f32_dpp v8, v8, v8 row_ror:8 row_mask:0xf bank_mask:0xf bound_ctrl:1
	v_add_f32_dpp v6, v6, v6 row_ror:8 row_mask:0xf bank_mask:0xf bound_ctrl:1
	s_waitcnt lgkmcnt(0)
	v_mov_b32_e32 v98, v85
	v_add_f32_dpp v8, v8, v8 row_ror:4 row_mask:0xf bank_mask:0xf bound_ctrl:1
	v_add_f32_dpp v6, v6, v6 row_ror:4 row_mask:0xf bank_mask:0xf bound_ctrl:1
	v_pk_mul_f32 v[46:47], v[44:45], v[90:91]
	v_add_f32_dpp v8, v8, v8 row_ror:2 row_mask:0xf bank_mask:0xf bound_ctrl:1
	v_add_f32_dpp v6, v6, v6 row_ror:2 row_mask:0xf bank_mask:0xf bound_ctrl:1
	v_pk_mul_f32 v[44:45], v[44:45], v[96:97]
	v_add_f32_dpp v8, v8, v8 row_ror:1 row_mask:0xf bank_mask:0xf bound_ctrl:1
	v_pk_mul_f32 v[100:101], v[22:23], v[8:9] op_sel_hi:[1,0]
	v_pk_mul_f32 v[8:9], v[24:25], v[8:9] op_sel_hi:[1,0]
	v_add_f32_dpp v6, v6, v6 row_ror:1 row_mask:0xf bank_mask:0xf bound_ctrl:1
	v_pk_fma_f32 v[8:9], v[28:29], v[84:85], v[8:9] op_sel_hi:[1,0,1]
	v_add_f32_e32 v64, v66, v67
	s_waitcnt vmcnt(4)
	v_pk_fma_f32 v[8:9], v[210:211], v[12:13], v[8:9]
	v_pk_mul_f32 v[12:13], v[22:23], v[6:7] op_sel_hi:[1,0]
	v_pk_mul_f32 v[6:7], v[24:25], v[6:7] op_sel_hi:[1,0]
	v_add_f32_e32 v62, v62, v63
	v_pk_fma_f32 v[6:7], v[28:29], v[98:99], v[6:7] op_sel_hi:[1,0,1]
	v_pk_fma_f32 v[46:47], v[42:43], v[92:93], v[46:47]
	v_pk_fma_f32 v[42:43], v[42:43], v[94:95], v[44:45]
	v_pk_mul_f32 v[20:21], v[32:33], v[16:17]
	v_pk_fma_f32 v[100:101], v[26:27], v[84:85], v[100:101] op_sel_hi:[1,0,1]
	v_pk_fma_f32 v[12:13], v[26:27], v[98:99], v[12:13] op_sel_hi:[1,0,1]
	v_pk_fma_f32 v[4:5], v[210:211], v[16:17], v[6:7]
	ds_write2st64_b32 v111, v64, v62 offset0:248 offset1:249
	v_add_f32_e32 v44, v46, v47
	v_add_f32_e32 v42, v42, v43
	v_pk_fma_f32 v[18:19], v[30:31], v[10:11], v[18:19]
	v_pk_fma_f32 v[20:21], v[30:31], v[14:15], v[20:21]
	v_pk_fma_f32 v[10:11], v[208:209], v[10:11], v[100:101]
	v_pk_fma_f32 v[2:3], v[208:209], v[14:15], v[12:13]
	v_pk_mul_f32 v[6:7], v[40:41], v[8:9]
	v_pk_mul_f32 v[12:13], v[40:41], v[4:5]
	ds_read_b128 v[62:65], v118 offset:16640
	global_load_dwordx4 v[196:199], v118, s[56:57]
	s_add_u32 s56, s56, s58
	s_addc_u32 s57, s57, s59
	ds_read_b128 v[70:73], v118 offset:17152
	ds_read_b128 v[74:77], v118 offset:17408
	ds_read_b128 v[78:81], v118 offset:17664
	ds_read2_b32 v[86:87], v117 offset0:160 offset1:164
	ds_write2st64_b32 v112, v44, v42 offset0:80 offset1:81
	v_add_f32_e32 v18, v18, v19
	v_add_f32_e32 v19, v20, v21
	v_pk_fma_f32 v[6:7], v[38:39], v[10:11], v[6:7]
	v_pk_fma_f32 v[12:13], v[38:39], v[2:3], v[12:13]
	ds_read_b128 v[46:49], v118 offset:17920
	global_load_dwordx4 v[200:203], v118, s[56:57]
	s_add_u32 s56, s56, s58
	s_addc_u32 s57, s57, s59
	ds_read_b128 v[50:53], v118 offset:18432
	ds_read_b128 v[54:57], v118 offset:18688
	ds_read_b128 v[58:61], v118 offset:18944
	ds_read2_b32 v[88:89], v117 offset0:192 offset1:196
	ds_write2st64_b32 v112, v18, v19 offset0:88 offset1:89
	v_add_f32_e32 v6, v6, v7
	v_add_f32_e32 v7, v12, v13
	ds_read_b128 v[18:21], v118 offset:19200
	global_load_dwordx4 v[204:207], v118, s[56:57]
	s_add_u32 s56, s56, s58
	s_addc_u32 s57, s57, s59
	ds_read_b128 v[34:37], v118 offset:19712
	ds_read_b128 v[90:93], v118 offset:19968
	ds_read_b128 v[94:97], v118 offset:20224
	ds_read2_b32 v[82:83], v117 offset0:224 offset1:228
	ds_write2st64_b32 v112, v6, v7 offset0:96 offset1:97
	s_waitcnt lgkmcnt(13)
	v_pk_mul_f32 v[6:7], v[64:65], v[8:9]
	v_pk_mul_f32 v[12:13], v[64:65], v[4:5]
	v_pk_fma_f32 v[6:7], v[62:63], v[10:11], v[6:7]
	v_pk_fma_f32 v[12:13], v[62:63], v[2:3], v[12:13]
	v_add_f32_e32 v6, v6, v7
	v_add_f32_e32 v7, v12, v13
	v_mov_b32_e32 v14, v87
	v_add_f32_dpp v6, v6, v6 row_ror:8 row_mask:0xf bank_mask:0xf bound_ctrl:1
	v_add_f32_dpp v7, v7, v7 row_ror:8 row_mask:0xf bank_mask:0xf bound_ctrl:1
	s_nop 0
	v_add_f32_dpp v6, v6, v6 row_ror:4 row_mask:0xf bank_mask:0xf bound_ctrl:1
	v_add_f32_dpp v7, v7, v7 row_ror:4 row_mask:0xf bank_mask:0xf bound_ctrl:1
	s_nop 0
	v_add_f32_dpp v6, v6, v6 row_ror:2 row_mask:0xf bank_mask:0xf bound_ctrl:1
	v_add_f32_dpp v7, v7, v7 row_ror:2 row_mask:0xf bank_mask:0xf bound_ctrl:1
	s_nop 0
	v_add_f32_dpp v6, v6, v6 row_ror:1 row_mask:0xf bank_mask:0xf bound_ctrl:1
	v_add_f32_dpp v12, v7, v7 row_ror:1 row_mask:0xf bank_mask:0xf bound_ctrl:1
	v_pk_mul_f32 v[16:17], v[70:71], v[6:7] op_sel_hi:[1,0]
	v_pk_mul_f32 v[6:7], v[72:73], v[6:7] op_sel_hi:[1,0]
	v_pk_fma_f32 v[16:17], v[74:75], v[86:87], v[16:17] op_sel_hi:[1,0,1]
	v_pk_fma_f32 v[6:7], v[76:77], v[86:87], v[6:7] op_sel_hi:[1,0,1]
	s_waitcnt vmcnt(6)
	v_pk_fma_f32 v[10:11], v[212:213], v[10:11], v[16:17]
	v_pk_fma_f32 v[6:7], v[214:215], v[8:9], v[6:7]
	v_pk_mul_f32 v[8:9], v[70:71], v[12:13] op_sel_hi:[1,0]
	s_nop 0
	v_pk_fma_f32 v[8:9], v[74:75], v[14:15], v[8:9] op_sel_hi:[1,0,1]
	s_nop 0
	v_pk_fma_f32 v[2:3], v[212:213], v[2:3], v[8:9]
	v_pk_mul_f32 v[8:9], v[72:73], v[12:13] op_sel_hi:[1,0]
	s_nop 0
	v_pk_fma_f32 v[8:9], v[76:77], v[14:15], v[8:9] op_sel_hi:[1,0,1]
	s_waitcnt lgkmcnt(7)
	v_mov_b32_e32 v14, v89
	v_pk_fma_f32 v[4:5], v[214:215], v[4:5], v[8:9]
	v_pk_mul_f32 v[8:9], v[80:81], v[6:7]
	v_pk_mul_f32 v[12:13], v[80:81], v[4:5]
	v_pk_fma_f32 v[8:9], v[78:79], v[10:11], v[8:9]
	v_pk_fma_f32 v[12:13], v[78:79], v[2:3], v[12:13]
	v_add_f32_e32 v8, v8, v9
	v_add_f32_e32 v9, v12, v13
	ds_write2st64_b32 v112, v8, v9 offset0:104 offset1:105
	ds_read_b32 v249, v246
	v_pk_mul_f32 v[8:9], v[48:49], v[6:7]
	v_pk_mul_f32 v[12:13], v[48:49], v[4:5]
	v_pk_fma_f32 v[8:9], v[46:47], v[10:11], v[8:9]
	v_pk_fma_f32 v[12:13], v[46:47], v[2:3], v[12:13]
	v_add_f32_e32 v8, v8, v9
	v_add_f32_e32 v9, v12, v13
	s_nop 0
	v_add_f32_dpp v8, v8, v8 row_ror:8 row_mask:0xf bank_mask:0xf bound_ctrl:1
	v_add_f32_dpp v9, v9, v9 row_ror:8 row_mask:0xf bank_mask:0xf bound_ctrl:1
	s_nop 0
	v_add_f32_dpp v8, v8, v8 row_ror:4 row_mask:0xf bank_mask:0xf bound_ctrl:1
	v_add_f32_dpp v9, v9, v9 row_ror:4 row_mask:0xf bank_mask:0xf bound_ctrl:1
	s_nop 0
	v_add_f32_dpp v8, v8, v8 row_ror:2 row_mask:0xf bank_mask:0xf bound_ctrl:1
	v_add_f32_dpp v9, v9, v9 row_ror:2 row_mask:0xf bank_mask:0xf bound_ctrl:1
	s_nop 0
	v_add_f32_dpp v8, v8, v8 row_ror:1 row_mask:0xf bank_mask:0xf bound_ctrl:1
	v_add_f32_dpp v12, v9, v9 row_ror:1 row_mask:0xf bank_mask:0xf bound_ctrl:1
	v_pk_mul_f32 v[16:17], v[50:51], v[8:9] op_sel_hi:[1,0]
	v_pk_mul_f32 v[8:9], v[52:53], v[8:9] op_sel_hi:[1,0]
	v_pk_fma_f32 v[16:17], v[54:55], v[88:89], v[16:17] op_sel_hi:[1,0,1]
	v_pk_fma_f32 v[8:9], v[56:57], v[88:89], v[8:9] op_sel_hi:[1,0,1]
	s_waitcnt vmcnt(5)
	v_pk_fma_f32 v[10:11], v[216:217], v[10:11], v[16:17]
	v_pk_fma_f32 v[6:7], v[218:219], v[6:7], v[8:9]
	v_pk_mul_f32 v[8:9], v[50:51], v[12:13] op_sel_hi:[1,0]
	s_nop 0
	v_pk_fma_f32 v[8:9], v[54:55], v[14:15], v[8:9] op_sel_hi:[1,0,1]
	s_nop 0
	v_pk_fma_f32 v[2:3], v[216:217], v[2:3], v[8:9]
	v_pk_mul_f32 v[8:9], v[52:53], v[12:13] op_sel_hi:[1,0]
	s_nop 0
	v_pk_fma_f32 v[8:9], v[56:57], v[14:15], v[8:9] op_sel_hi:[1,0,1]
	s_waitcnt lgkmcnt(3)
	v_mov_b32_e32 v14, v83
	v_pk_fma_f32 v[4:5], v[218:219], v[4:5], v[8:9]
	v_pk_mul_f32 v[8:9], v[60:61], v[6:7]
	v_pk_mul_f32 v[12:13], v[60:61], v[4:5]
	v_pk_fma_f32 v[8:9], v[58:59], v[10:11], v[8:9]
	v_pk_fma_f32 v[12:13], v[58:59], v[2:3], v[12:13]
	v_add_f32_e32 v8, v8, v9
	v_add_f32_e32 v9, v12, v13
	ds_write2st64_b32 v112, v8, v9 offset0:112 offset1:113
	s_add_i32 s64, s4, 1
	s_waitcnt lgkmcnt(1)
	v_cmp_gt_u32_e32 vcc, s64, v249
	s_nop 0
	s_cbranch_vccnz .Lsflag_slow_1
.Lsflag_go_1:
	ds_read_b128 v[224:227], v118 offset:20480
	ds_read_b128 v[228:231], v118 offset:20992
	ds_read_b128 v[232:235], v118 offset:21248
	ds_read_b128 v[236:239], v118 offset:21504
	v_pk_mul_f32 v[8:9], v[20:21], v[6:7]
	v_pk_mul_f32 v[12:13], v[20:21], v[4:5]
	v_pk_fma_f32 v[8:9], v[18:19], v[10:11], v[8:9]
	v_pk_fma_f32 v[12:13], v[18:19], v[2:3], v[12:13]
	v_add_f32_e32 v8, v8, v9
	v_add_f32_e32 v9, v12, v13
	s_nop 0
	v_add_f32_dpp v8, v8, v8 row_ror:8 row_mask:0xf bank_mask:0xf bound_ctrl:1
	v_add_f32_dpp v9, v9, v9 row_ror:8 row_mask:0xf bank_mask:0xf bound_ctrl:1
	s_nop 0
	v_add_f32_dpp v8, v8, v8 row_ror:4 row_mask:0xf bank_mask:0xf bound_ctrl:1
	v_add_f32_dpp v9, v9, v9 row_ror:4 row_mask:0xf bank_mask:0xf bound_ctrl:1
	s_nop 0
	v_add_f32_dpp v8, v8, v8 row_ror:2 row_mask:0xf bank_mask:0xf bound_ctrl:1
	v_add_f32_dpp v9, v9, v9 row_ror:2 row_mask:0xf bank_mask:0xf bound_ctrl:1
	s_nop 0
	v_add_f32_dpp v8, v8, v8 row_ror:1 row_mask:0xf bank_mask:0xf bound_ctrl:1
	v_add_f32_dpp v12, v9, v9 row_ror:1 row_mask:0xf bank_mask:0xf bound_ctrl:1
	v_pk_mul_f32 v[16:17], v[34:35], v[8:9] op_sel_hi:[1,0]
	v_pk_mul_f32 v[8:9], v[36:37], v[8:9] op_sel_hi:[1,0]
	v_pk_fma_f32 v[16:17], v[90:91], v[82:83], v[16:17] op_sel_hi:[1,0,1]
	v_pk_fma_f32 v[8:9], v[92:93], v[82:83], v[8:9] op_sel_hi:[1,0,1]
	s_waitcnt vmcnt(4)
	v_pk_fma_f32 v[22:23], v[220:221], v[10:11], v[16:17]
	v_pk_fma_f32 v[24:25], v[222:223], v[6:7], v[8:9]
	v_pk_mul_f32 v[6:7], v[34:35], v[12:13] op_sel_hi:[1,0]
	s_nop 0
	v_pk_fma_f32 v[6:7], v[90:91], v[14:15], v[6:7] op_sel_hi:[1,0,1]
	s_nop 0
	v_pk_fma_f32 v[26:27], v[220:221], v[2:3], v[6:7]
	v_pk_mul_f32 v[2:3], v[36:37], v[12:13] op_sel_hi:[1,0]
	s_nop 0
	v_pk_fma_f32 v[2:3], v[92:93], v[14:15], v[2:3] op_sel_hi:[1,0,1]
	s_nop 0
	v_pk_fma_f32 v[28:29], v[222:223], v[4:5], v[2:3]
	v_pk_mul_f32 v[2:3], v[96:97], v[24:25]
	v_pk_mul_f32 v[4:5], v[96:97], v[28:29]
	v_pk_fma_f32 v[2:3], v[94:95], v[22:23], v[2:3]
	v_pk_fma_f32 v[4:5], v[94:95], v[26:27], v[4:5]
	v_add_f32_e32 v2, v2, v3
	v_add_f32_e32 v3, v4, v5
	ds_write2st64_b32 v112, v2, v3 offset0:120 offset1:121
	v_mov_b32_e32 v248, s64
	ds_write_b32 v247, v248
	global_load_dwordx4 v[208:211], v118, s[56:57]
	s_add_u32 s56, s56, s58
	s_addc_u32 s57, s57, s59
	s_waitcnt lgkmcnt(5)
	v_pk_mul_f32 v[66:67], v[226:227], v[24:25]
	v_pk_mul_f32 v[20:21], v[226:227], v[28:29]
	v_pk_fma_f32 v[66:67], v[224:225], v[22:23], v[66:67]
	v_pk_fma_f32 v[18:19], v[224:225], v[26:27], v[20:21]
	v_add_f32_e32 v20, v66, v67
	v_add_f32_e32 v18, v18, v19
	ds_read2_b32 v[62:63], v120 offset1:4
	ds_read_b128 v[30:33], v118 offset:21760
	global_load_dwordx4 v[212:215], v118, s[56:57]
	s_add_u32 s56, s56, s58
	s_addc_u32 s57, s57, s59
	ds_read_b128 v[38:41], v118 offset:22272
	ds_read_b128 v[42:45], v118 offset:22528
	ds_read_b128 v[46:49], v118 offset:22784
	ds_read2_b32 v[64:65], v120 offset0:32 offset1:36
	ds_read_b128 v[50:53], v118 offset:23040
	global_load_dwordx4 v[216:219], v118, s[56:57]
	s_add_u32 s56, s56, s58
	s_addc_u32 s57, s57, s59
	ds_read_b128 v[58:61], v118 offset:23552
	ds_read_b128 v[82:85], v118 offset:23808
	ds_read_b128 v[88:91], v118 offset:24064
	ds_read2_b32 v[108:109], v120 offset0:64 offset1:68
	ds_read_b128 v[92:95], v118 offset:24320
	global_load_dwordx4 v[220:223], v118, s[56:57]
	s_add_u32 s56, s56, s58
	s_addc_u32 s57, s57, s59
	ds_read_b128 v[100:103], v118 offset:24832
	ds_read_b128 v[104:107], v118 offset:25088
	ds_read_b128 v[124:127], v118 offset:25344
	ds_read2_b32 v[130:131], v120 offset0:96 offset1:100
	v_add_f32_dpp v20, v20, v20 row_ror:8 row_mask:0xf bank_mask:0xf bound_ctrl:1
	v_add_f32_dpp v18, v18, v18 row_ror:8 row_mask:0xf bank_mask:0xf bound_ctrl:1
	s_waitcnt lgkmcnt(12)
	v_mov_b32_e32 v66, v63
	v_add_f32_dpp v20, v20, v20 row_ror:4 row_mask:0xf bank_mask:0xf bound_ctrl:1
	v_add_f32_dpp v18, v18, v18 row_ror:4 row_mask:0xf bank_mask:0xf bound_ctrl:1
	s_nop 0
	v_add_f32_dpp v20, v20, v20 row_ror:2 row_mask:0xf bank_mask:0xf bound_ctrl:1
	v_add_f32_dpp v18, v18, v18 row_ror:2 row_mask:0xf bank_mask:0xf bound_ctrl:1
	s_nop 0
	v_add_f32_dpp v20, v20, v20 row_ror:1 row_mask:0xf bank_mask:0xf bound_ctrl:1
	v_add_f32_dpp v18, v18, v18 row_ror:1 row_mask:0xf bank_mask:0xf bound_ctrl:1
	v_pk_mul_f32 v[68:69], v[228:229], v[20:21] op_sel_hi:[1,0]
	v_pk_mul_f32 v[10:11], v[228:229], v[18:19] op_sel_hi:[1,0]
	v_pk_fma_f32 v[68:69], v[232:233], v[62:63], v[68:69] op_sel_hi:[1,0,1]
	v_pk_mul_f32 v[20:21], v[230:231], v[20:21] op_sel_hi:[1,0]
	v_pk_fma_f32 v[10:11], v[232:233], v[66:67], v[10:11] op_sel_hi:[1,0,1]
	s_waitcnt vmcnt(7)
	v_pk_fma_f32 v[22:23], v[192:193], v[22:23], v[68:69]
	v_pk_fma_f32 v[20:21], v[234:235], v[62:63], v[20:21] op_sel_hi:[1,0,1]
	v_pk_fma_f32 v[26:27], v[192:193], v[26:27], v[10:11]
	v_pk_mul_f32 v[6:7], v[230:231], v[18:19] op_sel_hi:[1,0]
	v_pk_fma_f32 v[24:25], v[194:195], v[24:25], v[20:21]
	v_pk_fma_f32 v[6:7], v[234:235], v[66:67], v[6:7] op_sel_hi:[1,0,1]
	v_pk_mul_f32 v[62:63], v[32:33], v[24:25]
	v_pk_fma_f32 v[28:29], v[194:195], v[28:29], v[6:7]
	v_pk_fma_f32 v[62:63], v[30:31], v[22:23], v[62:63]
	v_pk_mul_f32 v[32:33], v[32:33], v[28:29]
	v_pk_mul_f32 v[6:7], v[238:239], v[24:25]
	v_pk_fma_f32 v[30:31], v[30:31], v[26:27], v[32:33]
	v_add_f32_e32 v32, v62, v63
	v_add_f32_e32 v30, v30, v31
	s_waitcnt lgkmcnt(10)
	v_mov_b32_e32 v62, v65
	v_add_f32_dpp v32, v32, v32 row_ror:8 row_mask:0xf bank_mask:0xf bound_ctrl:1
	v_add_f32_dpp v30, v30, v30 row_ror:8 row_mask:0xf bank_mask:0xf bound_ctrl:1
	v_pk_mul_f32 v[4:5], v[238:239], v[28:29]
	v_add_f32_dpp v32, v32, v32 row_ror:4 row_mask:0xf bank_mask:0xf bound_ctrl:1
	v_add_f32_dpp v30, v30, v30 row_ror:4 row_mask:0xf bank_mask:0xf bound_ctrl:1
	v_pk_fma_f32 v[6:7], v[236:237], v[22:23], v[6:7]
	v_add_f32_dpp v32, v32, v32 row_ror:2 row_mask:0xf bank_mask:0xf bound_ctrl:1
	v_add_f32_dpp v30, v30, v30 row_ror:2 row_mask:0xf bank_mask:0xf bound_ctrl:1
	v_pk_fma_f32 v[2:3], v[236:237], v[26:27], v[4:5]
	v_add_f32_dpp v32, v32, v32 row_ror:1 row_mask:0xf bank_mask:0xf bound_ctrl:1
	v_pk_mul_f32 v[66:67], v[38:39], v[32:33] op_sel_hi:[1,0]
	v_pk_mul_f32 v[32:33], v[40:41], v[32:33] op_sel_hi:[1,0]
	v_add_f32_dpp v30, v30, v30 row_ror:1 row_mask:0xf bank_mask:0xf bound_ctrl:1
	v_pk_fma_f32 v[32:33], v[44:45], v[64:65], v[32:33] op_sel_hi:[1,0,1]
	v_pk_fma_f32 v[66:67], v[42:43], v[64:65], v[66:67] op_sel_hi:[1,0,1]
	s_waitcnt vmcnt(6)
	v_pk_fma_f32 v[24:25], v[198:199], v[24:25], v[32:33]
	v_pk_mul_f32 v[32:33], v[38:39], v[30:31] op_sel_hi:[1,0]
	v_pk_mul_f32 v[30:31], v[40:41], v[30:31] op_sel_hi:[1,0]
	v_pk_fma_f32 v[32:33], v[42:43], v[62:63], v[32:33] op_sel_hi:[1,0,1]
	v_pk_fma_f32 v[30:31], v[44:45], v[62:63], v[30:31] op_sel_hi:[1,0,1]
	v_pk_fma_f32 v[22:23], v[196:197], v[22:23], v[66:67]
	v_pk_fma_f32 v[28:29], v[198:199], v[28:29], v[30:31]
	v_pk_fma_f32 v[26:27], v[196:197], v[26:27], v[32:33]
	v_pk_mul_f32 v[30:31], v[48:49], v[24:25]
	v_pk_mul_f32 v[32:33], v[48:49], v[28:29]
	v_add_f32_e32 v4, v6, v7
	v_add_f32_e32 v2, v2, v3
	v_pk_fma_f32 v[30:31], v[46:47], v[22:23], v[30:31]
	v_pk_fma_f32 v[32:33], v[46:47], v[26:27], v[32:33]
	ds_write2st64_b32 v113, v4, v2 offset1:1
	v_add_f32_e32 v30, v30, v31
	v_add_f32_e32 v31, v32, v33
	ds_read_b128 v[2:5], v118 offset:25600
	global_load_dwordx4 v[192:195], v118, s[56:57]
	s_add_u32 s56, s56, s58
	s_addc_u32 s57, s57, s59
	ds_read_b128 v[10:13], v118 offset:26112
	ds_read_b128 v[14:17], v118 offset:26368
	ds_read_b128 v[18:21], v118 offset:26624
	ds_read2_b32 v[132:133], v120 offset0:128 offset1:132
	ds_write2st64_b32 v113, v30, v31 offset0:8 offset1:9
	s_waitcnt lgkmcnt(12)
	v_pk_mul_f32 v[30:31], v[52:53], v[24:25]
	v_pk_mul_f32 v[32:33], v[52:53], v[28:29]
	v_pk_fma_f32 v[30:31], v[50:51], v[22:23], v[30:31]
	v_pk_fma_f32 v[32:33], v[50:51], v[26:27], v[32:33]
	v_add_f32_e32 v30, v30, v31
	v_add_f32_e32 v31, v32, v33
	v_mov_b32_e32 v34, v109
	v_add_f32_dpp v30, v30, v30 row_ror:8 row_mask:0xf bank_mask:0xf bound_ctrl:1
	v_add_f32_dpp v31, v31, v31 row_ror:8 row_mask:0xf bank_mask:0xf bound_ctrl:1
	ds_read_b128 v[78:81], v118 offset:26880
	global_load_dwordx4 v[196:199], v118, s[56:57]
	s_add_u32 s56, s56, s58
	s_addc_u32 s57, s57, s59
	ds_read_b128 v[70:73], v118 offset:27392
	ds_read_b128 v[74:77], v118 offset:27648
	ds_read_b128 v[62:65], v118 offset:27904
	ds_read2_b32 v[86:87], v120 offset0:160 offset1:164
	v_add_f32_dpp v30, v30, v30 row_ror:4 row_mask:0xf bank_mask:0xf bound_ctrl:1
	v_add_f32_dpp v31, v31, v31 row_ror:4 row_mask:0xf bank_mask:0xf bound_ctrl:1
	s_nop 0
	v_add_f32_dpp v30, v30, v30 row_ror:2 row_mask:0xf bank_mask:0xf bound_ctrl:1
	v_add_f32_dpp v31, v31, v31 row_ror:2 row_mask:0xf bank_mask:0xf bound_ctrl:1
	s_nop 0
	v_add_f32_dpp v30, v30, v30 row_ror:1 row_mask:0xf bank_mask:0xf bound_ctrl:1
	v_add_f32_dpp v32, v31, v31 row_ror:1 row_mask:0xf bank_mask:0xf bound_ctrl:1
	v_pk_mul_f32 v[36:37], v[58:59], v[30:31] op_sel_hi:[1,0]
	v_pk_mul_f32 v[30:31], v[60:61], v[30:31] op_sel_hi:[1,0]
	v_pk_fma_f32 v[36:37], v[82:83], v[108:109], v[36:37] op_sel_hi:[1,0,1]
	v_pk_fma_f32 v[30:31], v[84:85], v[108:109], v[30:31] op_sel_hi:[1,0,1]
	s_waitcnt vmcnt(7)
	v_pk_fma_f32 v[22:23], v[200:201], v[22:23], v[36:37]
	v_pk_fma_f32 v[24:25], v[202:203], v[24:25], v[30:31]
	v_pk_mul_f32 v[30:31], v[58:59], v[32:33] op_sel_hi:[1,0]
	s_nop 0
	v_pk_fma_f32 v[30:31], v[82:83], v[34:35], v[30:31] op_sel_hi:[1,0,1]
	s_nop 0
	v_pk_fma_f32 v[26:27], v[200:201], v[26:27], v[30:31]
	v_pk_mul_f32 v[30:31], v[60:61], v[32:33] op_sel_hi:[1,0]
	s_nop 0
	v_pk_fma_f32 v[30:31], v[84:85], v[34:35], v[30:31] op_sel_hi:[1,0,1]
	s_waitcnt lgkmcnt(12)
	v_mov_b32_e32 v34, v131
	v_pk_fma_f32 v[28:29], v[202:203], v[28:29], v[30:31]
	v_pk_mul_f32 v[30:31], v[90:91], v[24:25]
	v_pk_mul_f32 v[32:33], v[90:91], v[28:29]
	v_pk_fma_f32 v[30:31], v[88:89], v[22:23], v[30:31]
	v_pk_fma_f32 v[32:33], v[88:89], v[26:27], v[32:33]
	v_add_f32_e32 v30, v30, v31
	v_add_f32_e32 v31, v32, v33
	ds_write2st64_b32 v113, v30, v31 offset0:16 offset1:17
	v_pk_mul_f32 v[30:31], v[94:95], v[24:25]
	v_pk_mul_f32 v[32:33], v[94:95], v[28:29]
	v_pk_fma_f32 v[30:31], v[92:93], v[22:23], v[30:31]
	v_pk_fma_f32 v[32:33], v[92:93], v[26:27], v[32:33]
	v_add_f32_e32 v30, v30, v31
	v_add_f32_e32 v31, v32, v33
	ds_read_b128 v[58:61], v118 offset:28160
	global_load_dwordx4 v[200:203], v118, s[56:57]
	s_add_u32 s56, s56, s58
	s_addc_u32 s57, s57, s59
	ds_read_b128 v[50:53], v118 offset:28672
	ds_read_b128 v[54:57], v118 offset:28928
	ds_read_b128 v[42:45], v118 offset:29184
	ds_read2_b32 v[84:85], v120 offset0:192 offset1:196
	v_add_f32_dpp v30, v30, v30 row_ror:8 row_mask:0xf bank_mask:0xf bound_ctrl:1
	v_add_f32_dpp v31, v31, v31 row_ror:8 row_mask:0xf bank_mask:0xf bound_ctrl:1
	s_nop 0
	v_add_f32_dpp v30, v30, v30 row_ror:4 row_mask:0xf bank_mask:0xf bound_ctrl:1
	v_add_f32_dpp v31, v31, v31 row_ror:4 row_mask:0xf bank_mask:0xf bound_ctrl:1
	s_nop 0
	v_add_f32_dpp v30, v30, v30 row_ror:2 row_mask:0xf bank_mask:0xf bound_ctrl:1
	v_add_f32_dpp v31, v31, v31 row_ror:2 row_mask:0xf bank_mask:0xf bound_ctrl:1
	s_nop 0
	v_add_f32_dpp v30, v30, v30 row_ror:1 row_mask:0xf bank_mask:0xf bound_ctrl:1
	v_pk_mul_f32 v[36:37], v[100:101], v[30:31] op_sel_hi:[1,0]
	v_add_f32_dpp v32, v31, v31 row_ror:1 row_mask:0xf bank_mask:0xf bound_ctrl:1
	v_pk_fma_f32 v[36:37], v[104:105], v[130:131], v[36:37] op_sel_hi:[1,0,1]
	s_nop 0
	s_waitcnt vmcnt(7)
	v_pk_fma_f32 v[88:89], v[204:205], v[22:23], v[36:37]
	v_pk_mul_f32 v[22:23], v[102:103], v[30:31] op_sel_hi:[1,0]
	s_nop 0
	v_pk_fma_f32 v[22:23], v[106:107], v[130:131], v[22:23] op_sel_hi:[1,0,1]
	s_nop 0
	v_pk_fma_f32 v[90:91], v[206:207], v[24:25], v[22:23]
	v_pk_mul_f32 v[22:23], v[100:101], v[32:33] op_sel_hi:[1,0]
	s_nop 0
	v_pk_fma_f32 v[22:23], v[104:105], v[34:35], v[22:23] op_sel_hi:[1,0,1]
	s_nop 0
	v_pk_fma_f32 v[92:93], v[204:205], v[26:27], v[22:23]
	v_pk_mul_f32 v[22:23], v[102:103], v[32:33] op_sel_hi:[1,0]
	s_waitcnt lgkmcnt(12)
	v_pk_mul_f32 v[96:97], v[4:5], v[90:91]
	v_pk_fma_f32 v[22:23], v[106:107], v[34:35], v[22:23] op_sel_hi:[1,0,1]
	v_pk_fma_f32 v[96:97], v[2:3], v[88:89], v[96:97]
	v_pk_fma_f32 v[94:95], v[206:207], v[28:29], v[22:23]
	v_pk_mul_f32 v[22:23], v[126:127], v[90:91]
	v_pk_mul_f32 v[4:5], v[4:5], v[94:95]
	v_pk_mul_f32 v[24:25], v[126:127], v[94:95]
	v_pk_fma_f32 v[2:3], v[2:3], v[92:93], v[4:5]
	v_add_f32_e32 v4, v96, v97
	v_add_f32_e32 v2, v2, v3
	v_mov_b32_e32 v96, v133
	v_add_f32_dpp v4, v4, v4 row_ror:8 row_mask:0xf bank_mask:0xf bound_ctrl:1
	v_add_f32_dpp v2, v2, v2 row_ror:8 row_mask:0xf bank_mask:0xf bound_ctrl:1
	v_pk_fma_f32 v[22:23], v[124:125], v[88:89], v[22:23]
	v_add_f32_dpp v4, v4, v4 row_ror:4 row_mask:0xf bank_mask:0xf bound_ctrl:1
	v_add_f32_dpp v2, v2, v2 row_ror:4 row_mask:0xf bank_mask:0xf bound_ctrl:1
	v_pk_fma_f32 v[24:25], v[124:125], v[92:93], v[24:25]
	v_add_f32_dpp v4, v4, v4 row_ror:2 row_mask:0xf bank_mask:0xf bound_ctrl:1
	v_add_f32_dpp v2, v2, v2 row_ror:2 row_mask:0xf bank_mask:0xf bound_ctrl:1
	v_add_f32_e32 v22, v22, v23
	v_add_f32_dpp v4, v4, v4 row_ror:1 row_mask:0xf bank_mask:0xf bound_ctrl:1
	v_pk_mul_f32 v[98:99], v[10:11], v[4:5] op_sel_hi:[1,0]
	v_pk_mul_f32 v[4:5], v[12:13], v[4:5] op_sel_hi:[1,0]
	v_add_f32_dpp v2, v2, v2 row_ror:1 row_mask:0xf bank_mask:0xf bound_ctrl:1
	v_pk_fma_f32 v[4:5], v[16:17], v[132:133], v[4:5] op_sel_hi:[1,0,1]
	v_pk_fma_f32 v[98:99], v[14:15], v[132:133], v[98:99] op_sel_hi:[1,0,1]
	s_waitcnt vmcnt(6)
	v_pk_fma_f32 v[90:91], v[210:211], v[90:91], v[4:5]
	v_pk_mul_f32 v[4:5], v[10:11], v[2:3] op_sel_hi:[1,0]
	v_pk_mul_f32 v[2:3], v[12:13], v[2:3] op_sel_hi:[1,0]
	v_pk_fma_f32 v[4:5], v[14:15], v[96:97], v[4:5] op_sel_hi:[1,0,1]
	v_pk_fma_f32 v[2:3], v[16:17], v[96:97], v[2:3] op_sel_hi:[1,0,1]
	v_pk_fma_f32 v[88:89], v[208:209], v[88:89], v[98:99]
	v_pk_fma_f32 v[94:95], v[210:211], v[94:95], v[2:3]
	v_pk_fma_f32 v[92:93], v[208:209], v[92:93], v[4:5]
	s_waitcnt lgkmcnt(10)
	v_pk_mul_f32 v[96:97], v[80:81], v[90:91]
	v_pk_mul_f32 v[80:81], v[80:81], v[94:95]
	v_pk_fma_f32 v[96:97], v[78:79], v[88:89], v[96:97]
	v_pk_fma_f32 v[78:79], v[78:79], v[92:93], v[80:81]
	v_add_f32_e32 v80, v96, v97
	v_add_f32_e32 v78, v78, v79
	s_waitcnt lgkmcnt(6)
	v_mov_b32_e32 v96, v87
	v_add_f32_dpp v80, v80, v80 row_ror:8 row_mask:0xf bank_mask:0xf bound_ctrl:1
	v_add_f32_dpp v78, v78, v78 row_ror:8 row_mask:0xf bank_mask:0xf bound_ctrl:1
	v_pk_mul_f32 v[2:3], v[20:21], v[90:91]
	v_add_f32_dpp v80, v80, v80 row_ror:4 row_mask:0xf bank_mask:0xf bound_ctrl:1
	v_add_f32_dpp v78, v78, v78 row_ror:4 row_mask:0xf bank_mask:0xf bound_ctrl:1
	v_pk_mul_f32 v[4:5], v[20:21], v[94:95]
	v_add_f32_dpp v80, v80, v80 row_ror:2 row_mask:0xf bank_mask:0xf bound_ctrl:1
	v_add_f32_dpp v78, v78, v78 row_ror:2 row_mask:0xf bank_mask:0xf bound_ctrl:1
	v_add_f32_e32 v23, v24, v25
	v_add_f32_dpp v80, v80, v80 row_ror:1 row_mask:0xf bank_mask:0xf bound_ctrl:1
	v_add_f32_dpp v78, v78, v78 row_ror:1 row_mask:0xf bank_mask:0xf bound_ctrl:1
	v_pk_mul_f32 v[98:99], v[70:71], v[80:81] op_sel_hi:[1,0]
	v_pk_mul_f32 v[70:71], v[70:71], v[78:79] op_sel_hi:[1,0]
	v_pk_fma_f32 v[98:99], v[74:75], v[86:87], v[98:99] op_sel_hi:[1,0,1]
	v_pk_fma_f32 v[70:71], v[74:75], v[96:97], v[70:71] op_sel_hi:[1,0,1]
	s_waitcnt vmcnt(5)
	v_pk_fma_f32 v[104:105], v[212:213], v[88:89], v[98:99]
	v_pk_mul_f32 v[80:81], v[72:73], v[80:81] op_sel_hi:[1,0]
	v_pk_fma_f32 v[66:67], v[212:213], v[92:93], v[70:71]
	v_pk_mul_f32 v[70:71], v[72:73], v[78:79] op_sel_hi:[1,0]
	v_pk_fma_f32 v[80:81], v[76:77], v[86:87], v[80:81] op_sel_hi:[1,0,1]
	v_pk_fma_f32 v[70:71], v[76:77], v[96:97], v[70:71] op_sel_hi:[1,0,1]
	v_pk_fma_f32 v[106:107], v[214:215], v[90:91], v[80:81]
	v_pk_fma_f32 v[68:69], v[214:215], v[94:95], v[70:71]
	v_pk_fma_f32 v[2:3], v[18:19], v[88:89], v[2:3]
	v_pk_fma_f32 v[4:5], v[18:19], v[92:93], v[4:5]
	v_pk_mul_f32 v[70:71], v[64:65], v[106:107]
	v_pk_mul_f32 v[64:65], v[64:65], v[68:69]
	ds_write2st64_b32 v113, v22, v23 offset0:24 offset1:25
	v_add_f32_e32 v2, v2, v3
	v_add_f32_e32 v3, v4, v5
	v_pk_fma_f32 v[70:71], v[62:63], v[104:105], v[70:71]
	v_pk_fma_f32 v[62:63], v[62:63], v[66:67], v[64:65]
	ds_read_b128 v[38:41], v118 offset:29440
	global_load_dwordx4 v[204:207], v118, s[56:57]
	s_add_u32 s56, s56, s58
	s_addc_u32 s57, s57, s59
	ds_read_b128 v[30:33], v118 offset:29952
	ds_read_b128 v[34:37], v118 offset:30208
	ds_read_b128 v[22:25], v118 offset:30464
	ds_read2_b32 v[82:83], v120 offset0:224 offset1:228
	ds_write2st64_b32 v113, v2, v3 offset0:32 offset1:33
	v_add_f32_e32 v64, v70, v71
	v_add_f32_e32 v62, v62, v63
	ds_read_b128 v[18:21], v118 offset:30720
	global_load_dwordx4 v[208:211], v118, s[56:57]
	s_add_u32 s56, s56, s58
	s_addc_u32 s57, s57, s59
	ds_read_b128 v[10:13], v118 offset:31232
	ds_read_b128 v[14:17], v118 offset:31488
	ds_read_b128 v[2:5], v118 offset:31744
	ds_write2st64_b32 v113, v64, v62 offset0:40 offset1:41
	s_waitcnt lgkmcnt(12)
	v_pk_mul_f32 v[62:63], v[60:61], v[106:107]
	v_pk_mul_f32 v[60:61], v[60:61], v[68:69]
	v_pk_fma_f32 v[62:63], v[58:59], v[104:105], v[62:63]
	v_pk_fma_f32 v[58:59], v[58:59], v[66:67], v[60:61]
	v_add_f32_e32 v60, v62, v63
	v_add_f32_e32 v58, v58, v59
	v_mov_b32_e32 v62, v85
	v_add_f32_dpp v60, v60, v60 row_ror:8 row_mask:0xf bank_mask:0xf bound_ctrl:1
	v_add_f32_dpp v58, v58, v58 row_ror:8 row_mask:0xf bank_mask:0xf bound_ctrl:1
	ds_read2_b32 v[102:103], v114 offset1:4
	v_add_f32_dpp v60, v60, v60 row_ror:4 row_mask:0xf bank_mask:0xf bound_ctrl:1
	v_add_f32_dpp v58, v58, v58 row_ror:4 row_mask:0xf bank_mask:0xf bound_ctrl:1
	ds_read_b128 v[98:101], v118 offset:32000
	global_load_dwordx4 v[212:215], v118, s[56:57]
	s_add_u32 s56, s56, s58
	s_addc_u32 s57, s57, s59
	ds_read_b128 v[90:93], v118 offset:32512
	ds_read_b128 v[94:97], v118 offset:32768
	ds_read_b128 v[78:81], v118 offset:33024
	ds_read2_b32 v[108:109], v114 offset0:32 offset1:36
	v_add_f32_dpp v60, v60, v60 row_ror:2 row_mask:0xf bank_mask:0xf bound_ctrl:1
	v_add_f32_dpp v58, v58, v58 row_ror:2 row_mask:0xf bank_mask:0xf bound_ctrl:1
	s_nop 0
	v_add_f32_dpp v60, v60, v60 row_ror:1 row_mask:0xf bank_mask:0xf bound_ctrl:1
	v_add_f32_dpp v58, v58, v58 row_ror:1 row_mask:0xf bank_mask:0xf bound_ctrl:1
	v_pk_mul_f32 v[64:65], v[50:51], v[60:61] op_sel_hi:[1,0]
	v_pk_mul_f32 v[50:51], v[50:51], v[58:59] op_sel_hi:[1,0]
	v_pk_fma_f32 v[64:65], v[54:55], v[84:85], v[64:65] op_sel_hi:[1,0,1]
	v_pk_fma_f32 v[50:51], v[54:55], v[62:63], v[50:51] op_sel_hi:[1,0,1]
	s_waitcnt vmcnt(7)
	v_pk_fma_f32 v[104:105], v[216:217], v[104:105], v[64:65]
	v_pk_mul_f32 v[60:61], v[52:53], v[60:61] op_sel_hi:[1,0]
	v_pk_fma_f32 v[54:55], v[216:217], v[66:67], v[50:51]
	v_pk_mul_f32 v[46:47], v[52:53], v[58:59] op_sel_hi:[1,0]
	v_pk_fma_f32 v[60:61], v[56:57], v[84:85], v[60:61] op_sel_hi:[1,0,1]
	v_pk_fma_f32 v[46:47], v[56:57], v[62:63], v[46:47] op_sel_hi:[1,0,1]
	v_pk_fma_f32 v[60:61], v[218:219], v[106:107], v[60:61]
	v_pk_fma_f32 v[56:57], v[218:219], v[68:69], v[46:47]
	s_waitcnt lgkmcnt(12)
	v_pk_mul_f32 v[50:51], v[40:41], v[60:61]
	v_pk_mul_f32 v[40:41], v[40:41], v[56:57]
	v_pk_fma_f32 v[50:51], v[38:39], v[104:105], v[50:51]
	v_pk_fma_f32 v[38:39], v[38:39], v[54:55], v[40:41]
	v_add_f32_e32 v40, v50, v51
	v_add_f32_e32 v38, v38, v39
	v_mov_b32_e32 v58, v83
	v_add_f32_dpp v40, v40, v40 row_ror:8 row_mask:0xf bank_mask:0xf bound_ctrl:1
	v_add_f32_dpp v38, v38, v38 row_ror:8 row_mask:0xf bank_mask:0xf bound_ctrl:1
	v_pk_mul_f32 v[46:47], v[44:45], v[60:61]
	v_add_f32_dpp v40, v40, v40 row_ror:4 row_mask:0xf bank_mask:0xf bound_ctrl:1
	v_add_f32_dpp v38, v38, v38 row_ror:4 row_mask:0xf bank_mask:0xf bound_ctrl:1
	v_pk_mul_f32 v[44:45], v[44:45], v[56:57]
	v_add_f32_dpp v40, v40, v40 row_ror:2 row_mask:0xf bank_mask:0xf bound_ctrl:1
	v_add_f32_dpp v38, v38, v38 row_ror:2 row_mask:0xf bank_mask:0xf bound_ctrl:1
	v_pk_fma_f32 v[46:47], v[42:43], v[104:105], v[46:47]
	v_add_f32_dpp v40, v40, v40 row_ror:1 row_mask:0xf bank_mask:0xf bound_ctrl:1
	v_add_f32_dpp v38, v38, v38 row_ror:1 row_mask:0xf bank_mask:0xf bound_ctrl:1
	v_pk_mul_f32 v[50:51], v[30:31], v[40:41] op_sel_hi:[1,0]
	v_pk_mul_f32 v[30:31], v[30:31], v[38:39] op_sel_hi:[1,0]
	v_pk_fma_f32 v[50:51], v[34:35], v[82:83], v[50:51] op_sel_hi:[1,0,1]
	v_pk_fma_f32 v[30:31], v[34:35], v[58:59], v[30:31] op_sel_hi:[1,0,1]
	s_waitcnt vmcnt(6)
	v_pk_fma_f32 v[50:51], v[220:221], v[104:105], v[50:51]
	v_pk_mul_f32 v[40:41], v[32:33], v[40:41] op_sel_hi:[1,0]
	v_pk_fma_f32 v[26:27], v[220:221], v[54:55], v[30:31]
	v_pk_mul_f32 v[30:31], v[32:33], v[38:39] op_sel_hi:[1,0]
	v_pk_fma_f32 v[40:41], v[36:37], v[82:83], v[40:41] op_sel_hi:[1,0,1]
	v_pk_fma_f32 v[30:31], v[36:37], v[58:59], v[30:31] op_sel_hi:[1,0,1]
	v_pk_fma_f32 v[52:53], v[222:223], v[60:61], v[40:41]
	v_pk_fma_f32 v[28:29], v[222:223], v[56:57], v[30:31]
	v_pk_fma_f32 v[42:43], v[42:43], v[54:55], v[44:45]
	v_pk_mul_f32 v[30:31], v[24:25], v[52:53]
	v_pk_mul_f32 v[24:25], v[24:25], v[28:29]
	v_add_f32_e32 v44, v46, v47
	v_add_f32_e32 v42, v42, v43
	v_pk_fma_f32 v[30:31], v[22:23], v[50:51], v[30:31]
	v_pk_fma_f32 v[22:23], v[22:23], v[26:27], v[24:25]
	ds_write2st64_b32 v113, v44, v42 offset0:48 offset1:49
	v_add_f32_e32 v24, v30, v31
	v_add_f32_e32 v22, v22, v23
	ds_read_b128 v[46:49], v118 offset:33280
	global_load_dwordx4 v[216:219], v118, s[56:57]
	s_add_u32 s56, s56, s58
	s_addc_u32 s57, s57, s59
	ds_read_b128 v[62:65], v118 offset:33792
	ds_read_b128 v[74:77], v118 offset:34048
	ds_read_b128 v[70:73], v118 offset:34304
	ds_read2_b32 v[106:107], v114 offset0:64 offset1:68
	ds_write2st64_b32 v113, v24, v22 offset0:56 offset1:57
	s_waitcnt lgkmcnt(12)
	v_pk_mul_f32 v[22:23], v[20:21], v[52:53]
	v_pk_mul_f32 v[20:21], v[20:21], v[28:29]
	v_pk_fma_f32 v[22:23], v[18:19], v[50:51], v[22:23]
	v_pk_fma_f32 v[18:19], v[18:19], v[26:27], v[20:21]
	v_add_f32_e32 v20, v22, v23
	v_add_f32_e32 v18, v18, v19
	v_mov_b32_e32 v22, v103
	v_add_f32_dpp v20, v20, v20 row_ror:8 row_mask:0xf bank_mask:0xf bound_ctrl:1
	v_add_f32_dpp v18, v18, v18 row_ror:8 row_mask:0xf bank_mask:0xf bound_ctrl:1
	ds_read_b128 v[34:37], v118 offset:34560
	global_load_dwordx4 v[220:223], v118, s[56:57]
	s_add_u32 s56, s56, s58
	s_addc_u32 s57, s57, s59
	ds_read_b128 v[58:61], v118 offset:35072
	ds_read_b128 v[66:69], v118 offset:35328
	ds_read_b128 v[82:85], v118 offset:35584
	ds_read2_b32 v[104:105], v114 offset0:96 offset1:100
	v_add_f32_dpp v20, v20, v20 row_ror:4 row_mask:0xf bank_mask:0xf bound_ctrl:1
	v_add_f32_dpp v18, v18, v18 row_ror:4 row_mask:0xf bank_mask:0xf bound_ctrl:1
	s_nop 0
	v_add_f32_dpp v20, v20, v20 row_ror:2 row_mask:0xf bank_mask:0xf bound_ctrl:1
	v_add_f32_dpp v18, v18, v18 row_ror:2 row_mask:0xf bank_mask:0xf bound_ctrl:1
	s_nop 0
	v_add_f32_dpp v20, v20, v20 row_ror:1 row_mask:0xf bank_mask:0xf bound_ctrl:1
	v_add_f32_dpp v18, v18, v18 row_ror:1 row_mask:0xf bank_mask:0xf bound_ctrl:1
	v_pk_mul_f32 v[24:25], v[10:11], v[20:21] op_sel_hi:[1,0]
	v_pk_mul_f32 v[10:11], v[10:11], v[18:19] op_sel_hi:[1,0]
	v_pk_fma_f32 v[24:25], v[14:15], v[102:103], v[24:25] op_sel_hi:[1,0,1]
	v_pk_fma_f32 v[10:11], v[14:15], v[22:23], v[10:11] op_sel_hi:[1,0,1]
	s_waitcnt vmcnt(7)
	v_pk_fma_f32 v[54:55], v[192:193], v[50:51], v[24:25]
	v_pk_mul_f32 v[20:21], v[12:13], v[20:21] op_sel_hi:[1,0]
	v_pk_fma_f32 v[6:7], v[192:193], v[26:27], v[10:11]
	v_pk_mul_f32 v[10:11], v[12:13], v[18:19] op_sel_hi:[1,0]
	v_pk_fma_f32 v[20:21], v[16:17], v[102:103], v[20:21] op_sel_hi:[1,0,1]
	v_pk_fma_f32 v[10:11], v[16:17], v[22:23], v[10:11] op_sel_hi:[1,0,1]
	v_pk_fma_f32 v[56:57], v[194:195], v[52:53], v[20:21]
	v_pk_fma_f32 v[8:9], v[194:195], v[28:29], v[10:11]
	v_pk_mul_f32 v[10:11], v[4:5], v[56:57]
	v_pk_mul_f32 v[4:5], v[4:5], v[8:9]
	v_pk_fma_f32 v[10:11], v[2:3], v[54:55], v[10:11]
	v_pk_fma_f32 v[2:3], v[2:3], v[6:7], v[4:5]
	v_add_f32_e32 v4, v10, v11
	v_add_f32_e32 v2, v2, v3
	ds_write2st64_b32 v113, v4, v2 offset0:64 offset1:65
	s_waitcnt lgkmcnt(13)
	v_pk_mul_f32 v[2:3], v[100:101], v[56:57]
	v_pk_mul_f32 v[4:5], v[100:101], v[8:9]
	v_pk_fma_f32 v[2:3], v[98:99], v[54:55], v[2:3]
	v_pk_fma_f32 v[4:5], v[98:99], v[6:7], v[4:5]
	v_add_f32_e32 v2, v2, v3
	v_mov_b32_e32 v14, v109
	ds_read_b128 v[50:53], v118 offset:35840
	global_load_dwordx4 v[192:195], v118, s[56:57]
	s_add_u32 s56, s56, s58
	s_addc_u32 s57, s57, s59
	ds_read_b128 v[22:25], v118 offset:36352
	ds_read_b128 v[26:29], v118 offset:36608
	ds_read_b128 v[30:33], v118 offset:36864
	ds_read2_b32 v[102:103], v114 offset0:128 offset1:132
	v_add_f32_dpp v2, v2, v2 row_ror:8 row_mask:0xf bank_mask:0xf bound_ctrl:1
	s_nop 1
	v_add_f32_dpp v2, v2, v2 row_ror:4 row_mask:0xf bank_mask:0xf bound_ctrl:1
	s_nop 1
	v_add_f32_dpp v2, v2, v2 row_ror:2 row_mask:0xf bank_mask:0xf bound_ctrl:1
	s_nop 1
	v_add_f32_dpp v10, v2, v2 row_ror:1 row_mask:0xf bank_mask:0xf bound_ctrl:1
	v_add_f32_e32 v2, v4, v5
	v_pk_mul_f32 v[4:5], v[92:93], v[10:11] op_sel_hi:[1,0]
	s_nop 0
	v_add_f32_dpp v2, v2, v2 row_ror:8 row_mask:0xf bank_mask:0xf bound_ctrl:1
	v_pk_fma_f32 v[4:5], v[96:97], v[108:109], v[4:5] op_sel_hi:[1,0,1]
	s_nop 0
	v_add_f32_dpp v2, v2, v2 row_ror:4 row_mask:0xf bank_mask:0xf bound_ctrl:1
	s_waitcnt vmcnt(7)
	v_pk_fma_f32 v[4:5], v[198:199], v[56:57], v[4:5]
	s_nop 0
	v_add_f32_dpp v2, v2, v2 row_ror:2 row_mask:0xf bank_mask:0xf bound_ctrl:1
	s_nop 1
	v_add_f32_dpp v12, v2, v2 row_ror:1 row_mask:0xf bank_mask:0xf bound_ctrl:1
	v_pk_mul_f32 v[2:3], v[90:91], v[10:11] op_sel_hi:[1,0]
	v_pk_mul_f32 v[10:11], v[90:91], v[12:13] op_sel_hi:[1,0]
	v_pk_fma_f32 v[2:3], v[94:95], v[108:109], v[2:3] op_sel_hi:[1,0,1]
	v_pk_fma_f32 v[10:11], v[94:95], v[14:15], v[10:11] op_sel_hi:[1,0,1]
	v_pk_fma_f32 v[2:3], v[196:197], v[54:55], v[2:3]
	v_pk_fma_f32 v[6:7], v[196:197], v[6:7], v[10:11]
	v_pk_mul_f32 v[10:11], v[92:93], v[12:13] op_sel_hi:[1,0]
	s_nop 0
	v_pk_fma_f32 v[10:11], v[96:97], v[14:15], v[10:11] op_sel_hi:[1,0,1]
	s_waitcnt lgkmcnt(12)
	v_mov_b32_e32 v14, v107
	v_pk_fma_f32 v[8:9], v[198:199], v[8:9], v[10:11]
	v_pk_mul_f32 v[10:11], v[80:81], v[4:5]
	v_pk_mul_f32 v[12:13], v[80:81], v[8:9]
	v_pk_fma_f32 v[10:11], v[78:79], v[2:3], v[10:11]
	v_pk_fma_f32 v[12:13], v[78:79], v[6:7], v[12:13]
	v_add_f32_e32 v10, v10, v11
	v_add_f32_e32 v11, v12, v13
	ds_write2st64_b32 v113, v10, v11 offset0:72 offset1:73
	v_pk_mul_f32 v[10:11], v[48:49], v[4:5]
	v_pk_mul_f32 v[12:13], v[48:49], v[8:9]
	v_pk_fma_f32 v[10:11], v[46:47], v[2:3], v[10:11]
	v_pk_fma_f32 v[12:13], v[46:47], v[6:7], v[12:13]
	v_add_f32_e32 v10, v10, v11
	v_add_f32_e32 v11, v12, v13
	ds_read_b128 v[94:97], v118 offset:37120
	global_load_dwordx4 v[196:199], v118, s[56:57]
	s_add_u32 s56, s56, s58
	s_addc_u32 s57, s57, s59
	ds_read_b128 v[78:81], v118 offset:37632
	ds_read_b128 v[86:89], v118 offset:37888
	ds_read_b128 v[90:93], v118 offset:38144
	ds_read2_b32 v[98:99], v114 offset0:160 offset1:164
	v_add_f32_dpp v10, v10, v10 row_ror:8 row_mask:0xf bank_mask:0xf bound_ctrl:1
	v_add_f32_dpp v11, v11, v11 row_ror:8 row_mask:0xf bank_mask:0xf bound_ctrl:1
	s_nop 0
	v_add_f32_dpp v10, v10, v10 row_ror:4 row_mask:0xf bank_mask:0xf bound_ctrl:1
	v_add_f32_dpp v11, v11, v11 row_ror:4 row_mask:0xf bank_mask:0xf bound_ctrl:1
	s_nop 0
	v_add_f32_dpp v10, v10, v10 row_ror:2 row_mask:0xf bank_mask:0xf bound_ctrl:1
	v_add_f32_dpp v11, v11, v11 row_ror:2 row_mask:0xf bank_mask:0xf bound_ctrl:1
	s_nop 0
	v_add_f32_dpp v10, v10, v10 row_ror:1 row_mask:0xf bank_mask:0xf bound_ctrl:1
	v_add_f32_dpp v12, v11, v11 row_ror:1 row_mask:0xf bank_mask:0xf bound_ctrl:1
	v_pk_mul_f32 v[16:17], v[62:63], v[10:11] op_sel_hi:[1,0]
	v_pk_mul_f32 v[10:11], v[64:65], v[10:11] op_sel_hi:[1,0]
	v_pk_fma_f32 v[16:17], v[74:75], v[106:107], v[16:17] op_sel_hi:[1,0,1]
	v_pk_fma_f32 v[10:11], v[76:77], v[106:107], v[10:11] op_sel_hi:[1,0,1]
	s_waitcnt vmcnt(7)
	v_pk_fma_f32 v[2:3], v[200:201], v[2:3], v[16:17]
	v_pk_fma_f32 v[4:5], v[202:203], v[4:5], v[10:11]
	v_pk_mul_f32 v[10:11], v[62:63], v[12:13] op_sel_hi:[1,0]
	s_nop 0
	v_pk_fma_f32 v[10:11], v[74:75], v[14:15], v[10:11] op_sel_hi:[1,0,1]
	s_nop 0
	v_pk_fma_f32 v[6:7], v[200:201], v[6:7], v[10:11]
	v_pk_mul_f32 v[10:11], v[64:65], v[12:13] op_sel_hi:[1,0]
	s_nop 0
	v_pk_fma_f32 v[10:11], v[76:77], v[14:15], v[10:11] op_sel_hi:[1,0,1]
	s_waitcnt lgkmcnt(12)
	v_mov_b32_e32 v14, v105
	v_pk_fma_f32 v[8:9], v[202:203], v[8:9], v[10:11]
	v_pk_mul_f32 v[10:11], v[72:73], v[4:5]
	v_pk_mul_f32 v[12:13], v[72:73], v[8:9]
	v_pk_fma_f32 v[10:11], v[70:71], v[2:3], v[10:11]
	v_pk_fma_f32 v[12:13], v[70:71], v[6:7], v[12:13]
	v_add_f32_e32 v10, v10, v11
	v_add_f32_e32 v11, v12, v13
	ds_write2st64_b32 v113, v10, v11 offset0:80 offset1:81
	v_pk_mul_f32 v[10:11], v[36:37], v[4:5]
	v_pk_mul_f32 v[12:13], v[36:37], v[8:9]
	v_pk_fma_f32 v[10:11], v[34:35], v[2:3], v[10:11]
	v_pk_fma_f32 v[12:13], v[34:35], v[6:7], v[12:13]
	v_add_f32_e32 v10, v10, v11
	v_add_f32_e32 v11, v12, v13
	ds_read_b128 v[74:77], v118 offset:38400
	global_load_dwordx4 v[200:203], v118, s[56:57]
	s_add_u32 s56, s56, s58
	s_addc_u32 s57, s57, s59
	ds_read_b128 v[46:49], v118 offset:38912
	ds_read_b128 v[62:65], v118 offset:39168
	ds_read_b128 v[70:73], v118 offset:39424
	ds_read2_b32 v[100:101], v114 offset0:192 offset1:196
	v_add_f32_dpp v10, v10, v10 row_ror:8 row_mask:0xf bank_mask:0xf bound_ctrl:1
	v_add_f32_dpp v11, v11, v11 row_ror:8 row_mask:0xf bank_mask:0xf bound_ctrl:1
	s_nop 0
	v_add_f32_dpp v10, v10, v10 row_ror:4 row_mask:0xf bank_mask:0xf bound_ctrl:1
	v_add_f32_dpp v11, v11, v11 row_ror:4 row_mask:0xf bank_mask:0xf bound_ctrl:1
	s_nop 0
	v_add_f32_dpp v10, v10, v10 row_ror:2 row_mask:0xf bank_mask:0xf bound_ctrl:1
	v_add_f32_dpp v11, v11, v11 row_ror:2 row_mask:0xf bank_mask:0xf bound_ctrl:1
	s_nop 0
	v_add_f32_dpp v10, v10, v10 row_ror:1 row_mask:0xf bank_mask:0xf bound_ctrl:1
	v_pk_mul_f32 v[16:17], v[58:59], v[10:11] op_sel_hi:[1,0]
	v_add_f32_dpp v12, v11, v11 row_ror:1 row_mask:0xf bank_mask:0xf bound_ctrl:1
	v_pk_fma_f32 v[16:17], v[66:67], v[104:105], v[16:17] op_sel_hi:[1,0,1]
	s_nop 0
	s_waitcnt vmcnt(7)
	v_pk_fma_f32 v[106:107], v[204:205], v[2:3], v[16:17]
	v_pk_mul_f32 v[2:3], v[60:61], v[10:11] op_sel_hi:[1,0]
	s_nop 0
	v_pk_fma_f32 v[2:3], v[68:69], v[104:105], v[2:3] op_sel_hi:[1,0,1]
	s_nop 0
	v_pk_fma_f32 v[104:105], v[206:207], v[4:5], v[2:3]
	v_pk_mul_f32 v[2:3], v[58:59], v[12:13] op_sel_hi:[1,0]
	s_nop 0
	v_pk_fma_f32 v[2:3], v[66:67], v[14:15], v[2:3] op_sel_hi:[1,0,1]
	s_nop 0
	v_pk_fma_f32 v[58:59], v[204:205], v[6:7], v[2:3]
	v_pk_mul_f32 v[2:3], v[60:61], v[12:13] op_sel_hi:[1,0]
	s_waitcnt lgkmcnt(12)
	v_pk_mul_f32 v[60:61], v[52:53], v[104:105]
	v_pk_fma_f32 v[2:3], v[68:69], v[14:15], v[2:3] op_sel_hi:[1,0,1]
	v_pk_fma_f32 v[60:61], v[50:51], v[106:107], v[60:61]
	v_pk_fma_f32 v[40:41], v[206:207], v[8:9], v[2:3]
	v_pk_mul_f32 v[2:3], v[84:85], v[104:105]
	v_pk_mul_f32 v[52:53], v[52:53], v[40:41]
	v_pk_mul_f32 v[4:5], v[84:85], v[40:41]
	v_pk_fma_f32 v[50:51], v[50:51], v[58:59], v[52:53]
	v_add_f32_e32 v52, v60, v61
	v_add_f32_e32 v50, v50, v51
	v_mov_b32_e32 v60, v103
	v_add_f32_dpp v52, v52, v52 row_ror:8 row_mask:0xf bank_mask:0xf bound_ctrl:1
	v_add_f32_dpp v50, v50, v50 row_ror:8 row_mask:0xf bank_mask:0xf bound_ctrl:1
	v_pk_fma_f32 v[2:3], v[82:83], v[106:107], v[2:3]
	v_add_f32_dpp v52, v52, v52 row_ror:4 row_mask:0xf bank_mask:0xf bound_ctrl:1
	v_add_f32_dpp v50, v50, v50 row_ror:4 row_mask:0xf bank_mask:0xf bound_ctrl:1
	v_pk_fma_f32 v[4:5], v[82:83], v[58:59], v[4:5]
	v_add_f32_dpp v52, v52, v52 row_ror:2 row_mask:0xf bank_mask:0xf bound_ctrl:1
	v_add_f32_dpp v50, v50, v50 row_ror:2 row_mask:0xf bank_mask:0xf bound_ctrl:1
	v_add_f32_e32 v2, v2, v3
	v_add_f32_dpp v52, v52, v52 row_ror:1 row_mask:0xf bank_mask:0xf bound_ctrl:1
	v_add_f32_dpp v50, v50, v50 row_ror:1 row_mask:0xf bank_mask:0xf bound_ctrl:1
	v_pk_mul_f32 v[66:67], v[22:23], v[52:53] op_sel_hi:[1,0]
	v_pk_mul_f32 v[22:23], v[22:23], v[50:51] op_sel_hi:[1,0]
	v_pk_fma_f32 v[66:67], v[26:27], v[102:103], v[66:67] op_sel_hi:[1,0,1]
	v_pk_fma_f32 v[22:23], v[26:27], v[60:61], v[22:23] op_sel_hi:[1,0,1]
	s_waitcnt vmcnt(6)
	v_pk_fma_f32 v[66:67], v[208:209], v[106:107], v[66:67]
	v_pk_mul_f32 v[52:53], v[24:25], v[52:53] op_sel_hi:[1,0]
	v_pk_fma_f32 v[18:19], v[208:209], v[58:59], v[22:23]
	v_pk_mul_f32 v[22:23], v[24:25], v[50:51] op_sel_hi:[1,0]
	v_pk_fma_f32 v[52:53], v[28:29], v[102:103], v[52:53] op_sel_hi:[1,0,1]
	v_pk_fma_f32 v[22:23], v[28:29], v[60:61], v[22:23] op_sel_hi:[1,0,1]
	v_pk_fma_f32 v[52:53], v[210:211], v[104:105], v[52:53]
	v_pk_fma_f32 v[20:21], v[210:211], v[40:41], v[22:23]
	v_pk_mul_f32 v[22:23], v[32:33], v[52:53]
	v_pk_mul_f32 v[24:25], v[32:33], v[20:21]
	v_add_f32_e32 v3, v4, v5
	v_pk_fma_f32 v[22:23], v[30:31], v[66:67], v[22:23]
	v_pk_fma_f32 v[24:25], v[30:31], v[18:19], v[24:25]
	ds_write2st64_b32 v113, v2, v3 offset0:88 offset1:89
	v_add_f32_e32 v22, v22, v23
	v_add_f32_e32 v23, v24, v25
	ds_read_b128 v[34:37], v118 offset:39680
	global_load_dwordx4 v[204:207], v118, s[56:57]
	s_add_u32 s56, s56, s58
	s_addc_u32 s57, s57, s59
	ds_read_b128 v[6:9], v118 offset:40192
	ds_read_b128 v[10:13], v118 offset:40448
	ds_read_b128 v[14:17], v118 offset:40704
	ds_read2_b32 v[38:39], v114 offset0:224 offset1:228
	ds_write2st64_b32 v113, v22, v23 offset0:96 offset1:97
	s_waitcnt lgkmcnt(13)
	v_pk_mul_f32 v[22:23], v[96:97], v[52:53]
	v_pk_mul_f32 v[24:25], v[96:97], v[20:21]
	v_pk_fma_f32 v[22:23], v[94:95], v[66:67], v[22:23]
	v_pk_fma_f32 v[24:25], v[94:95], v[18:19], v[24:25]
	v_add_f32_e32 v22, v22, v23
	v_add_f32_e32 v23, v24, v25
	v_mov_b32_e32 v26, v99
	v_add_f32_dpp v22, v22, v22 row_ror:8 row_mask:0xf bank_mask:0xf bound_ctrl:1
	v_add_f32_dpp v23, v23, v23 row_ror:8 row_mask:0xf bank_mask:0xf bound_ctrl:1
	s_waitcnt lgkmcnt(7)
	v_mov_b32_e32 v32, v101
	v_add_f32_dpp v22, v22, v22 row_ror:4 row_mask:0xf bank_mask:0xf bound_ctrl:1
	v_add_f32_dpp v23, v23, v23 row_ror:4 row_mask:0xf bank_mask:0xf bound_ctrl:1
	s_nop 0
	v_add_f32_dpp v22, v22, v22 row_ror:2 row_mask:0xf bank_mask:0xf bound_ctrl:1
	v_add_f32_dpp v23, v23, v23 row_ror:2 row_mask:0xf bank_mask:0xf bound_ctrl:1
	s_nop 0
	v_add_f32_dpp v22, v22, v22 row_ror:1 row_mask:0xf bank_mask:0xf bound_ctrl:1
	v_add_f32_dpp v24, v23, v23 row_ror:1 row_mask:0xf bank_mask:0xf bound_ctrl:1
	v_pk_mul_f32 v[28:29], v[78:79], v[22:23] op_sel_hi:[1,0]
	v_pk_mul_f32 v[22:23], v[80:81], v[22:23] op_sel_hi:[1,0]
	v_pk_mul_f32 v[30:31], v[78:79], v[24:25] op_sel_hi:[1,0]
	v_pk_mul_f32 v[24:25], v[80:81], v[24:25] op_sel_hi:[1,0]
	v_pk_fma_f32 v[22:23], v[88:89], v[98:99], v[22:23] op_sel_hi:[1,0,1]
	v_pk_fma_f32 v[24:25], v[88:89], v[26:27], v[24:25] op_sel_hi:[1,0,1]
	v_pk_fma_f32 v[28:29], v[86:87], v[98:99], v[28:29] op_sel_hi:[1,0,1]
	s_waitcnt vmcnt(6)
	v_pk_fma_f32 v[22:23], v[214:215], v[52:53], v[22:23]
	v_pk_fma_f32 v[30:31], v[86:87], v[26:27], v[30:31] op_sel_hi:[1,0,1]
	v_pk_fma_f32 v[26:27], v[214:215], v[20:21], v[24:25]
	v_pk_fma_f32 v[28:29], v[212:213], v[66:67], v[28:29]
	v_pk_fma_f32 v[18:19], v[212:213], v[18:19], v[30:31]
	v_pk_mul_f32 v[20:21], v[92:93], v[22:23]
	v_pk_mul_f32 v[24:25], v[92:93], v[26:27]
	v_pk_fma_f32 v[20:21], v[90:91], v[28:29], v[20:21]
	v_pk_fma_f32 v[24:25], v[90:91], v[18:19], v[24:25]
	v_add_f32_e32 v20, v20, v21
	v_add_f32_e32 v21, v24, v25
	ds_write2st64_b32 v113, v20, v21 offset0:104 offset1:105
	ds_read_b32 v249, v246
	v_pk_mul_f32 v[20:21], v[76:77], v[22:23]
	v_pk_mul_f32 v[24:25], v[76:77], v[26:27]
	v_pk_fma_f32 v[20:21], v[74:75], v[28:29], v[20:21]
	v_pk_fma_f32 v[24:25], v[74:75], v[18:19], v[24:25]
	v_add_f32_e32 v20, v20, v21
	v_add_f32_e32 v21, v24, v25
	s_nop 0
	v_add_f32_dpp v20, v20, v20 row_ror:8 row_mask:0xf bank_mask:0xf bound_ctrl:1
	v_add_f32_dpp v21, v21, v21 row_ror:8 row_mask:0xf bank_mask:0xf bound_ctrl:1
	s_nop 0
	v_add_f32_dpp v20, v20, v20 row_ror:4 row_mask:0xf bank_mask:0xf bound_ctrl:1
	v_add_f32_dpp v21, v21, v21 row_ror:4 row_mask:0xf bank_mask:0xf bound_ctrl:1
	s_nop 0
	v_add_f32_dpp v20, v20, v20 row_ror:2 row_mask:0xf bank_mask:0xf bound_ctrl:1
	v_add_f32_dpp v21, v21, v21 row_ror:2 row_mask:0xf bank_mask:0xf bound_ctrl:1
	s_nop 0
	v_add_f32_dpp v20, v20, v20 row_ror:1 row_mask:0xf bank_mask:0xf bound_ctrl:1
	v_add_f32_dpp v30, v21, v21 row_ror:1 row_mask:0xf bank_mask:0xf bound_ctrl:1
	v_pk_mul_f32 v[24:25], v[46:47], v[20:21] op_sel_hi:[1,0]
	v_pk_mul_f32 v[20:21], v[48:49], v[20:21] op_sel_hi:[1,0]
	v_pk_fma_f32 v[24:25], v[62:63], v[100:101], v[24:25] op_sel_hi:[1,0,1]
	v_pk_fma_f32 v[20:21], v[64:65], v[100:101], v[20:21] op_sel_hi:[1,0,1]
	s_waitcnt vmcnt(5)
	v_pk_fma_f32 v[24:25], v[216:217], v[28:29], v[24:25]
	v_pk_fma_f32 v[22:23], v[218:219], v[22:23], v[20:21]
	v_pk_mul_f32 v[20:21], v[46:47], v[30:31] op_sel_hi:[1,0]
	s_nop 0
	v_pk_fma_f32 v[20:21], v[62:63], v[32:33], v[20:21] op_sel_hi:[1,0,1]
	s_nop 0
	v_pk_fma_f32 v[20:21], v[216:217], v[18:19], v[20:21]
	v_pk_mul_f32 v[18:19], v[48:49], v[30:31] op_sel_hi:[1,0]
	s_nop 0
	v_pk_fma_f32 v[18:19], v[64:65], v[32:33], v[18:19] op_sel_hi:[1,0,1]
	s_nop 0
	v_pk_fma_f32 v[18:19], v[218:219], v[26:27], v[18:19]
	v_pk_mul_f32 v[26:27], v[72:73], v[22:23]
	v_pk_mul_f32 v[28:29], v[72:73], v[18:19]
	v_pk_fma_f32 v[26:27], v[70:71], v[24:25], v[26:27]
	v_pk_fma_f32 v[28:29], v[70:71], v[20:21], v[28:29]
	v_add_f32_e32 v26, v26, v27
	v_add_f32_e32 v27, v28, v29
	ds_write2st64_b32 v113, v26, v27 offset0:112 offset1:113
	s_add_i32 s64, s4, 2
	s_waitcnt lgkmcnt(1)
	v_cmp_gt_u32_e32 vcc, s64, v249
	s_nop 0
	s_cbranch_vccnz .Lsflag_slow_2
.Lsflag_go_2:
	ds_read_b128 v[224:227], v118
	ds_read_b128 v[228:231], v118 offset:512
	ds_read_b128 v[232:235], v118 offset:768
	ds_read_b128 v[236:239], v118 offset:1024
	s_waitcnt lgkmcnt(5)
	v_pk_mul_f32 v[26:27], v[36:37], v[22:23]
	v_pk_mul_f32 v[28:29], v[36:37], v[18:19]
	v_pk_fma_f32 v[26:27], v[34:35], v[24:25], v[26:27]
	v_pk_fma_f32 v[30:31], v[34:35], v[20:21], v[28:29]
	v_add_f32_e32 v26, v26, v27
	s_nop 1
	v_add_f32_dpp v26, v26, v26 row_ror:8 row_mask:0xf bank_mask:0xf bound_ctrl:1
	s_nop 1
	v_add_f32_dpp v26, v26, v26 row_ror:4 row_mask:0xf bank_mask:0xf bound_ctrl:1
	s_nop 1
	v_add_f32_dpp v26, v26, v26 row_ror:2 row_mask:0xf bank_mask:0xf bound_ctrl:1
	s_nop 1
	v_add_f32_dpp v28, v26, v26 row_ror:1 row_mask:0xf bank_mask:0xf bound_ctrl:1
	v_add_f32_e32 v26, v30, v31
	s_waitcnt lgkmcnt(5)
	v_mov_b32_e32 v30, v39
	v_pk_mul_f32 v[32:33], v[6:7], v[28:29] op_sel_hi:[1,0]
	v_add_f32_dpp v26, v26, v26 row_ror:8 row_mask:0xf bank_mask:0xf bound_ctrl:1
	v_pk_fma_f32 v[32:33], v[10:11], v[38:39], v[32:33] op_sel_hi:[1,0,1]
	s_nop 0
	v_add_f32_dpp v26, v26, v26 row_ror:4 row_mask:0xf bank_mask:0xf bound_ctrl:1
	s_waitcnt vmcnt(4)
	v_pk_fma_f32 v[84:85], v[220:221], v[24:25], v[32:33]
	v_pk_mul_f32 v[24:25], v[8:9], v[28:29] op_sel_hi:[1,0]
	v_add_f32_dpp v26, v26, v26 row_ror:2 row_mask:0xf bank_mask:0xf bound_ctrl:1
	v_pk_fma_f32 v[24:25], v[12:13], v[38:39], v[24:25] op_sel_hi:[1,0,1]
	s_nop 0
	v_add_f32_dpp v26, v26, v26 row_ror:1 row_mask:0xf bank_mask:0xf bound_ctrl:1
	v_pk_mul_f32 v[6:7], v[6:7], v[26:27] op_sel_hi:[1,0]
	v_pk_fma_f32 v[86:87], v[222:223], v[22:23], v[24:25]
	v_pk_fma_f32 v[6:7], v[10:11], v[30:31], v[6:7] op_sel_hi:[1,0,1]
	s_nop 0
	v_pk_fma_f32 v[88:89], v[220:221], v[20:21], v[6:7]
	v_pk_mul_f32 v[2:3], v[8:9], v[26:27] op_sel_hi:[1,0]
	s_nop 0
	v_pk_fma_f32 v[2:3], v[12:13], v[30:31], v[2:3] op_sel_hi:[1,0,1]
	s_nop 0
	v_pk_fma_f32 v[92:93], v[222:223], v[18:19], v[2:3]
	v_pk_mul_f32 v[2:3], v[16:17], v[86:87]
	v_pk_mul_f32 v[4:5], v[16:17], v[92:93]
	v_pk_fma_f32 v[2:3], v[14:15], v[84:85], v[2:3]
	v_pk_fma_f32 v[4:5], v[14:15], v[88:89], v[4:5]
	v_add_f32_e32 v2, v2, v3
	v_add_f32_e32 v3, v4, v5
	ds_write2st64_b32 v113, v2, v3 offset0:120 offset1:121
	v_mov_b32_e32 v248, s64
	ds_write_b32 v247, v248
	global_load_dwordx4 v[208:211], v118, s[56:57]
	s_add_u32 s56, s56, s58
	s_addc_u32 s57, s57, s59
	ds_read2_b32 v[94:95], v121 offset1:4
	ds_read_b128 v[42:45], v118 offset:1280
	global_load_dwordx4 v[212:215], v118, s[56:57]
	s_add_u32 s56, s56, s58
	s_addc_u32 s57, s57, s59
	ds_read_b128 v[62:65], v118 offset:1792
	ds_read_b128 v[70:73], v118 offset:2048
	ds_read_b128 v[74:77], v118 offset:2304
	ds_read2_b32 v[96:97], v121 offset0:32 offset1:36
	ds_read_b128 v[78:81], v118 offset:2560
	global_load_dwordx4 v[216:219], v118, s[56:57]
	s_add_u32 s56, s56, s58
	s_addc_u32 s57, s57, s59
	ds_read_b128 v[58:61], v118 offset:3072
	ds_read_b128 v[66:69], v118 offset:3328
	ds_read_b128 v[10:13], v118 offset:3584
	ds_read2_b32 v[82:83], v121 offset0:64 offset1:68
	ds_read_b128 v[50:53], v118 offset:3840
	global_load_dwordx4 v[220:223], v118, s[56:57]
	s_add_u32 s56, s56, s58
	s_addc_u32 s57, s57, s59
	ds_read_b128 v[30:33], v118 offset:4352
	ds_read_b128 v[34:37], v118 offset:4608
	ds_read_b128 v[6:9], v118 offset:4864
	ds_read2_b32 v[90:91], v121 offset0:96 offset1:100
	s_waitcnt lgkmcnt(12)
	v_pk_mul_f32 v[98:99], v[226:227], v[86:87]
	v_pk_mul_f32 v[4:5], v[226:227], v[92:93]
	v_pk_fma_f32 v[98:99], v[224:225], v[84:85], v[98:99]
	v_pk_fma_f32 v[2:3], v[224:225], v[88:89], v[4:5]
	v_add_f32_e32 v4, v98, v99
	v_add_f32_e32 v2, v2, v3
	v_mov_b32_e32 v98, v95
	v_add_f32_dpp v4, v4, v4 row_ror:8 row_mask:0xf bank_mask:0xf bound_ctrl:1
	v_add_f32_dpp v2, v2, v2 row_ror:8 row_mask:0xf bank_mask:0xf bound_ctrl:1
	s_nop 0
	v_add_f32_dpp v4, v4, v4 row_ror:4 row_mask:0xf bank_mask:0xf bound_ctrl:1
	v_add_f32_dpp v2, v2, v2 row_ror:4 row_mask:0xf bank_mask:0xf bound_ctrl:1
	s_nop 0
	v_add_f32_dpp v4, v4, v4 row_ror:2 row_mask:0xf bank_mask:0xf bound_ctrl:1
	v_add_f32_dpp v2, v2, v2 row_ror:2 row_mask:0xf bank_mask:0xf bound_ctrl:1
	s_nop 0
	v_add_f32_dpp v4, v4, v4 row_ror:1 row_mask:0xf bank_mask:0xf bound_ctrl:1
	v_pk_mul_f32 v[100:101], v[228:229], v[4:5] op_sel_hi:[1,0]
	v_pk_mul_f32 v[4:5], v[230:231], v[4:5] op_sel_hi:[1,0]
	v_add_f32_dpp v2, v2, v2 row_ror:1 row_mask:0xf bank_mask:0xf bound_ctrl:1
	v_pk_fma_f32 v[4:5], v[234:235], v[94:95], v[4:5] op_sel_hi:[1,0,1]
	v_pk_fma_f32 v[100:101], v[232:233], v[94:95], v[100:101] op_sel_hi:[1,0,1]
	s_waitcnt vmcnt(7)
	v_pk_fma_f32 v[86:87], v[194:195], v[86:87], v[4:5]
	v_pk_mul_f32 v[4:5], v[228:229], v[2:3] op_sel_hi:[1,0]
	v_pk_mul_f32 v[2:3], v[230:231], v[2:3] op_sel_hi:[1,0]
	v_pk_fma_f32 v[84:85], v[192:193], v[84:85], v[100:101]
	v_pk_fma_f32 v[2:3], v[234:235], v[98:99], v[2:3] op_sel_hi:[1,0,1]
	v_pk_fma_f32 v[4:5], v[232:233], v[98:99], v[4:5] op_sel_hi:[1,0,1]
	v_pk_fma_f32 v[92:93], v[194:195], v[92:93], v[2:3]
	v_pk_mul_f32 v[98:99], v[44:45], v[86:87]
	v_pk_fma_f32 v[88:89], v[192:193], v[88:89], v[4:5]
	v_pk_fma_f32 v[98:99], v[42:43], v[84:85], v[98:99]
	v_pk_mul_f32 v[44:45], v[44:45], v[92:93]
	v_pk_mul_f32 v[2:3], v[238:239], v[86:87]
	v_pk_fma_f32 v[42:43], v[42:43], v[88:89], v[44:45]
	v_add_f32_e32 v44, v98, v99
	v_add_f32_e32 v42, v42, v43
	s_waitcnt lgkmcnt(10)
	v_mov_b32_e32 v98, v97
	v_add_f32_dpp v44, v44, v44 row_ror:8 row_mask:0xf bank_mask:0xf bound_ctrl:1
	v_add_f32_dpp v42, v42, v42 row_ror:8 row_mask:0xf bank_mask:0xf bound_ctrl:1
	v_pk_mul_f32 v[4:5], v[238:239], v[92:93]
	v_add_f32_dpp v44, v44, v44 row_ror:4 row_mask:0xf bank_mask:0xf bound_ctrl:1
	v_add_f32_dpp v42, v42, v42 row_ror:4 row_mask:0xf bank_mask:0xf bound_ctrl:1
	v_pk_fma_f32 v[2:3], v[236:237], v[84:85], v[2:3]
	v_add_f32_dpp v44, v44, v44 row_ror:2 row_mask:0xf bank_mask:0xf bound_ctrl:1
	v_add_f32_dpp v42, v42, v42 row_ror:2 row_mask:0xf bank_mask:0xf bound_ctrl:1
	v_pk_fma_f32 v[4:5], v[236:237], v[88:89], v[4:5]
	v_add_f32_dpp v44, v44, v44 row_ror:1 row_mask:0xf bank_mask:0xf bound_ctrl:1
	v_pk_mul_f32 v[100:101], v[62:63], v[44:45] op_sel_hi:[1,0]
	v_pk_mul_f32 v[44:45], v[64:65], v[44:45] op_sel_hi:[1,0]
	v_add_f32_dpp v42, v42, v42 row_ror:1 row_mask:0xf bank_mask:0xf bound_ctrl:1
	v_pk_fma_f32 v[44:45], v[72:73], v[96:97], v[44:45] op_sel_hi:[1,0,1]
	v_pk_fma_f32 v[100:101], v[70:71], v[96:97], v[100:101] op_sel_hi:[1,0,1]
	s_waitcnt vmcnt(6)
	v_pk_fma_f32 v[86:87], v[198:199], v[86:87], v[44:45]
	v_pk_mul_f32 v[44:45], v[62:63], v[42:43] op_sel_hi:[1,0]
	v_pk_mul_f32 v[42:43], v[64:65], v[42:43] op_sel_hi:[1,0]
	v_pk_fma_f32 v[44:45], v[70:71], v[98:99], v[44:45] op_sel_hi:[1,0,1]
	v_pk_fma_f32 v[42:43], v[72:73], v[98:99], v[42:43] op_sel_hi:[1,0,1]
	v_pk_fma_f32 v[84:85], v[196:197], v[84:85], v[100:101]
	v_pk_fma_f32 v[92:93], v[198:199], v[92:93], v[42:43]
	v_pk_fma_f32 v[88:89], v[196:197], v[88:89], v[44:45]
	s_waitcnt lgkmcnt(9)
	v_pk_mul_f32 v[98:99], v[80:81], v[86:87]
	v_pk_mul_f32 v[80:81], v[80:81], v[92:93]
	v_pk_fma_f32 v[98:99], v[78:79], v[84:85], v[98:99]
	v_pk_fma_f32 v[78:79], v[78:79], v[88:89], v[80:81]
	v_add_f32_e32 v80, v98, v99
	v_add_f32_e32 v78, v78, v79
	s_waitcnt lgkmcnt(5)
	v_mov_b32_e32 v98, v83
	v_add_f32_dpp v80, v80, v80 row_ror:8 row_mask:0xf bank_mask:0xf bound_ctrl:1
	v_add_f32_dpp v78, v78, v78 row_ror:8 row_mask:0xf bank_mask:0xf bound_ctrl:1
	v_pk_mul_f32 v[44:45], v[76:77], v[92:93]
	v_add_f32_dpp v80, v80, v80 row_ror:4 row_mask:0xf bank_mask:0xf bound_ctrl:1
	v_add_f32_dpp v78, v78, v78 row_ror:4 row_mask:0xf bank_mask:0xf bound_ctrl:1
	v_add_f32_e32 v2, v2, v3
	v_add_f32_dpp v80, v80, v80 row_ror:2 row_mask:0xf bank_mask:0xf bound_ctrl:1
	v_add_f32_dpp v78, v78, v78 row_ror:2 row_mask:0xf bank_mask:0xf bound_ctrl:1
	v_add_f32_e32 v3, v4, v5
	v_add_f32_dpp v80, v80, v80 row_ror:1 row_mask:0xf bank_mask:0xf bound_ctrl:1
	v_add_f32_dpp v78, v78, v78 row_ror:1 row_mask:0xf bank_mask:0xf bound_ctrl:1
	v_pk_mul_f32 v[100:101], v[58:59], v[80:81] op_sel_hi:[1,0]
	v_pk_mul_f32 v[58:59], v[58:59], v[78:79] op_sel_hi:[1,0]
	v_pk_fma_f32 v[100:101], v[66:67], v[82:83], v[100:101] op_sel_hi:[1,0,1]
	v_pk_fma_f32 v[58:59], v[66:67], v[98:99], v[58:59] op_sel_hi:[1,0,1]
	s_waitcnt vmcnt(5)
	v_pk_fma_f32 v[100:101], v[200:201], v[84:85], v[100:101]
	v_pk_mul_f32 v[80:81], v[60:61], v[80:81] op_sel_hi:[1,0]
	v_pk_fma_f32 v[66:67], v[200:201], v[88:89], v[58:59]
	v_pk_mul_f32 v[46:47], v[60:61], v[78:79] op_sel_hi:[1,0]
	v_pk_fma_f32 v[80:81], v[68:69], v[82:83], v[80:81] op_sel_hi:[1,0,1]
	v_pk_fma_f32 v[46:47], v[68:69], v[98:99], v[46:47] op_sel_hi:[1,0,1]
	v_pk_fma_f32 v[80:81], v[202:203], v[86:87], v[80:81]
	v_pk_fma_f32 v[68:69], v[202:203], v[92:93], v[46:47]
	s_waitcnt lgkmcnt(4)
	v_pk_mul_f32 v[78:79], v[52:53], v[80:81]
	v_pk_mul_f32 v[52:53], v[52:53], v[68:69]
	v_pk_fma_f32 v[78:79], v[50:51], v[100:101], v[78:79]
	v_pk_fma_f32 v[50:51], v[50:51], v[66:67], v[52:53]
	v_add_f32_e32 v52, v78, v79
	v_add_f32_e32 v50, v50, v51
	s_waitcnt lgkmcnt(0)
	v_mov_b32_e32 v78, v91
	v_add_f32_dpp v52, v52, v52 row_ror:8 row_mask:0xf bank_mask:0xf bound_ctrl:1
	v_add_f32_dpp v50, v50, v50 row_ror:8 row_mask:0xf bank_mask:0xf bound_ctrl:1
	v_pk_mul_f32 v[46:47], v[12:13], v[80:81]
	v_add_f32_dpp v52, v52, v52 row_ror:4 row_mask:0xf bank_mask:0xf bound_ctrl:1
	v_add_f32_dpp v50, v50, v50 row_ror:4 row_mask:0xf bank_mask:0xf bound_ctrl:1
	v_pk_fma_f32 v[46:47], v[10:11], v[100:101], v[46:47]
	v_add_f32_dpp v52, v52, v52 row_ror:2 row_mask:0xf bank_mask:0xf bound_ctrl:1
	v_add_f32_dpp v50, v50, v50 row_ror:2 row_mask:0xf bank_mask:0xf bound_ctrl:1
	ds_write2st64_b32 v111, v2, v3 offset0:176 offset1:177
	v_add_f32_dpp v52, v52, v52 row_ror:1 row_mask:0xf bank_mask:0xf bound_ctrl:1
	v_add_f32_dpp v50, v50, v50 row_ror:1 row_mask:0xf bank_mask:0xf bound_ctrl:1
	v_pk_mul_f32 v[92:93], v[30:31], v[52:53] op_sel_hi:[1,0]
	v_pk_mul_f32 v[30:31], v[30:31], v[50:51] op_sel_hi:[1,0]
	v_pk_fma_f32 v[92:93], v[34:35], v[90:91], v[92:93] op_sel_hi:[1,0,1]
	v_pk_fma_f32 v[30:31], v[34:35], v[78:79], v[30:31] op_sel_hi:[1,0,1]
	s_waitcnt vmcnt(4)
	v_pk_fma_f32 v[100:101], v[204:205], v[100:101], v[92:93]
	v_pk_mul_f32 v[52:53], v[32:33], v[52:53] op_sel_hi:[1,0]
	v_pk_fma_f32 v[30:31], v[204:205], v[66:67], v[30:31]
	v_pk_mul_f32 v[14:15], v[32:33], v[50:51] op_sel_hi:[1,0]
	v_pk_fma_f32 v[52:53], v[36:37], v[90:91], v[52:53] op_sel_hi:[1,0,1]
	v_pk_fma_f32 v[14:15], v[36:37], v[78:79], v[14:15] op_sel_hi:[1,0,1]
	ds_read_b128 v[38:41], v118 offset:5120
	global_load_dwordx4 v[192:195], v118, s[56:57]
	s_add_u32 s56, s56, s58
	s_addc_u32 s57, s57, s59
	ds_read_b128 v[22:25], v118 offset:5632
	ds_read_b128 v[26:29], v118 offset:5888
	ds_read_b128 v[2:5], v118 offset:6144
	ds_read2_b32 v[94:95], v121 offset0:128 offset1:132
	v_pk_fma_f32 v[80:81], v[206:207], v[80:81], v[52:53]
	v_pk_fma_f32 v[32:33], v[206:207], v[68:69], v[14:15]
	s_waitcnt lgkmcnt(4)
	v_pk_mul_f32 v[78:79], v[40:41], v[80:81]
	v_pk_mul_f32 v[40:41], v[40:41], v[32:33]
	v_pk_fma_f32 v[78:79], v[38:39], v[100:101], v[78:79]
	v_pk_fma_f32 v[38:39], v[38:39], v[30:31], v[40:41]
	v_add_f32_e32 v40, v78, v79
	v_add_f32_e32 v38, v38, v39
	s_waitcnt lgkmcnt(0)
	v_mov_b32_e32 v78, v95
	v_add_f32_dpp v40, v40, v40 row_ror:8 row_mask:0xf bank_mask:0xf bound_ctrl:1
	v_add_f32_dpp v38, v38, v38 row_ror:8 row_mask:0xf bank_mask:0xf bound_ctrl:1
	v_pk_mul_f32 v[14:15], v[8:9], v[80:81]
	v_add_f32_dpp v40, v40, v40 row_ror:4 row_mask:0xf bank_mask:0xf bound_ctrl:1
	v_add_f32_dpp v38, v38, v38 row_ror:4 row_mask:0xf bank_mask:0xf bound_ctrl:1
	v_pk_mul_f32 v[42:43], v[76:77], v[86:87]
	v_add_f32_dpp v40, v40, v40 row_ror:2 row_mask:0xf bank_mask:0xf bound_ctrl:1
	v_add_f32_dpp v38, v38, v38 row_ror:2 row_mask:0xf bank_mask:0xf bound_ctrl:1
	v_pk_fma_f32 v[14:15], v[6:7], v[100:101], v[14:15]
	v_add_f32_dpp v40, v40, v40 row_ror:1 row_mask:0xf bank_mask:0xf bound_ctrl:1
	v_add_f32_dpp v38, v38, v38 row_ror:1 row_mask:0xf bank_mask:0xf bound_ctrl:1
	v_pk_mul_f32 v[90:91], v[22:23], v[40:41] op_sel_hi:[1,0]
	v_pk_mul_f32 v[22:23], v[22:23], v[38:39] op_sel_hi:[1,0]
	v_pk_fma_f32 v[90:91], v[26:27], v[94:95], v[90:91] op_sel_hi:[1,0,1]
	v_pk_mul_f32 v[40:41], v[24:25], v[40:41] op_sel_hi:[1,0]
	v_pk_fma_f32 v[22:23], v[26:27], v[78:79], v[22:23] op_sel_hi:[1,0,1]
	s_waitcnt vmcnt(4)
	v_pk_fma_f32 v[100:101], v[208:209], v[100:101], v[90:91]
	v_pk_fma_f32 v[40:41], v[28:29], v[94:95], v[40:41] op_sel_hi:[1,0,1]
	v_pk_fma_f32 v[94:95], v[208:209], v[30:31], v[22:23]
	v_pk_mul_f32 v[18:19], v[24:25], v[38:39] op_sel_hi:[1,0]
	v_pk_fma_f32 v[42:43], v[74:75], v[84:85], v[42:43]
	v_pk_fma_f32 v[44:45], v[74:75], v[88:89], v[44:45]
	v_pk_mul_f32 v[12:13], v[12:13], v[68:69]
	v_pk_fma_f32 v[18:19], v[28:29], v[78:79], v[18:19] op_sel_hi:[1,0,1]
	v_add_f32_e32 v42, v42, v43
	v_add_f32_e32 v43, v44, v45
	v_pk_fma_f32 v[10:11], v[10:11], v[66:67], v[12:13]
	v_pk_mul_f32 v[8:9], v[8:9], v[32:33]
	v_pk_fma_f32 v[80:81], v[210:211], v[80:81], v[40:41]
	v_pk_fma_f32 v[78:79], v[210:211], v[32:33], v[18:19]
	ds_write2st64_b32 v111, v42, v43 offset0:184 offset1:185
	v_add_f32_e32 v12, v46, v47
	v_add_f32_e32 v10, v10, v11
	v_pk_fma_f32 v[6:7], v[6:7], v[30:31], v[8:9]
	v_pk_mul_f32 v[18:19], v[4:5], v[80:81]
	v_pk_mul_f32 v[4:5], v[4:5], v[78:79]
	ds_read_b128 v[74:77], v118 offset:6400
	global_load_dwordx4 v[196:199], v118, s[56:57]
	s_add_u32 s56, s56, s58
	s_addc_u32 s57, s57, s59
	ds_read_b128 v[62:65], v118 offset:6912
	ds_read_b128 v[70:73], v118 offset:7168
	ds_read_b128 v[42:45], v118 offset:7424
	ds_read2_b32 v[96:97], v121 offset0:160 offset1:164
	ds_write2st64_b32 v111, v12, v10 offset0:192 offset1:193
	v_add_f32_e32 v8, v14, v15
	v_add_f32_e32 v6, v6, v7
	v_pk_fma_f32 v[18:19], v[2:3], v[100:101], v[18:19]
	v_pk_fma_f32 v[2:3], v[2:3], v[94:95], v[4:5]
	ds_read_b128 v[86:89], v118 offset:7680
	global_load_dwordx4 v[200:203], v118, s[56:57]
	s_add_u32 s56, s56, s58
	s_addc_u32 s57, s57, s59
	ds_read_b128 v[58:61], v118 offset:8192
	ds_read_b128 v[82:85], v118 offset:8448
	ds_read_b128 v[10:13], v118 offset:8704
	ds_read2_b32 v[98:99], v121 offset0:192 offset1:196
	ds_write2st64_b32 v111, v8, v6 offset0:200 offset1:201
	v_add_f32_e32 v4, v18, v19
	v_add_f32_e32 v2, v2, v3
	ds_read_b128 v[66:69], v118 offset:8960
	global_load_dwordx4 v[204:207], v118, s[56:57]
	s_add_u32 s56, s56, s58
	s_addc_u32 s57, s57, s59
	ds_read_b128 v[34:37], v118 offset:9472
	ds_read_b128 v[50:53], v118 offset:9728
	ds_read_b128 v[6:9], v118 offset:9984
	ds_read2_b32 v[92:93], v121 offset0:224 offset1:228
	ds_write2st64_b32 v111, v4, v2 offset0:208 offset1:209
	s_waitcnt lgkmcnt(13)
	v_pk_mul_f32 v[2:3], v[76:77], v[80:81]
	v_pk_mul_f32 v[4:5], v[76:77], v[78:79]
	v_pk_fma_f32 v[2:3], v[74:75], v[100:101], v[2:3]
	v_pk_fma_f32 v[4:5], v[74:75], v[94:95], v[4:5]
	v_add_f32_e32 v2, v2, v3
	v_add_f32_e32 v3, v4, v5
	v_mov_b32_e32 v74, v97
	v_add_f32_dpp v2, v2, v2 row_ror:8 row_mask:0xf bank_mask:0xf bound_ctrl:1
	v_add_f32_dpp v3, v3, v3 row_ror:8 row_mask:0xf bank_mask:0xf bound_ctrl:1
	s_waitcnt lgkmcnt(1)
	v_mov_b32_e32 v104, v93
	v_add_f32_dpp v2, v2, v2 row_ror:4 row_mask:0xf bank_mask:0xf bound_ctrl:1
	v_add_f32_dpp v3, v3, v3 row_ror:4 row_mask:0xf bank_mask:0xf bound_ctrl:1
	ds_read_b128 v[38:41], v118 offset:10240
	global_load_dwordx4 v[208:211], v118, s[56:57]
	s_add_u32 s56, s56, s58
	s_addc_u32 s57, s57, s59
	ds_read_b128 v[26:29], v118 offset:10752
	ds_read_b128 v[30:33], v118 offset:11008
	ds_read_b128 v[18:21], v118 offset:11264
	ds_read2_b32 v[90:91], v117 offset1:4
	v_add_f32_dpp v2, v2, v2 row_ror:2 row_mask:0xf bank_mask:0xf bound_ctrl:1
	v_add_f32_dpp v3, v3, v3 row_ror:2 row_mask:0xf bank_mask:0xf bound_ctrl:1
	s_nop 0
	v_add_f32_dpp v2, v2, v2 row_ror:1 row_mask:0xf bank_mask:0xf bound_ctrl:1
	v_add_f32_dpp v4, v3, v3 row_ror:1 row_mask:0xf bank_mask:0xf bound_ctrl:1
	v_pk_mul_f32 v[76:77], v[62:63], v[2:3] op_sel_hi:[1,0]
	v_pk_mul_f32 v[2:3], v[64:65], v[2:3] op_sel_hi:[1,0]
	v_pk_mul_f32 v[62:63], v[62:63], v[4:5] op_sel_hi:[1,0]
	v_pk_fma_f32 v[2:3], v[72:73], v[96:97], v[2:3] op_sel_hi:[1,0,1]
	v_pk_mul_f32 v[4:5], v[64:65], v[4:5] op_sel_hi:[1,0]
	v_pk_fma_f32 v[76:77], v[70:71], v[96:97], v[76:77] op_sel_hi:[1,0,1]
	s_waitcnt vmcnt(7)
	v_pk_fma_f32 v[2:3], v[214:215], v[80:81], v[2:3]
	v_pk_fma_f32 v[4:5], v[72:73], v[74:75], v[4:5] op_sel_hi:[1,0,1]
	v_pk_fma_f32 v[100:101], v[212:213], v[100:101], v[76:77]
	v_pk_fma_f32 v[62:63], v[70:71], v[74:75], v[62:63] op_sel_hi:[1,0,1]
	v_pk_fma_f32 v[4:5], v[214:215], v[78:79], v[4:5]
	v_pk_mul_f32 v[56:57], v[44:45], v[2:3]
	v_pk_fma_f32 v[54:55], v[212:213], v[94:95], v[62:63]
	v_pk_fma_f32 v[56:57], v[42:43], v[100:101], v[56:57]
	v_pk_mul_f32 v[44:45], v[44:45], v[4:5]
	s_nop 0
	v_pk_fma_f32 v[42:43], v[42:43], v[54:55], v[44:45]
	v_add_f32_e32 v44, v56, v57
	v_pk_mul_f32 v[56:57], v[88:89], v[2:3]
	v_pk_mul_f32 v[88:89], v[88:89], v[4:5]
	v_pk_fma_f32 v[56:57], v[86:87], v[100:101], v[56:57]
	v_pk_fma_f32 v[86:87], v[86:87], v[54:55], v[88:89]
	v_add_f32_e32 v56, v56, v57
	v_add_f32_e32 v57, v86, v87
	v_mov_b32_e32 v88, v99
	v_add_f32_dpp v56, v56, v56 row_ror:8 row_mask:0xf bank_mask:0xf bound_ctrl:1
	v_add_f32_dpp v57, v57, v57 row_ror:8 row_mask:0xf bank_mask:0xf bound_ctrl:1
	v_add_f32_e32 v42, v42, v43
	v_add_f32_dpp v56, v56, v56 row_ror:4 row_mask:0xf bank_mask:0xf bound_ctrl:1
	v_add_f32_dpp v57, v57, v57 row_ror:4 row_mask:0xf bank_mask:0xf bound_ctrl:1
	ds_write2st64_b32 v111, v44, v42 offset0:216 offset1:217
	v_add_f32_dpp v56, v56, v56 row_ror:2 row_mask:0xf bank_mask:0xf bound_ctrl:1
	v_add_f32_dpp v57, v57, v57 row_ror:2 row_mask:0xf bank_mask:0xf bound_ctrl:1
	ds_read_b128 v[78:81], v118 offset:11520
	global_load_dwordx4 v[212:215], v118, s[56:57]
	s_add_u32 s56, s56, s58
	s_addc_u32 s57, s57, s59
	ds_read_b128 v[70:73], v118 offset:12032
	ds_read_b128 v[74:77], v118 offset:12288
	ds_read_b128 v[42:45], v118 offset:12544
	ds_read2_b32 v[94:95], v117 offset0:32 offset1:36
	v_add_f32_dpp v56, v56, v56 row_ror:1 row_mask:0xf bank_mask:0xf bound_ctrl:1
	v_add_f32_dpp v86, v57, v57 row_ror:1 row_mask:0xf bank_mask:0xf bound_ctrl:1
	v_pk_mul_f32 v[96:97], v[58:59], v[56:57] op_sel_hi:[1,0]
	v_pk_mul_f32 v[56:57], v[60:61], v[56:57] op_sel_hi:[1,0]
	v_pk_fma_f32 v[96:97], v[82:83], v[98:99], v[96:97] op_sel_hi:[1,0,1]
	v_pk_fma_f32 v[56:57], v[84:85], v[98:99], v[56:57] op_sel_hi:[1,0,1]
	s_waitcnt vmcnt(7)
	v_pk_fma_f32 v[96:97], v[216:217], v[100:101], v[96:97]
	v_pk_fma_f32 v[98:99], v[218:219], v[2:3], v[56:57]
	v_pk_mul_f32 v[2:3], v[58:59], v[86:87] op_sel_hi:[1,0]
	s_nop 0
	v_pk_fma_f32 v[2:3], v[82:83], v[88:89], v[2:3] op_sel_hi:[1,0,1]
	s_nop 0
	v_pk_fma_f32 v[100:101], v[216:217], v[54:55], v[2:3]
	v_pk_mul_f32 v[2:3], v[60:61], v[86:87] op_sel_hi:[1,0]
	s_nop 0
	v_pk_fma_f32 v[2:3], v[84:85], v[88:89], v[2:3] op_sel_hi:[1,0,1]
	v_pk_mul_f32 v[84:85], v[68:69], v[98:99]
	v_pk_fma_f32 v[102:103], v[218:219], v[4:5], v[2:3]
	v_pk_fma_f32 v[84:85], v[66:67], v[96:97], v[84:85]
	v_pk_mul_f32 v[68:69], v[68:69], v[102:103]
	v_pk_mul_f32 v[2:3], v[12:13], v[98:99]
	v_pk_fma_f32 v[66:67], v[66:67], v[100:101], v[68:69]
	v_add_f32_e32 v68, v84, v85
	v_add_f32_e32 v66, v66, v67
	v_pk_fma_f32 v[2:3], v[10:11], v[96:97], v[2:3]
	v_add_f32_dpp v68, v68, v68 row_ror:8 row_mask:0xf bank_mask:0xf bound_ctrl:1
	v_add_f32_dpp v66, v66, v66 row_ror:8 row_mask:0xf bank_mask:0xf bound_ctrl:1
	v_pk_mul_f32 v[4:5], v[12:13], v[102:103]
	v_add_f32_dpp v68, v68, v68 row_ror:4 row_mask:0xf bank_mask:0xf bound_ctrl:1
	v_add_f32_dpp v66, v66, v66 row_ror:4 row_mask:0xf bank_mask:0xf bound_ctrl:1
	v_pk_fma_f32 v[4:5], v[10:11], v[100:101], v[4:5]
	v_add_f32_dpp v68, v68, v68 row_ror:2 row_mask:0xf bank_mask:0xf bound_ctrl:1
	v_add_f32_dpp v66, v66, v66 row_ror:2 row_mask:0xf bank_mask:0xf bound_ctrl:1
	v_add_f32_e32 v2, v2, v3
	v_add_f32_dpp v68, v68, v68 row_ror:1 row_mask:0xf bank_mask:0xf bound_ctrl:1
	v_add_f32_dpp v66, v66, v66 row_ror:1 row_mask:0xf bank_mask:0xf bound_ctrl:1
	v_pk_mul_f32 v[84:85], v[34:35], v[68:69] op_sel_hi:[1,0]
	v_pk_mul_f32 v[34:35], v[34:35], v[66:67] op_sel_hi:[1,0]
	v_pk_fma_f32 v[84:85], v[50:51], v[92:93], v[84:85] op_sel_hi:[1,0,1]
	v_pk_fma_f32 v[34:35], v[50:51], v[104:105], v[34:35] op_sel_hi:[1,0,1]
	s_waitcnt vmcnt(6)
	v_pk_fma_f32 v[84:85], v[220:221], v[96:97], v[84:85]
	v_pk_mul_f32 v[68:69], v[36:37], v[68:69] op_sel_hi:[1,0]
	v_pk_fma_f32 v[88:89], v[220:221], v[100:101], v[34:35]
	v_pk_mul_f32 v[14:15], v[36:37], v[66:67] op_sel_hi:[1,0]
	v_pk_fma_f32 v[68:69], v[52:53], v[92:93], v[68:69] op_sel_hi:[1,0,1]
	v_pk_fma_f32 v[14:15], v[52:53], v[104:105], v[14:15] op_sel_hi:[1,0,1]
	v_pk_fma_f32 v[86:87], v[222:223], v[98:99], v[68:69]
	v_pk_fma_f32 v[96:97], v[222:223], v[102:103], v[14:15]
	s_waitcnt lgkmcnt(10)
	v_pk_mul_f32 v[98:99], v[40:41], v[86:87]
	v_pk_mul_f32 v[40:41], v[40:41], v[96:97]
	v_pk_fma_f32 v[98:99], v[38:39], v[84:85], v[98:99]
	v_pk_fma_f32 v[38:39], v[38:39], v[88:89], v[40:41]
	v_add_f32_e32 v40, v98, v99
	v_add_f32_e32 v38, v38, v39
	s_waitcnt lgkmcnt(6)
	v_mov_b32_e32 v98, v91
	v_add_f32_dpp v40, v40, v40 row_ror:8 row_mask:0xf bank_mask:0xf bound_ctrl:1
	v_add_f32_dpp v38, v38, v38 row_ror:8 row_mask:0xf bank_mask:0xf bound_ctrl:1
	v_pk_mul_f32 v[14:15], v[8:9], v[86:87]
	v_add_f32_dpp v40, v40, v40 row_ror:4 row_mask:0xf bank_mask:0xf bound_ctrl:1
	v_add_f32_dpp v38, v38, v38 row_ror:4 row_mask:0xf bank_mask:0xf bound_ctrl:1
	v_pk_mul_f32 v[8:9], v[8:9], v[96:97]
	v_add_f32_dpp v40, v40, v40 row_ror:2 row_mask:0xf bank_mask:0xf bound_ctrl:1
	v_add_f32_dpp v38, v38, v38 row_ror:2 row_mask:0xf bank_mask:0xf bound_ctrl:1
	v_pk_fma_f32 v[14:15], v[6:7], v[84:85], v[14:15]
	v_add_f32_dpp v40, v40, v40 row_ror:1 row_mask:0xf bank_mask:0xf bound_ctrl:1
	v_add_f32_dpp v38, v38, v38 row_ror:1 row_mask:0xf bank_mask:0xf bound_ctrl:1
	v_pk_mul_f32 v[100:101], v[26:27], v[40:41] op_sel_hi:[1,0]
	v_pk_mul_f32 v[26:27], v[26:27], v[38:39] op_sel_hi:[1,0]
	v_pk_fma_f32 v[100:101], v[30:31], v[90:91], v[100:101] op_sel_hi:[1,0,1]
	v_pk_fma_f32 v[26:27], v[30:31], v[98:99], v[26:27] op_sel_hi:[1,0,1]
	v_pk_fma_f32 v[6:7], v[6:7], v[88:89], v[8:9]
	s_waitcnt vmcnt(5)
	v_pk_fma_f32 v[84:85], v[192:193], v[84:85], v[100:101]
	v_pk_mul_f32 v[40:41], v[28:29], v[40:41] op_sel_hi:[1,0]
	v_pk_fma_f32 v[88:89], v[192:193], v[88:89], v[26:27]
	v_pk_mul_f32 v[22:23], v[28:29], v[38:39] op_sel_hi:[1,0]
	v_pk_fma_f32 v[40:41], v[32:33], v[90:91], v[40:41] op_sel_hi:[1,0,1]
	v_pk_fma_f32 v[22:23], v[32:33], v[98:99], v[22:23] op_sel_hi:[1,0,1]
	v_pk_fma_f32 v[86:87], v[194:195], v[86:87], v[40:41]
	v_pk_fma_f32 v[96:97], v[194:195], v[96:97], v[22:23]
	s_waitcnt lgkmcnt(4)
	v_pk_mul_f32 v[98:99], v[80:81], v[86:87]
	v_pk_mul_f32 v[80:81], v[80:81], v[96:97]
	v_pk_fma_f32 v[98:99], v[78:79], v[84:85], v[98:99]
	v_pk_fma_f32 v[78:79], v[78:79], v[88:89], v[80:81]
	v_add_f32_e32 v80, v98, v99
	v_add_f32_e32 v78, v78, v79
	s_waitcnt lgkmcnt(0)
	v_mov_b32_e32 v98, v95
	v_add_f32_dpp v80, v80, v80 row_ror:8 row_mask:0xf bank_mask:0xf bound_ctrl:1
	v_add_f32_dpp v78, v78, v78 row_ror:8 row_mask:0xf bank_mask:0xf bound_ctrl:1
	v_pk_mul_f32 v[22:23], v[20:21], v[86:87]
	v_add_f32_dpp v80, v80, v80 row_ror:4 row_mask:0xf bank_mask:0xf bound_ctrl:1
	v_add_f32_dpp v78, v78, v78 row_ror:4 row_mask:0xf bank_mask:0xf bound_ctrl:1
	v_pk_mul_f32 v[20:21], v[20:21], v[96:97]
	v_add_f32_dpp v80, v80, v80 row_ror:2 row_mask:0xf bank_mask:0xf bound_ctrl:1
	v_add_f32_dpp v78, v78, v78 row_ror:2 row_mask:0xf bank_mask:0xf bound_ctrl:1
	v_add_f32_e32 v3, v4, v5
	v_add_f32_dpp v80, v80, v80 row_ror:1 row_mask:0xf bank_mask:0xf bound_ctrl:1
	v_add_f32_dpp v78, v78, v78 row_ror:1 row_mask:0xf bank_mask:0xf bound_ctrl:1
	v_pk_mul_f32 v[100:101], v[70:71], v[80:81] op_sel_hi:[1,0]
	v_pk_mul_f32 v[70:71], v[70:71], v[78:79] op_sel_hi:[1,0]
	v_pk_fma_f32 v[100:101], v[74:75], v[94:95], v[100:101] op_sel_hi:[1,0,1]
	v_pk_fma_f32 v[70:71], v[74:75], v[98:99], v[70:71] op_sel_hi:[1,0,1]
	v_pk_fma_f32 v[22:23], v[18:19], v[84:85], v[22:23]
	v_pk_fma_f32 v[18:19], v[18:19], v[88:89], v[20:21]
	s_waitcnt vmcnt(4)
	v_pk_fma_f32 v[84:85], v[196:197], v[84:85], v[100:101]
	v_pk_mul_f32 v[80:81], v[72:73], v[80:81] op_sel_hi:[1,0]
	v_pk_fma_f32 v[88:89], v[196:197], v[88:89], v[70:71]
	v_pk_mul_f32 v[62:63], v[72:73], v[78:79] op_sel_hi:[1,0]
	ds_write2st64_b32 v111, v2, v3 offset0:224 offset1:225
	v_pk_fma_f32 v[80:81], v[76:77], v[94:95], v[80:81] op_sel_hi:[1,0,1]
	v_pk_fma_f32 v[62:63], v[76:77], v[98:99], v[62:63] op_sel_hi:[1,0,1]
	ds_read_b128 v[10:13], v118 offset:12800
	global_load_dwordx4 v[216:219], v118, s[56:57]
	s_add_u32 s56, s56, s58
	s_addc_u32 s57, s57, s59
	ds_read_b128 v[46:49], v118 offset:13312
	ds_read_b128 v[58:61], v118 offset:13568
	ds_read_b128 v[54:57], v118 offset:13824
	ds_read2_b32 v[82:83], v117 offset0:64 offset1:68
	v_pk_fma_f32 v[86:87], v[198:199], v[86:87], v[80:81]
	v_pk_fma_f32 v[96:97], v[198:199], v[96:97], v[62:63]
	s_waitcnt lgkmcnt(4)
	v_pk_mul_f32 v[98:99], v[12:13], v[86:87]
	v_pk_mul_f32 v[12:13], v[12:13], v[96:97]
	v_pk_fma_f32 v[98:99], v[10:11], v[84:85], v[98:99]
	v_pk_fma_f32 v[10:11], v[10:11], v[88:89], v[12:13]
	v_add_f32_e32 v12, v98, v99
	v_add_f32_e32 v10, v10, v11
	s_waitcnt lgkmcnt(0)
	v_mov_b32_e32 v100, v83
	v_add_f32_dpp v12, v12, v12 row_ror:8 row_mask:0xf bank_mask:0xf bound_ctrl:1
	v_add_f32_dpp v10, v10, v10 row_ror:8 row_mask:0xf bank_mask:0xf bound_ctrl:1
	v_add_f32_e32 v8, v14, v15
	v_add_f32_dpp v12, v12, v12 row_ror:4 row_mask:0xf bank_mask:0xf bound_ctrl:1
	v_add_f32_dpp v10, v10, v10 row_ror:4 row_mask:0xf bank_mask:0xf bound_ctrl:1
	v_add_f32_e32 v6, v6, v7
	v_add_f32_dpp v12, v12, v12 row_ror:2 row_mask:0xf bank_mask:0xf bound_ctrl:1
	v_add_f32_dpp v10, v10, v10 row_ror:2 row_mask:0xf bank_mask:0xf bound_ctrl:1
	ds_write2st64_b32 v111, v8, v6 offset0:232 offset1:233
	v_add_f32_dpp v12, v12, v12 row_ror:1 row_mask:0xf bank_mask:0xf bound_ctrl:1
	v_add_f32_dpp v98, v10, v10 row_ror:1 row_mask:0xf bank_mask:0xf bound_ctrl:1
	v_pk_mul_f32 v[10:11], v[46:47], v[12:13] op_sel_hi:[1,0]
	v_pk_mul_f32 v[46:47], v[46:47], v[98:99] op_sel_hi:[1,0]
	v_pk_fma_f32 v[10:11], v[58:59], v[82:83], v[10:11] op_sel_hi:[1,0,1]
	v_pk_mul_f32 v[12:13], v[48:49], v[12:13] op_sel_hi:[1,0]
	v_pk_fma_f32 v[46:47], v[58:59], v[100:101], v[46:47] op_sel_hi:[1,0,1]
	s_waitcnt vmcnt(4)
	v_pk_fma_f32 v[10:11], v[200:201], v[84:85], v[10:11]
	v_pk_fma_f32 v[12:13], v[60:61], v[82:83], v[12:13] op_sel_hi:[1,0,1]
	v_pk_fma_f32 v[2:3], v[200:201], v[88:89], v[46:47]
	v_pk_mul_f32 v[46:47], v[48:49], v[98:99] op_sel_hi:[1,0]
	v_pk_fma_f32 v[12:13], v[202:203], v[86:87], v[12:13]
	v_pk_fma_f32 v[46:47], v[60:61], v[100:101], v[46:47] op_sel_hi:[1,0,1]
	ds_read_b128 v[6:9], v118 offset:14080
	global_load_dwordx4 v[220:223], v118, s[56:57]
	s_add_u32 s56, s56, s58
	s_addc_u32 s57, s57, s59
	ds_read_b128 v[34:37], v118 offset:14592
	ds_read_b128 v[50:53], v118 offset:14848
	ds_read_b128 v[66:69], v118 offset:15104
	ds_read2_b32 v[92:93], v117 offset0:96 offset1:100
	v_pk_fma_f32 v[4:5], v[202:203], v[96:97], v[46:47]
	s_waitcnt lgkmcnt(4)
	v_pk_mul_f32 v[98:99], v[8:9], v[12:13]
	v_pk_mul_f32 v[8:9], v[8:9], v[4:5]
	v_pk_fma_f32 v[98:99], v[6:7], v[10:11], v[98:99]
	v_pk_fma_f32 v[6:7], v[6:7], v[2:3], v[8:9]
	v_add_f32_e32 v8, v98, v99
	v_add_f32_e32 v6, v6, v7
	s_waitcnt lgkmcnt(0)
	v_mov_b32_e32 v102, v93
	v_add_f32_dpp v8, v8, v8 row_ror:8 row_mask:0xf bank_mask:0xf bound_ctrl:1
	v_add_f32_dpp v6, v6, v6 row_ror:8 row_mask:0xf bank_mask:0xf bound_ctrl:1
	v_pk_mul_f32 v[48:49], v[56:57], v[4:5]
	v_add_f32_dpp v8, v8, v8 row_ror:4 row_mask:0xf bank_mask:0xf bound_ctrl:1
	v_add_f32_dpp v6, v6, v6 row_ror:4 row_mask:0xf bank_mask:0xf bound_ctrl:1
	v_pk_fma_f32 v[48:49], v[54:55], v[2:3], v[48:49]
	v_add_f32_dpp v8, v8, v8 row_ror:2 row_mask:0xf bank_mask:0xf bound_ctrl:1
	v_add_f32_dpp v6, v6, v6 row_ror:2 row_mask:0xf bank_mask:0xf bound_ctrl:1
	v_add_f32_e32 v20, v22, v23
	v_add_f32_dpp v8, v8, v8 row_ror:1 row_mask:0xf bank_mask:0xf bound_ctrl:1
	v_pk_mul_f32 v[98:99], v[34:35], v[8:9] op_sel_hi:[1,0]
	v_pk_mul_f32 v[8:9], v[36:37], v[8:9] op_sel_hi:[1,0]
	v_add_f32_dpp v6, v6, v6 row_ror:1 row_mask:0xf bank_mask:0xf bound_ctrl:1
	v_pk_fma_f32 v[8:9], v[52:53], v[92:93], v[8:9] op_sel_hi:[1,0,1]
	v_pk_fma_f32 v[98:99], v[50:51], v[92:93], v[98:99] op_sel_hi:[1,0,1]
	s_waitcnt vmcnt(4)
	v_pk_fma_f32 v[92:93], v[206:207], v[12:13], v[8:9]
	v_pk_mul_f32 v[8:9], v[34:35], v[6:7] op_sel_hi:[1,0]
	v_add_f32_e32 v18, v18, v19
	v_pk_fma_f32 v[8:9], v[50:51], v[102:103], v[8:9] op_sel_hi:[1,0,1]
	ds_write2st64_b32 v111, v20, v18 offset0:240 offset1:241
	v_pk_fma_f32 v[100:101], v[204:205], v[2:3], v[8:9]
	v_pk_mul_f32 v[2:3], v[36:37], v[6:7] op_sel_hi:[1,0]
	ds_read_b128 v[38:41], v118 offset:15360
	global_load_dwordx4 v[192:195], v118, s[56:57]
	s_add_u32 s56, s56, s58
	s_addc_u32 s57, s57, s59
	ds_read_b128 v[22:25], v118 offset:15872
	ds_read_b128 v[26:29], v118 offset:16128
	ds_read_b128 v[30:33], v118 offset:16384
	ds_read2_b32 v[90:91], v117 offset0:128 offset1:132
	v_pk_fma_f32 v[2:3], v[52:53], v[102:103], v[2:3] op_sel_hi:[1,0,1]
	v_pk_fma_f32 v[98:99], v[204:205], v[10:11], v[98:99]
	v_pk_fma_f32 v[52:53], v[206:207], v[4:5], v[2:3]
	v_pk_mul_f32 v[2:3], v[68:69], v[92:93]
	v_pk_mul_f32 v[4:5], v[68:69], v[52:53]
	v_pk_fma_f32 v[2:3], v[66:67], v[98:99], v[2:3]
	v_pk_fma_f32 v[4:5], v[66:67], v[100:101], v[4:5]
	s_waitcnt lgkmcnt(4)
	v_pk_mul_f32 v[66:67], v[40:41], v[92:93]
	v_pk_mul_f32 v[40:41], v[40:41], v[52:53]
	v_pk_fma_f32 v[66:67], v[38:39], v[98:99], v[66:67]
	v_pk_fma_f32 v[38:39], v[38:39], v[100:101], v[40:41]
	v_add_f32_e32 v40, v66, v67
	v_add_f32_e32 v38, v38, v39
	s_waitcnt lgkmcnt(0)
	v_mov_b32_e32 v66, v91
	v_add_f32_dpp v40, v40, v40 row_ror:8 row_mask:0xf bank_mask:0xf bound_ctrl:1
	v_add_f32_dpp v38, v38, v38 row_ror:8 row_mask:0xf bank_mask:0xf bound_ctrl:1
	v_pk_mul_f32 v[62:63], v[44:45], v[86:87]
	v_add_f32_dpp v40, v40, v40 row_ror:4 row_mask:0xf bank_mask:0xf bound_ctrl:1
	v_add_f32_dpp v38, v38, v38 row_ror:4 row_mask:0xf bank_mask:0xf bound_ctrl:1
	v_pk_mul_f32 v[44:45], v[44:45], v[96:97]
	v_add_f32_dpp v40, v40, v40 row_ror:2 row_mask:0xf bank_mask:0xf bound_ctrl:1
	v_add_f32_dpp v38, v38, v38 row_ror:2 row_mask:0xf bank_mask:0xf bound_ctrl:1
	v_pk_fma_f32 v[62:63], v[42:43], v[84:85], v[62:63]
	v_add_f32_dpp v40, v40, v40 row_ror:1 row_mask:0xf bank_mask:0xf bound_ctrl:1
	v_add_f32_dpp v38, v38, v38 row_ror:1 row_mask:0xf bank_mask:0xf bound_ctrl:1
	v_pk_mul_f32 v[68:69], v[22:23], v[40:41] op_sel_hi:[1,0]
	v_pk_mul_f32 v[22:23], v[22:23], v[38:39] op_sel_hi:[1,0]
	v_pk_fma_f32 v[68:69], v[26:27], v[90:91], v[68:69] op_sel_hi:[1,0,1]
	v_pk_fma_f32 v[22:23], v[26:27], v[66:67], v[22:23] op_sel_hi:[1,0,1]
	s_waitcnt vmcnt(4)
	v_pk_fma_f32 v[68:69], v[208:209], v[98:99], v[68:69]
	v_pk_mul_f32 v[40:41], v[24:25], v[40:41] op_sel_hi:[1,0]
	v_pk_fma_f32 v[18:19], v[208:209], v[100:101], v[22:23]
	v_pk_mul_f32 v[22:23], v[24:25], v[38:39] op_sel_hi:[1,0]
	v_pk_fma_f32 v[42:43], v[42:43], v[88:89], v[44:45]
	v_pk_mul_f32 v[46:47], v[56:57], v[12:13]
	v_pk_fma_f32 v[40:41], v[28:29], v[90:91], v[40:41] op_sel_hi:[1,0,1]
	v_pk_fma_f32 v[22:23], v[28:29], v[66:67], v[22:23] op_sel_hi:[1,0,1]
	v_add_f32_e32 v44, v62, v63
	v_add_f32_e32 v42, v42, v43
	v_pk_fma_f32 v[46:47], v[54:55], v[10:11], v[46:47]
	v_pk_fma_f32 v[40:41], v[210:211], v[92:93], v[40:41]
	v_pk_fma_f32 v[20:21], v[210:211], v[52:53], v[22:23]
	ds_write2st64_b32 v111, v44, v42 offset0:248 offset1:249
	v_add_f32_e32 v46, v46, v47
	v_add_f32_e32 v47, v48, v49
	v_pk_mul_f32 v[22:23], v[32:33], v[40:41]
	v_pk_mul_f32 v[24:25], v[32:33], v[20:21]
	ds_read_b128 v[78:81], v118 offset:16640
	global_load_dwordx4 v[196:199], v118, s[56:57]
	s_add_u32 s56, s56, s58
	s_addc_u32 s57, s57, s59
	ds_read_b128 v[62:65], v118 offset:17152
	ds_read_b128 v[70:73], v118 offset:17408
	ds_read_b128 v[74:77], v118 offset:17664
	ds_read2_b32 v[94:95], v117 offset0:160 offset1:164
	ds_write2st64_b32 v112, v46, v47 offset0:80 offset1:81
	v_add_f32_e32 v2, v2, v3
	v_add_f32_e32 v3, v4, v5
	v_pk_fma_f32 v[22:23], v[30:31], v[68:69], v[22:23]
	v_pk_fma_f32 v[24:25], v[30:31], v[18:19], v[24:25]
	ds_read_b128 v[86:89], v118 offset:17920
	global_load_dwordx4 v[200:203], v118, s[56:57]
	s_add_u32 s56, s56, s58
	s_addc_u32 s57, s57, s59
	ds_read_b128 v[54:57], v118 offset:18432
	ds_read_b128 v[58:61], v118 offset:18688
	ds_read_b128 v[82:85], v118 offset:18944
	ds_read2_b32 v[96:97], v117 offset0:192 offset1:196
	ds_write2st64_b32 v112, v2, v3 offset0:88 offset1:89
	v_add_f32_e32 v22, v22, v23
	v_add_f32_e32 v23, v24, v25
	ds_read_b128 v[34:37], v118 offset:19200
	global_load_dwordx4 v[204:207], v118, s[56:57]
	s_add_u32 s56, s56, s58
	s_addc_u32 s57, s57, s59
	ds_read_b128 v[6:9], v118 offset:19712
	ds_read_b128 v[14:17], v118 offset:19968
	ds_read_b128 v[10:13], v118 offset:20224
	ds_read2_b32 v[50:51], v117 offset0:224 offset1:228
	ds_write2st64_b32 v112, v22, v23 offset0:96 offset1:97
	s_waitcnt lgkmcnt(13)
	v_pk_mul_f32 v[22:23], v[80:81], v[40:41]
	v_pk_mul_f32 v[24:25], v[80:81], v[20:21]
	v_pk_fma_f32 v[22:23], v[78:79], v[68:69], v[22:23]
	v_pk_fma_f32 v[24:25], v[78:79], v[18:19], v[24:25]
	v_add_f32_e32 v22, v22, v23
	v_add_f32_e32 v23, v24, v25
	v_mov_b32_e32 v26, v95
	v_add_f32_dpp v22, v22, v22 row_ror:8 row_mask:0xf bank_mask:0xf bound_ctrl:1
	v_add_f32_dpp v23, v23, v23 row_ror:8 row_mask:0xf bank_mask:0xf bound_ctrl:1
	s_waitcnt lgkmcnt(7)
	v_mov_b32_e32 v32, v97
	v_add_f32_dpp v22, v22, v22 row_ror:4 row_mask:0xf bank_mask:0xf bound_ctrl:1
	v_add_f32_dpp v23, v23, v23 row_ror:4 row_mask:0xf bank_mask:0xf bound_ctrl:1
	s_nop 0
	v_add_f32_dpp v22, v22, v22 row_ror:2 row_mask:0xf bank_mask:0xf bound_ctrl:1
	v_add_f32_dpp v23, v23, v23 row_ror:2 row_mask:0xf bank_mask:0xf bound_ctrl:1
	s_nop 0
	v_add_f32_dpp v22, v22, v22 row_ror:1 row_mask:0xf bank_mask:0xf bound_ctrl:1
	v_add_f32_dpp v24, v23, v23 row_ror:1 row_mask:0xf bank_mask:0xf bound_ctrl:1
	v_pk_mul_f32 v[28:29], v[62:63], v[22:23] op_sel_hi:[1,0]
	v_pk_mul_f32 v[22:23], v[64:65], v[22:23] op_sel_hi:[1,0]
	v_pk_mul_f32 v[30:31], v[62:63], v[24:25] op_sel_hi:[1,0]
	v_pk_mul_f32 v[24:25], v[64:65], v[24:25] op_sel_hi:[1,0]
	v_pk_fma_f32 v[22:23], v[72:73], v[94:95], v[22:23] op_sel_hi:[1,0,1]
	v_pk_fma_f32 v[24:25], v[72:73], v[26:27], v[24:25] op_sel_hi:[1,0,1]
	v_pk_fma_f32 v[28:29], v[70:71], v[94:95], v[28:29] op_sel_hi:[1,0,1]
	s_waitcnt vmcnt(6)
	v_pk_fma_f32 v[22:23], v[214:215], v[40:41], v[22:23]
	v_pk_fma_f32 v[30:31], v[70:71], v[26:27], v[30:31] op_sel_hi:[1,0,1]
	v_pk_fma_f32 v[26:27], v[214:215], v[20:21], v[24:25]
	v_pk_fma_f32 v[28:29], v[212:213], v[68:69], v[28:29]
	v_pk_fma_f32 v[18:19], v[212:213], v[18:19], v[30:31]
	v_pk_mul_f32 v[20:21], v[76:77], v[22:23]
	v_pk_mul_f32 v[24:25], v[76:77], v[26:27]
	v_pk_fma_f32 v[20:21], v[74:75], v[28:29], v[20:21]
	v_pk_fma_f32 v[24:25], v[74:75], v[18:19], v[24:25]
	v_add_f32_e32 v20, v20, v21
	v_add_f32_e32 v21, v24, v25
	ds_write2st64_b32 v112, v20, v21 offset0:104 offset1:105
	ds_read_b32 v249, v246
	v_pk_mul_f32 v[20:21], v[88:89], v[22:23]
	v_pk_mul_f32 v[24:25], v[88:89], v[26:27]
	v_pk_fma_f32 v[20:21], v[86:87], v[28:29], v[20:21]
	v_pk_fma_f32 v[24:25], v[86:87], v[18:19], v[24:25]
	v_add_f32_e32 v20, v20, v21
	v_add_f32_e32 v21, v24, v25
	s_nop 0
	v_add_f32_dpp v20, v20, v20 row_ror:8 row_mask:0xf bank_mask:0xf bound_ctrl:1
	v_add_f32_dpp v21, v21, v21 row_ror:8 row_mask:0xf bank_mask:0xf bound_ctrl:1
	s_nop 0
	v_add_f32_dpp v20, v20, v20 row_ror:4 row_mask:0xf bank_mask:0xf bound_ctrl:1
	v_add_f32_dpp v21, v21, v21 row_ror:4 row_mask:0xf bank_mask:0xf bound_ctrl:1
	s_nop 0
	v_add_f32_dpp v20, v20, v20 row_ror:2 row_mask:0xf bank_mask:0xf bound_ctrl:1
	v_add_f32_dpp v21, v21, v21 row_ror:2 row_mask:0xf bank_mask:0xf bound_ctrl:1
	s_nop 0
	v_add_f32_dpp v20, v20, v20 row_ror:1 row_mask:0xf bank_mask:0xf bound_ctrl:1
	v_add_f32_dpp v30, v21, v21 row_ror:1 row_mask:0xf bank_mask:0xf bound_ctrl:1
	v_pk_mul_f32 v[24:25], v[54:55], v[20:21] op_sel_hi:[1,0]
	v_pk_mul_f32 v[20:21], v[56:57], v[20:21] op_sel_hi:[1,0]
	v_pk_fma_f32 v[24:25], v[58:59], v[96:97], v[24:25] op_sel_hi:[1,0,1]
	v_pk_fma_f32 v[20:21], v[60:61], v[96:97], v[20:21] op_sel_hi:[1,0,1]
	s_waitcnt vmcnt(5)
	v_pk_fma_f32 v[24:25], v[216:217], v[28:29], v[24:25]
	v_pk_fma_f32 v[22:23], v[218:219], v[22:23], v[20:21]
	v_pk_mul_f32 v[20:21], v[54:55], v[30:31] op_sel_hi:[1,0]
	s_nop 0
	v_pk_fma_f32 v[20:21], v[58:59], v[32:33], v[20:21] op_sel_hi:[1,0,1]
	s_nop 0
	v_pk_fma_f32 v[20:21], v[216:217], v[18:19], v[20:21]
	v_pk_mul_f32 v[18:19], v[56:57], v[30:31] op_sel_hi:[1,0]
	s_nop 0
	v_pk_fma_f32 v[18:19], v[60:61], v[32:33], v[18:19] op_sel_hi:[1,0,1]
	s_nop 0
	v_pk_fma_f32 v[18:19], v[218:219], v[26:27], v[18:19]
	v_pk_mul_f32 v[26:27], v[84:85], v[22:23]
	v_pk_mul_f32 v[28:29], v[84:85], v[18:19]
	v_pk_fma_f32 v[26:27], v[82:83], v[24:25], v[26:27]
	v_pk_fma_f32 v[28:29], v[82:83], v[20:21], v[28:29]
	v_add_f32_e32 v26, v26, v27
	v_add_f32_e32 v27, v28, v29
	ds_write2st64_b32 v112, v26, v27 offset0:112 offset1:113
	s_add_i32 s64, s4, 3
	s_waitcnt lgkmcnt(1)
	v_cmp_gt_u32_e32 vcc, s64, v249
	s_nop 0
	s_cbranch_vccnz .Lsflag_slow_3
.Lsflag_go_3:
	ds_read_b128 v[224:227], v118 offset:20480
	ds_read_b128 v[228:231], v118 offset:20992
	ds_read_b128 v[232:235], v118 offset:21248
	ds_read_b128 v[236:239], v118 offset:21504
	s_waitcnt lgkmcnt(5)
	v_pk_mul_f32 v[26:27], v[36:37], v[22:23]
	v_pk_mul_f32 v[28:29], v[36:37], v[18:19]
	v_pk_fma_f32 v[26:27], v[34:35], v[24:25], v[26:27]
	v_pk_fma_f32 v[30:31], v[34:35], v[20:21], v[28:29]
	v_add_f32_e32 v26, v26, v27
	s_nop 1
	v_add_f32_dpp v26, v26, v26 row_ror:8 row_mask:0xf bank_mask:0xf bound_ctrl:1
	s_nop 1
	v_add_f32_dpp v26, v26, v26 row_ror:4 row_mask:0xf bank_mask:0xf bound_ctrl:1
	s_nop 1
	v_add_f32_dpp v26, v26, v26 row_ror:2 row_mask:0xf bank_mask:0xf bound_ctrl:1
	s_nop 1
	v_add_f32_dpp v28, v26, v26 row_ror:1 row_mask:0xf bank_mask:0xf bound_ctrl:1
	v_add_f32_e32 v26, v30, v31
	s_waitcnt lgkmcnt(5)
	v_mov_b32_e32 v30, v51
	v_pk_mul_f32 v[32:33], v[6:7], v[28:29] op_sel_hi:[1,0]
	v_add_f32_dpp v26, v26, v26 row_ror:8 row_mask:0xf bank_mask:0xf bound_ctrl:1
	v_pk_fma_f32 v[32:33], v[14:15], v[50:51], v[32:33] op_sel_hi:[1,0,1]
	s_nop 0
	v_add_f32_dpp v26, v26, v26 row_ror:4 row_mask:0xf bank_mask:0xf bound_ctrl:1
	s_waitcnt vmcnt(4)
	v_pk_fma_f32 v[76:77], v[220:221], v[24:25], v[32:33]
	v_pk_mul_f32 v[24:25], v[8:9], v[28:29] op_sel_hi:[1,0]
	v_add_f32_dpp v26, v26, v26 row_ror:2 row_mask:0xf bank_mask:0xf bound_ctrl:1
	v_pk_fma_f32 v[24:25], v[16:17], v[50:51], v[24:25] op_sel_hi:[1,0,1]
	s_nop 0
	v_add_f32_dpp v26, v26, v26 row_ror:1 row_mask:0xf bank_mask:0xf bound_ctrl:1
	v_pk_mul_f32 v[6:7], v[6:7], v[26:27] op_sel_hi:[1,0]
	v_pk_fma_f32 v[78:79], v[222:223], v[22:23], v[24:25]
	v_pk_fma_f32 v[6:7], v[14:15], v[30:31], v[6:7] op_sel_hi:[1,0,1]
	s_nop 0
	v_pk_fma_f32 v[80:81], v[220:221], v[20:21], v[6:7]
	v_pk_mul_f32 v[2:3], v[8:9], v[26:27] op_sel_hi:[1,0]
	s_nop 0
	v_pk_fma_f32 v[2:3], v[16:17], v[30:31], v[2:3] op_sel_hi:[1,0,1]
	s_nop 0
	v_pk_fma_f32 v[92:93], v[222:223], v[18:19], v[2:3]
	v_pk_mul_f32 v[2:3], v[12:13], v[78:79]
	v_pk_mul_f32 v[4:5], v[12:13], v[92:93]
	v_pk_fma_f32 v[2:3], v[10:11], v[76:77], v[2:3]
	v_pk_fma_f32 v[4:5], v[10:11], v[80:81], v[4:5]
	v_add_f32_e32 v2, v2, v3
	v_add_f32_e32 v3, v4, v5
	ds_write2st64_b32 v112, v2, v3 offset0:120 offset1:121
	v_mov_b32_e32 v248, s64
	ds_write_b32 v247, v248
	global_load_dwordx4 v[208:211], v118, s[56:57]
	s_add_u32 s56, s56, s58
	s_addc_u32 s57, s57, s59
	ds_read2_b32 v[94:95], v120 offset1:4
	ds_read_b128 v[50:53], v118 offset:21760
	global_load_dwordx4 v[212:215], v118, s[56:57]
	s_add_u32 s56, s56, s58
	s_addc_u32 s57, s57, s59
	ds_read_b128 v[72:75], v118 offset:22272
	ds_read_b128 v[82:85], v118 offset:22528
	ds_read_b128 v[86:89], v118 offset:22784
	ds_read2_b32 v[96:97], v120 offset0:32 offset1:36
	ds_read_b128 v[62:65], v118 offset:23040
	global_load_dwordx4 v[216:219], v118, s[56:57]
	s_add_u32 s56, s56, s58
	s_addc_u32 s57, s57, s59
	ds_read_b128 v[54:57], v118 offset:23552
	ds_read_b128 v[58:61], v118 offset:23808
	ds_read_b128 v[14:17], v118 offset:24064
	ds_read2_b32 v[66:67], v120 offset0:64 offset1:68
	ds_read_b128 v[42:45], v118 offset:24320
	global_load_dwordx4 v[220:223], v118, s[56:57]
	s_add_u32 s56, s56, s58
	s_addc_u32 s57, s57, s59
	ds_read_b128 v[30:33], v118 offset:24832
	ds_read_b128 v[34:37], v118 offset:25088
	ds_read_b128 v[2:5], v118 offset:25344
	ds_read2_b32 v[90:91], v120 offset0:96 offset1:100
	s_waitcnt lgkmcnt(12)
	v_pk_mul_f32 v[98:99], v[226:227], v[78:79]
	v_pk_mul_f32 v[12:13], v[226:227], v[92:93]
	v_pk_fma_f32 v[98:99], v[224:225], v[76:77], v[98:99]
	v_pk_fma_f32 v[10:11], v[224:225], v[80:81], v[12:13]
	v_add_f32_e32 v12, v98, v99
	v_add_f32_e32 v10, v10, v11
	v_mov_b32_e32 v98, v95
	v_add_f32_dpp v12, v12, v12 row_ror:8 row_mask:0xf bank_mask:0xf bound_ctrl:1
	v_add_f32_dpp v10, v10, v10 row_ror:8 row_mask:0xf bank_mask:0xf bound_ctrl:1
	s_nop 0
	v_add_f32_dpp v12, v12, v12 row_ror:4 row_mask:0xf bank_mask:0xf bound_ctrl:1
	v_add_f32_dpp v10, v10, v10 row_ror:4 row_mask:0xf bank_mask:0xf bound_ctrl:1
	s_nop 0
	v_add_f32_dpp v12, v12, v12 row_ror:2 row_mask:0xf bank_mask:0xf bound_ctrl:1
	v_add_f32_dpp v10, v10, v10 row_ror:2 row_mask:0xf bank_mask:0xf bound_ctrl:1
	s_nop 0
	v_add_f32_dpp v12, v12, v12 row_ror:1 row_mask:0xf bank_mask:0xf bound_ctrl:1
	v_pk_mul_f32 v[100:101], v[228:229], v[12:13] op_sel_hi:[1,0]
	v_pk_mul_f32 v[12:13], v[230:231], v[12:13] op_sel_hi:[1,0]
	v_add_f32_dpp v10, v10, v10 row_ror:1 row_mask:0xf bank_mask:0xf bound_ctrl:1
	v_pk_fma_f32 v[100:101], v[232:233], v[94:95], v[100:101] op_sel_hi:[1,0,1]
	v_pk_fma_f32 v[12:13], v[234:235], v[94:95], v[12:13] op_sel_hi:[1,0,1]
	s_waitcnt vmcnt(7)
	v_pk_fma_f32 v[76:77], v[192:193], v[76:77], v[100:101]
	v_pk_fma_f32 v[100:101], v[194:195], v[78:79], v[12:13]
	v_pk_mul_f32 v[12:13], v[228:229], v[10:11] op_sel_hi:[1,0]
	v_pk_mul_f32 v[10:11], v[230:231], v[10:11] op_sel_hi:[1,0]
	v_pk_fma_f32 v[12:13], v[232:233], v[98:99], v[12:13] op_sel_hi:[1,0,1]
	v_pk_fma_f32 v[10:11], v[234:235], v[98:99], v[10:11] op_sel_hi:[1,0,1]
	v_pk_fma_f32 v[102:103], v[192:193], v[80:81], v[12:13]
	v_pk_fma_f32 v[92:93], v[194:195], v[92:93], v[10:11]
	v_pk_mul_f32 v[10:11], v[238:239], v[100:101]
	v_pk_mul_f32 v[12:13], v[238:239], v[92:93]
	v_pk_fma_f32 v[10:11], v[236:237], v[76:77], v[10:11]
	v_pk_fma_f32 v[12:13], v[236:237], v[102:103], v[12:13]
	v_pk_mul_f32 v[46:47], v[52:53], v[100:101]
	v_pk_mul_f32 v[48:49], v[52:53], v[92:93]
	v_pk_fma_f32 v[46:47], v[50:51], v[76:77], v[46:47]
	v_pk_fma_f32 v[48:49], v[50:51], v[102:103], v[48:49]
	v_add_f32_e32 v46, v46, v47
	v_add_f32_e32 v47, v48, v49
	s_waitcnt lgkmcnt(10)
	v_mov_b32_e32 v50, v97
	v_add_f32_dpp v46, v46, v46 row_ror:8 row_mask:0xf bank_mask:0xf bound_ctrl:1
	v_add_f32_dpp v47, v47, v47 row_ror:8 row_mask:0xf bank_mask:0xf bound_ctrl:1
	v_add_f32_e32 v10, v10, v11
	v_add_f32_dpp v46, v46, v46 row_ror:4 row_mask:0xf bank_mask:0xf bound_ctrl:1
	v_add_f32_dpp v47, v47, v47 row_ror:4 row_mask:0xf bank_mask:0xf bound_ctrl:1
	v_add_f32_e32 v11, v12, v13
	v_add_f32_dpp v46, v46, v46 row_ror:2 row_mask:0xf bank_mask:0xf bound_ctrl:1
	v_add_f32_dpp v47, v47, v47 row_ror:2 row_mask:0xf bank_mask:0xf bound_ctrl:1
	ds_write2st64_b32 v113, v10, v11 offset1:1
	v_add_f32_dpp v46, v46, v46 row_ror:1 row_mask:0xf bank_mask:0xf bound_ctrl:1
	v_add_f32_dpp v48, v47, v47 row_ror:1 row_mask:0xf bank_mask:0xf bound_ctrl:1
	v_pk_mul_f32 v[52:53], v[72:73], v[46:47] op_sel_hi:[1,0]
	v_pk_mul_f32 v[46:47], v[74:75], v[46:47] op_sel_hi:[1,0]
	v_pk_fma_f32 v[52:53], v[82:83], v[96:97], v[52:53] op_sel_hi:[1,0,1]
	v_pk_fma_f32 v[46:47], v[84:85], v[96:97], v[46:47] op_sel_hi:[1,0,1]
	s_waitcnt vmcnt(6)
	v_pk_fma_f32 v[98:99], v[196:197], v[76:77], v[52:53]
	v_pk_fma_f32 v[100:101], v[198:199], v[100:101], v[46:47]
	v_pk_mul_f32 v[46:47], v[72:73], v[48:49] op_sel_hi:[1,0]
	ds_read_b128 v[78:81], v118 offset:25600
	global_load_dwordx4 v[192:195], v118, s[56:57]
	s_add_u32 s56, s56, s58
	s_addc_u32 s57, s57, s59
	ds_read_b128 v[22:25], v118 offset:26112
	ds_read_b128 v[26:29], v118 offset:26368
	ds_read_b128 v[10:13], v118 offset:26624
	ds_read2_b32 v[94:95], v120 offset0:128 offset1:132
	v_pk_fma_f32 v[46:47], v[82:83], v[50:51], v[46:47] op_sel_hi:[1,0,1]
	s_nop 0
	v_pk_fma_f32 v[68:69], v[196:197], v[102:103], v[46:47]
	v_pk_mul_f32 v[46:47], v[74:75], v[48:49] op_sel_hi:[1,0]
	s_nop 0
	v_pk_fma_f32 v[46:47], v[84:85], v[50:51], v[46:47] op_sel_hi:[1,0,1]
	s_waitcnt lgkmcnt(12)
	v_pk_mul_f32 v[84:85], v[64:65], v[100:101]
	v_pk_fma_f32 v[82:83], v[198:199], v[92:93], v[46:47]
	v_pk_fma_f32 v[84:85], v[62:63], v[98:99], v[84:85]
	v_pk_mul_f32 v[64:65], v[64:65], v[82:83]
	v_pk_mul_f32 v[46:47], v[88:89], v[100:101]
	v_pk_fma_f32 v[62:63], v[62:63], v[68:69], v[64:65]
	v_add_f32_e32 v64, v84, v85
	v_add_f32_e32 v62, v62, v63
	s_waitcnt lgkmcnt(11)
	v_mov_b32_e32 v84, v67
	v_add_f32_dpp v64, v64, v64 row_ror:8 row_mask:0xf bank_mask:0xf bound_ctrl:1
	v_add_f32_dpp v62, v62, v62 row_ror:8 row_mask:0xf bank_mask:0xf bound_ctrl:1
	v_pk_mul_f32 v[48:49], v[88:89], v[82:83]
	v_add_f32_dpp v64, v64, v64 row_ror:4 row_mask:0xf bank_mask:0xf bound_ctrl:1
	v_add_f32_dpp v62, v62, v62 row_ror:4 row_mask:0xf bank_mask:0xf bound_ctrl:1
	v_pk_fma_f32 v[46:47], v[86:87], v[98:99], v[46:47]
	v_add_f32_dpp v64, v64, v64 row_ror:2 row_mask:0xf bank_mask:0xf bound_ctrl:1
	v_add_f32_dpp v62, v62, v62 row_ror:2 row_mask:0xf bank_mask:0xf bound_ctrl:1
	v_pk_fma_f32 v[48:49], v[86:87], v[68:69], v[48:49]
	v_add_f32_dpp v64, v64, v64 row_ror:1 row_mask:0xf bank_mask:0xf bound_ctrl:1
	v_add_f32_dpp v62, v62, v62 row_ror:1 row_mask:0xf bank_mask:0xf bound_ctrl:1
	v_pk_mul_f32 v[92:93], v[54:55], v[64:65] op_sel_hi:[1,0]
	v_pk_mul_f32 v[54:55], v[54:55], v[62:63] op_sel_hi:[1,0]
	v_pk_fma_f32 v[92:93], v[58:59], v[66:67], v[92:93] op_sel_hi:[1,0,1]
	v_pk_fma_f32 v[54:55], v[58:59], v[84:85], v[54:55] op_sel_hi:[1,0,1]
	s_waitcnt vmcnt(6)
	v_pk_fma_f32 v[92:93], v[200:201], v[98:99], v[92:93]
	v_pk_mul_f32 v[64:65], v[56:57], v[64:65] op_sel_hi:[1,0]
	v_pk_fma_f32 v[58:59], v[200:201], v[68:69], v[54:55]
	v_pk_mul_f32 v[38:39], v[56:57], v[62:63] op_sel_hi:[1,0]
	v_pk_fma_f32 v[64:65], v[60:61], v[66:67], v[64:65] op_sel_hi:[1,0,1]
	v_pk_fma_f32 v[38:39], v[60:61], v[84:85], v[38:39] op_sel_hi:[1,0,1]
	v_pk_fma_f32 v[64:65], v[202:203], v[100:101], v[64:65]
	v_pk_fma_f32 v[60:61], v[202:203], v[82:83], v[38:39]
	s_waitcnt lgkmcnt(10)
	v_pk_mul_f32 v[62:63], v[44:45], v[64:65]
	v_pk_mul_f32 v[44:45], v[44:45], v[60:61]
	v_pk_fma_f32 v[62:63], v[42:43], v[92:93], v[62:63]
	v_pk_fma_f32 v[42:43], v[42:43], v[58:59], v[44:45]
	v_add_f32_e32 v44, v62, v63
	v_add_f32_e32 v42, v42, v43
	s_waitcnt lgkmcnt(6)
	v_mov_b32_e32 v62, v91
	v_add_f32_dpp v44, v44, v44 row_ror:8 row_mask:0xf bank_mask:0xf bound_ctrl:1
	v_add_f32_dpp v42, v42, v42 row_ror:8 row_mask:0xf bank_mask:0xf bound_ctrl:1
	v_pk_mul_f32 v[38:39], v[16:17], v[64:65]
	v_add_f32_dpp v44, v44, v44 row_ror:4 row_mask:0xf bank_mask:0xf bound_ctrl:1
	v_add_f32_dpp v42, v42, v42 row_ror:4 row_mask:0xf bank_mask:0xf bound_ctrl:1
	v_pk_mul_f32 v[16:17], v[16:17], v[60:61]
	v_add_f32_dpp v44, v44, v44 row_ror:2 row_mask:0xf bank_mask:0xf bound_ctrl:1
	v_add_f32_dpp v42, v42, v42 row_ror:2 row_mask:0xf bank_mask:0xf bound_ctrl:1
	v_add_f32_e32 v46, v46, v47
	v_add_f32_dpp v44, v44, v44 row_ror:1 row_mask:0xf bank_mask:0xf bound_ctrl:1
	v_add_f32_dpp v42, v42, v42 row_ror:1 row_mask:0xf bank_mask:0xf bound_ctrl:1
	v_pk_mul_f32 v[100:101], v[30:31], v[44:45] op_sel_hi:[1,0]
	v_pk_mul_f32 v[30:31], v[30:31], v[42:43] op_sel_hi:[1,0]
	v_pk_fma_f32 v[100:101], v[34:35], v[90:91], v[100:101] op_sel_hi:[1,0,1]
	v_pk_fma_f32 v[30:31], v[34:35], v[62:63], v[30:31] op_sel_hi:[1,0,1]
	s_waitcnt vmcnt(5)
	v_pk_fma_f32 v[100:101], v[204:205], v[92:93], v[100:101]
	v_pk_mul_f32 v[44:45], v[32:33], v[44:45] op_sel_hi:[1,0]
	v_pk_fma_f32 v[30:31], v[204:205], v[58:59], v[30:31]
	v_pk_mul_f32 v[6:7], v[32:33], v[42:43] op_sel_hi:[1,0]
	v_pk_fma_f32 v[44:45], v[36:37], v[90:91], v[44:45] op_sel_hi:[1,0,1]
	v_pk_fma_f32 v[6:7], v[36:37], v[62:63], v[6:7] op_sel_hi:[1,0,1]
	v_pk_fma_f32 v[90:91], v[206:207], v[64:65], v[44:45]
	v_pk_fma_f32 v[32:33], v[206:207], v[60:61], v[6:7]
	s_waitcnt lgkmcnt(4)
	v_pk_mul_f32 v[34:35], v[80:81], v[90:91]
	v_pk_mul_f32 v[36:37], v[80:81], v[32:33]
	v_pk_fma_f32 v[34:35], v[78:79], v[100:101], v[34:35]
	v_pk_fma_f32 v[36:37], v[78:79], v[30:31], v[36:37]
	v_add_f32_e32 v34, v34, v35
	v_add_f32_e32 v35, v36, v37
	s_waitcnt lgkmcnt(0)
	v_mov_b32_e32 v78, v95
	v_add_f32_dpp v34, v34, v34 row_ror:8 row_mask:0xf bank_mask:0xf bound_ctrl:1
	v_add_f32_dpp v35, v35, v35 row_ror:8 row_mask:0xf bank_mask:0xf bound_ctrl:1
	v_pk_mul_f32 v[6:7], v[4:5], v[90:91]
	v_add_f32_dpp v34, v34, v34 row_ror:4 row_mask:0xf bank_mask:0xf bound_ctrl:1
	v_add_f32_dpp v35, v35, v35 row_ror:4 row_mask:0xf bank_mask:0xf bound_ctrl:1
	v_pk_fma_f32 v[6:7], v[2:3], v[100:101], v[6:7]
	v_add_f32_dpp v34, v34, v34 row_ror:2 row_mask:0xf bank_mask:0xf bound_ctrl:1
	v_add_f32_dpp v35, v35, v35 row_ror:2 row_mask:0xf bank_mask:0xf bound_ctrl:1
	v_add_f32_e32 v47, v48, v49
	v_add_f32_dpp v34, v34, v34 row_ror:1 row_mask:0xf bank_mask:0xf bound_ctrl:1
	v_add_f32_dpp v36, v35, v35 row_ror:1 row_mask:0xf bank_mask:0xf bound_ctrl:1
	v_pk_mul_f32 v[80:81], v[22:23], v[34:35] op_sel_hi:[1,0]
	v_pk_mul_f32 v[22:23], v[22:23], v[36:37] op_sel_hi:[1,0]
	v_pk_fma_f32 v[80:81], v[26:27], v[94:95], v[80:81] op_sel_hi:[1,0,1]
	v_pk_fma_f32 v[22:23], v[26:27], v[78:79], v[22:23] op_sel_hi:[1,0,1]
	s_waitcnt vmcnt(4)
	v_pk_fma_f32 v[80:81], v[208:209], v[100:101], v[80:81]
	v_pk_mul_f32 v[34:35], v[24:25], v[34:35] op_sel_hi:[1,0]
	v_pk_fma_f32 v[100:101], v[208:209], v[30:31], v[22:23]
	v_pk_mul_f32 v[18:19], v[24:25], v[36:37] op_sel_hi:[1,0]
	v_pk_fma_f32 v[34:35], v[28:29], v[94:95], v[34:35] op_sel_hi:[1,0,1]
	v_pk_fma_f32 v[18:19], v[28:29], v[78:79], v[18:19] op_sel_hi:[1,0,1]
	v_pk_fma_f32 v[38:39], v[14:15], v[92:93], v[38:39]
	v_pk_fma_f32 v[14:15], v[14:15], v[58:59], v[16:17]
	v_pk_mul_f32 v[4:5], v[4:5], v[32:33]
	v_pk_fma_f32 v[94:95], v[210:211], v[90:91], v[34:35]
	v_pk_fma_f32 v[78:79], v[210:211], v[32:33], v[18:19]
	ds_write2st64_b32 v113, v46, v47 offset0:8 offset1:9
	v_add_f32_e32 v16, v38, v39
	v_add_f32_e32 v14, v14, v15
	v_pk_fma_f32 v[2:3], v[2:3], v[30:31], v[4:5]
	v_pk_mul_f32 v[18:19], v[12:13], v[94:95]
	v_pk_mul_f32 v[12:13], v[12:13], v[78:79]
	ds_read_b128 v[86:89], v118 offset:26880
	global_load_dwordx4 v[196:199], v118, s[56:57]
	s_add_u32 s56, s56, s58
	s_addc_u32 s57, s57, s59
	ds_read_b128 v[70:73], v118 offset:27392
	ds_read_b128 v[74:77], v118 offset:27648
	ds_read_b128 v[46:49], v118 offset:27904
	ds_read2_b32 v[96:97], v120 offset0:160 offset1:164
	ds_write2st64_b32 v113, v16, v14 offset0:16 offset1:17
	v_add_f32_e32 v4, v6, v7
	v_add_f32_e32 v2, v2, v3
	v_pk_fma_f32 v[18:19], v[10:11], v[80:81], v[18:19]
	v_pk_fma_f32 v[10:11], v[10:11], v[100:101], v[12:13]
	ds_read_b128 v[82:85], v118 offset:28160
	global_load_dwordx4 v[200:203], v118, s[56:57]
	s_add_u32 s56, s56, s58
	s_addc_u32 s57, s57, s59
	ds_read_b128 v[54:57], v118 offset:28672
	ds_read_b128 v[66:69], v118 offset:28928
	ds_read_b128 v[14:17], v118 offset:29184
	ds_read2_b32 v[98:99], v120 offset0:192 offset1:196
	ds_write2st64_b32 v113, v4, v2 offset0:24 offset1:25
	v_add_f32_e32 v12, v18, v19
	v_add_f32_e32 v10, v10, v11
	ds_read_b128 v[62:65], v118 offset:29440
	global_load_dwordx4 v[204:207], v118, s[56:57]
	s_add_u32 s56, s56, s58
	s_addc_u32 s57, s57, s59
	ds_read_b128 v[42:45], v118 offset:29952
	ds_read_b128 v[58:61], v118 offset:30208
	ds_read_b128 v[2:5], v118 offset:30464
	ds_read2_b32 v[92:93], v120 offset0:224 offset1:228
	ds_write2st64_b32 v113, v12, v10 offset0:32 offset1:33
	s_waitcnt lgkmcnt(13)
	v_pk_mul_f32 v[10:11], v[88:89], v[94:95]
	v_pk_mul_f32 v[12:13], v[88:89], v[78:79]
	v_pk_fma_f32 v[10:11], v[86:87], v[80:81], v[10:11]
	v_pk_fma_f32 v[12:13], v[86:87], v[100:101], v[12:13]
	v_add_f32_e32 v10, v10, v11
	v_add_f32_e32 v11, v12, v13
	v_mov_b32_e32 v86, v97
	v_add_f32_dpp v10, v10, v10 row_ror:8 row_mask:0xf bank_mask:0xf bound_ctrl:1
	v_add_f32_dpp v11, v11, v11 row_ror:8 row_mask:0xf bank_mask:0xf bound_ctrl:1
	ds_read_b128 v[34:37], v118 offset:30720
	global_load_dwordx4 v[208:211], v118, s[56:57]
	s_add_u32 s56, s56, s58
	s_addc_u32 s57, s57, s59
	ds_read_b128 v[26:29], v118 offset:31232
	ds_read_b128 v[30:33], v118 offset:31488
	ds_read_b128 v[18:21], v118 offset:31744
	ds_read2_b32 v[90:91], v114 offset1:4
	v_add_f32_dpp v10, v10, v10 row_ror:4 row_mask:0xf bank_mask:0xf bound_ctrl:1
	v_add_f32_dpp v11, v11, v11 row_ror:4 row_mask:0xf bank_mask:0xf bound_ctrl:1
	s_nop 0
	v_add_f32_dpp v10, v10, v10 row_ror:2 row_mask:0xf bank_mask:0xf bound_ctrl:1
	v_add_f32_dpp v11, v11, v11 row_ror:2 row_mask:0xf bank_mask:0xf bound_ctrl:1
	s_nop 0
	v_add_f32_dpp v10, v10, v10 row_ror:1 row_mask:0xf bank_mask:0xf bound_ctrl:1
	v_add_f32_dpp v12, v11, v11 row_ror:1 row_mask:0xf bank_mask:0xf bound_ctrl:1
	v_pk_mul_f32 v[88:89], v[70:71], v[10:11] op_sel_hi:[1,0]
	v_pk_mul_f32 v[10:11], v[72:73], v[10:11] op_sel_hi:[1,0]
	v_pk_mul_f32 v[70:71], v[70:71], v[12:13] op_sel_hi:[1,0]
	v_pk_fma_f32 v[10:11], v[76:77], v[96:97], v[10:11] op_sel_hi:[1,0,1]
	v_pk_mul_f32 v[12:13], v[72:73], v[12:13] op_sel_hi:[1,0]
	v_pk_fma_f32 v[88:89], v[74:75], v[96:97], v[88:89] op_sel_hi:[1,0,1]
	s_waitcnt vmcnt(7)
	v_pk_fma_f32 v[10:11], v[214:215], v[94:95], v[10:11]
	v_pk_fma_f32 v[12:13], v[76:77], v[86:87], v[12:13] op_sel_hi:[1,0,1]
	v_pk_fma_f32 v[88:89], v[212:213], v[80:81], v[88:89]
	v_pk_fma_f32 v[70:71], v[74:75], v[86:87], v[70:71] op_sel_hi:[1,0,1]
	v_pk_fma_f32 v[12:13], v[214:215], v[78:79], v[12:13]
	s_waitcnt lgkmcnt(12)
	v_pk_mul_f32 v[96:97], v[84:85], v[10:11]
	v_pk_fma_f32 v[94:95], v[212:213], v[100:101], v[70:71]
	v_pk_fma_f32 v[96:97], v[82:83], v[88:89], v[96:97]
	v_pk_mul_f32 v[84:85], v[84:85], v[12:13]
	v_pk_mul_f32 v[50:51], v[48:49], v[10:11]
	v_pk_fma_f32 v[82:83], v[82:83], v[94:95], v[84:85]
	v_add_f32_e32 v84, v96, v97
	v_add_f32_e32 v82, v82, v83
	v_mov_b32_e32 v96, v99
	v_add_f32_dpp v84, v84, v84 row_ror:8 row_mask:0xf bank_mask:0xf bound_ctrl:1
	v_add_f32_dpp v82, v82, v82 row_ror:8 row_mask:0xf bank_mask:0xf bound_ctrl:1
	v_pk_mul_f32 v[48:49], v[48:49], v[12:13]
	v_add_f32_dpp v84, v84, v84 row_ror:4 row_mask:0xf bank_mask:0xf bound_ctrl:1
	v_add_f32_dpp v82, v82, v82 row_ror:4 row_mask:0xf bank_mask:0xf bound_ctrl:1
	v_pk_fma_f32 v[50:51], v[46:47], v[88:89], v[50:51]
	v_add_f32_dpp v84, v84, v84 row_ror:2 row_mask:0xf bank_mask:0xf bound_ctrl:1
	v_add_f32_dpp v82, v82, v82 row_ror:2 row_mask:0xf bank_mask:0xf bound_ctrl:1
	v_pk_fma_f32 v[46:47], v[46:47], v[94:95], v[48:49]
	v_add_f32_dpp v84, v84, v84 row_ror:1 row_mask:0xf bank_mask:0xf bound_ctrl:1
	v_pk_mul_f32 v[100:101], v[54:55], v[84:85] op_sel_hi:[1,0]
	v_pk_mul_f32 v[84:85], v[56:57], v[84:85] op_sel_hi:[1,0]
	v_add_f32_dpp v82, v82, v82 row_ror:1 row_mask:0xf bank_mask:0xf bound_ctrl:1
	v_pk_fma_f32 v[84:85], v[68:69], v[98:99], v[84:85] op_sel_hi:[1,0,1]
	v_pk_fma_f32 v[100:101], v[66:67], v[98:99], v[100:101] op_sel_hi:[1,0,1]
	s_waitcnt vmcnt(6)
	v_pk_fma_f32 v[98:99], v[218:219], v[10:11], v[84:85]
	v_pk_mul_f32 v[10:11], v[54:55], v[82:83] op_sel_hi:[1,0]
	v_pk_fma_f32 v[88:89], v[216:217], v[88:89], v[100:101]
	v_pk_fma_f32 v[10:11], v[66:67], v[96:97], v[10:11] op_sel_hi:[1,0,1]
	s_waitcnt lgkmcnt(10)
	v_pk_mul_f32 v[84:85], v[64:65], v[98:99]
	v_pk_fma_f32 v[94:95], v[216:217], v[94:95], v[10:11]
	v_pk_mul_f32 v[10:11], v[56:57], v[82:83] op_sel_hi:[1,0]
	v_pk_fma_f32 v[84:85], v[62:63], v[88:89], v[84:85]
	v_pk_fma_f32 v[10:11], v[68:69], v[96:97], v[10:11] op_sel_hi:[1,0,1]
	s_waitcnt lgkmcnt(6)
	v_mov_b32_e32 v100, v93
	v_pk_fma_f32 v[96:97], v[218:219], v[12:13], v[10:11]
	v_pk_mul_f32 v[10:11], v[16:17], v[98:99]
	v_pk_mul_f32 v[64:65], v[64:65], v[96:97]
	v_pk_mul_f32 v[12:13], v[16:17], v[96:97]
	v_pk_fma_f32 v[62:63], v[62:63], v[94:95], v[64:65]
	v_add_f32_e32 v64, v84, v85
	v_add_f32_e32 v62, v62, v63
	v_pk_fma_f32 v[12:13], v[14:15], v[94:95], v[12:13]
	v_add_f32_dpp v64, v64, v64 row_ror:8 row_mask:0xf bank_mask:0xf bound_ctrl:1
	v_add_f32_dpp v62, v62, v62 row_ror:8 row_mask:0xf bank_mask:0xf bound_ctrl:1
	v_pk_fma_f32 v[10:11], v[14:15], v[88:89], v[10:11]
	v_add_f32_dpp v64, v64, v64 row_ror:4 row_mask:0xf bank_mask:0xf bound_ctrl:1
	v_add_f32_dpp v62, v62, v62 row_ror:4 row_mask:0xf bank_mask:0xf bound_ctrl:1
	v_add_f32_e32 v48, v50, v51
	v_add_f32_dpp v64, v64, v64 row_ror:2 row_mask:0xf bank_mask:0xf bound_ctrl:1
	v_add_f32_dpp v62, v62, v62 row_ror:2 row_mask:0xf bank_mask:0xf bound_ctrl:1
	v_add_f32_e32 v46, v46, v47
	v_add_f32_dpp v64, v64, v64 row_ror:1 row_mask:0xf bank_mask:0xf bound_ctrl:1
	v_add_f32_dpp v62, v62, v62 row_ror:1 row_mask:0xf bank_mask:0xf bound_ctrl:1
	v_pk_mul_f32 v[84:85], v[42:43], v[64:65] op_sel_hi:[1,0]
	v_pk_mul_f32 v[42:43], v[42:43], v[62:63] op_sel_hi:[1,0]
	v_pk_fma_f32 v[84:85], v[58:59], v[92:93], v[84:85] op_sel_hi:[1,0,1]
	v_pk_fma_f32 v[42:43], v[58:59], v[100:101], v[42:43] op_sel_hi:[1,0,1]
	s_waitcnt vmcnt(5)
	v_pk_fma_f32 v[84:85], v[220:221], v[88:89], v[84:85]
	v_pk_mul_f32 v[64:65], v[44:45], v[64:65] op_sel_hi:[1,0]
	v_pk_fma_f32 v[94:95], v[220:221], v[94:95], v[42:43]
	v_pk_mul_f32 v[6:7], v[44:45], v[62:63] op_sel_hi:[1,0]
	v_pk_fma_f32 v[64:65], v[60:61], v[92:93], v[64:65] op_sel_hi:[1,0,1]
	v_pk_fma_f32 v[6:7], v[60:61], v[100:101], v[6:7] op_sel_hi:[1,0,1]
	v_pk_fma_f32 v[88:89], v[222:223], v[98:99], v[64:65]
	v_pk_fma_f32 v[96:97], v[222:223], v[96:97], v[6:7]
	s_waitcnt lgkmcnt(4)
	v_pk_mul_f32 v[98:99], v[36:37], v[88:89]
	v_pk_mul_f32 v[36:37], v[36:37], v[96:97]
	v_pk_fma_f32 v[98:99], v[34:35], v[84:85], v[98:99]
	v_pk_fma_f32 v[34:35], v[34:35], v[94:95], v[36:37]
	v_add_f32_e32 v36, v98, v99
	v_add_f32_e32 v34, v34, v35
	s_waitcnt lgkmcnt(0)
	v_mov_b32_e32 v98, v91
	v_add_f32_dpp v36, v36, v36 row_ror:8 row_mask:0xf bank_mask:0xf bound_ctrl:1
	v_add_f32_dpp v34, v34, v34 row_ror:8 row_mask:0xf bank_mask:0xf bound_ctrl:1
	v_pk_mul_f32 v[6:7], v[4:5], v[88:89]
	v_add_f32_dpp v36, v36, v36 row_ror:4 row_mask:0xf bank_mask:0xf bound_ctrl:1
	v_add_f32_dpp v34, v34, v34 row_ror:4 row_mask:0xf bank_mask:0xf bound_ctrl:1
	v_pk_mul_f32 v[4:5], v[4:5], v[96:97]
	v_add_f32_dpp v36, v36, v36 row_ror:2 row_mask:0xf bank_mask:0xf bound_ctrl:1
	v_add_f32_dpp v34, v34, v34 row_ror:2 row_mask:0xf bank_mask:0xf bound_ctrl:1
	v_pk_fma_f32 v[6:7], v[2:3], v[84:85], v[6:7]
	v_add_f32_dpp v36, v36, v36 row_ror:1 row_mask:0xf bank_mask:0xf bound_ctrl:1
	v_add_f32_dpp v34, v34, v34 row_ror:1 row_mask:0xf bank_mask:0xf bound_ctrl:1
	v_pk_mul_f32 v[100:101], v[26:27], v[36:37] op_sel_hi:[1,0]
	v_pk_mul_f32 v[26:27], v[26:27], v[34:35] op_sel_hi:[1,0]
	v_pk_fma_f32 v[100:101], v[30:31], v[90:91], v[100:101] op_sel_hi:[1,0,1]
	v_pk_fma_f32 v[26:27], v[30:31], v[98:99], v[26:27] op_sel_hi:[1,0,1]
	v_pk_fma_f32 v[2:3], v[2:3], v[94:95], v[4:5]
	s_waitcnt vmcnt(4)
	v_pk_fma_f32 v[84:85], v[192:193], v[84:85], v[100:101]
	v_pk_mul_f32 v[36:37], v[28:29], v[36:37] op_sel_hi:[1,0]
	v_pk_fma_f32 v[94:95], v[192:193], v[94:95], v[26:27]
	v_pk_mul_f32 v[22:23], v[28:29], v[34:35] op_sel_hi:[1,0]
	ds_write2st64_b32 v113, v48, v46 offset0:40 offset1:41
	v_pk_fma_f32 v[36:37], v[32:33], v[90:91], v[36:37] op_sel_hi:[1,0,1]
	v_pk_fma_f32 v[22:23], v[32:33], v[98:99], v[22:23] op_sel_hi:[1,0,1]
	ds_read_b128 v[78:81], v118 offset:32000
	global_load_dwordx4 v[212:215], v118, s[56:57]
	s_add_u32 s56, s56, s58
	s_addc_u32 s57, s57, s59
	ds_read_b128 v[70:73], v118 offset:32512
	ds_read_b128 v[74:77], v118 offset:32768
	ds_read_b128 v[46:49], v118 offset:33024
	ds_read2_b32 v[86:87], v114 offset0:32 offset1:36
	v_pk_fma_f32 v[88:89], v[194:195], v[88:89], v[36:37]
	v_pk_fma_f32 v[96:97], v[194:195], v[96:97], v[22:23]
	s_waitcnt lgkmcnt(4)
	v_pk_mul_f32 v[98:99], v[80:81], v[88:89]
	v_pk_mul_f32 v[80:81], v[80:81], v[96:97]
	v_pk_fma_f32 v[98:99], v[78:79], v[84:85], v[98:99]
	v_pk_fma_f32 v[78:79], v[78:79], v[94:95], v[80:81]
	v_add_f32_e32 v80, v98, v99
	v_add_f32_e32 v78, v78, v79
	s_waitcnt lgkmcnt(0)
	v_mov_b32_e32 v98, v87
	v_add_f32_dpp v80, v80, v80 row_ror:8 row_mask:0xf bank_mask:0xf bound_ctrl:1
	v_add_f32_dpp v78, v78, v78 row_ror:8 row_mask:0xf bank_mask:0xf bound_ctrl:1
	v_pk_mul_f32 v[22:23], v[20:21], v[88:89]
	v_add_f32_dpp v80, v80, v80 row_ror:4 row_mask:0xf bank_mask:0xf bound_ctrl:1
	v_add_f32_dpp v78, v78, v78 row_ror:4 row_mask:0xf bank_mask:0xf bound_ctrl:1
	v_add_f32_e32 v10, v10, v11
	v_add_f32_dpp v80, v80, v80 row_ror:2 row_mask:0xf bank_mask:0xf bound_ctrl:1
	v_add_f32_dpp v78, v78, v78 row_ror:2 row_mask:0xf bank_mask:0xf bound_ctrl:1
	v_add_f32_e32 v11, v12, v13
	v_add_f32_dpp v80, v80, v80 row_ror:1 row_mask:0xf bank_mask:0xf bound_ctrl:1
	v_add_f32_dpp v78, v78, v78 row_ror:1 row_mask:0xf bank_mask:0xf bound_ctrl:1
	v_pk_mul_f32 v[100:101], v[70:71], v[80:81] op_sel_hi:[1,0]
	v_pk_mul_f32 v[80:81], v[72:73], v[80:81] op_sel_hi:[1,0]
	v_pk_mul_f32 v[70:71], v[70:71], v[78:79] op_sel_hi:[1,0]
	v_pk_fma_f32 v[100:101], v[74:75], v[86:87], v[100:101] op_sel_hi:[1,0,1]
	v_pk_fma_f32 v[80:81], v[76:77], v[86:87], v[80:81] op_sel_hi:[1,0,1]
	v_pk_fma_f32 v[70:71], v[74:75], v[98:99], v[70:71] op_sel_hi:[1,0,1]
	v_pk_fma_f32 v[22:23], v[18:19], v[84:85], v[22:23]
	s_waitcnt vmcnt(4)
	v_pk_fma_f32 v[84:85], v[196:197], v[84:85], v[100:101]
	v_pk_fma_f32 v[86:87], v[198:199], v[88:89], v[80:81]
	v_pk_fma_f32 v[88:89], v[196:197], v[94:95], v[70:71]
	v_pk_mul_f32 v[50:51], v[72:73], v[78:79] op_sel_hi:[1,0]
	ds_write2st64_b32 v113, v10, v11 offset0:48 offset1:49
	v_pk_fma_f32 v[50:51], v[76:77], v[98:99], v[50:51] op_sel_hi:[1,0,1]
	ds_read_b128 v[14:17], v118 offset:33280
	global_load_dwordx4 v[216:219], v118, s[56:57]
	s_add_u32 s56, s56, s58
	s_addc_u32 s57, s57, s59
	ds_read_b128 v[38:41], v118 offset:33792
	ds_read_b128 v[54:57], v118 offset:34048
	ds_read_b128 v[66:69], v118 offset:34304
	ds_read2_b32 v[82:83], v114 offset0:64 offset1:68
	v_pk_mul_f32 v[20:21], v[20:21], v[96:97]
	v_pk_fma_f32 v[96:97], v[198:199], v[96:97], v[50:51]
	s_waitcnt lgkmcnt(4)
	v_pk_mul_f32 v[98:99], v[16:17], v[86:87]
	v_pk_mul_f32 v[16:17], v[16:17], v[96:97]
	v_pk_fma_f32 v[98:99], v[14:15], v[84:85], v[98:99]
	v_pk_fma_f32 v[14:15], v[14:15], v[88:89], v[16:17]
	v_add_f32_e32 v16, v98, v99
	v_add_f32_e32 v14, v14, v15
	s_waitcnt lgkmcnt(0)
	v_mov_b32_e32 v100, v83
	v_add_f32_dpp v16, v16, v16 row_ror:8 row_mask:0xf bank_mask:0xf bound_ctrl:1
	v_add_f32_dpp v14, v14, v14 row_ror:8 row_mask:0xf bank_mask:0xf bound_ctrl:1
	v_add_f32_e32 v4, v6, v7
	v_add_f32_dpp v16, v16, v16 row_ror:4 row_mask:0xf bank_mask:0xf bound_ctrl:1
	v_add_f32_dpp v14, v14, v14 row_ror:4 row_mask:0xf bank_mask:0xf bound_ctrl:1
	v_add_f32_e32 v2, v2, v3
	v_add_f32_dpp v16, v16, v16 row_ror:2 row_mask:0xf bank_mask:0xf bound_ctrl:1
	v_add_f32_dpp v14, v14, v14 row_ror:2 row_mask:0xf bank_mask:0xf bound_ctrl:1
	ds_write2st64_b32 v113, v4, v2 offset0:56 offset1:57
	v_add_f32_dpp v16, v16, v16 row_ror:1 row_mask:0xf bank_mask:0xf bound_ctrl:1
	v_add_f32_dpp v98, v14, v14 row_ror:1 row_mask:0xf bank_mask:0xf bound_ctrl:1
	v_pk_mul_f32 v[14:15], v[38:39], v[16:17] op_sel_hi:[1,0]
	v_pk_mul_f32 v[38:39], v[38:39], v[98:99] op_sel_hi:[1,0]
	v_pk_fma_f32 v[14:15], v[54:55], v[82:83], v[14:15] op_sel_hi:[1,0,1]
	v_pk_mul_f32 v[16:17], v[40:41], v[16:17] op_sel_hi:[1,0]
	v_pk_fma_f32 v[38:39], v[54:55], v[100:101], v[38:39] op_sel_hi:[1,0,1]
	s_waitcnt vmcnt(4)
	v_pk_fma_f32 v[14:15], v[200:201], v[84:85], v[14:15]
	v_pk_fma_f32 v[16:17], v[56:57], v[82:83], v[16:17] op_sel_hi:[1,0,1]
	v_pk_fma_f32 v[10:11], v[200:201], v[88:89], v[38:39]
	v_pk_mul_f32 v[38:39], v[40:41], v[98:99] op_sel_hi:[1,0]
	v_pk_fma_f32 v[16:17], v[202:203], v[86:87], v[16:17]
	v_pk_fma_f32 v[38:39], v[56:57], v[100:101], v[38:39] op_sel_hi:[1,0,1]
	ds_read_b128 v[6:9], v118 offset:34560
	global_load_dwordx4 v[220:223], v118, s[56:57]
	s_add_u32 s56, s56, s58
	s_addc_u32 s57, s57, s59
	ds_read_b128 v[42:45], v118 offset:35072
	ds_read_b128 v[58:61], v118 offset:35328
	ds_read_b128 v[62:65], v118 offset:35584
	ds_read2_b32 v[92:93], v114 offset0:96 offset1:100
	v_pk_fma_f32 v[12:13], v[202:203], v[96:97], v[38:39]
	s_waitcnt lgkmcnt(4)
	v_pk_mul_f32 v[98:99], v[8:9], v[16:17]
	v_pk_mul_f32 v[8:9], v[8:9], v[12:13]
	v_pk_fma_f32 v[98:99], v[6:7], v[14:15], v[98:99]
	v_pk_fma_f32 v[6:7], v[6:7], v[10:11], v[8:9]
	v_add_f32_e32 v8, v98, v99
	v_add_f32_e32 v6, v6, v7
	s_waitcnt lgkmcnt(0)
	v_mov_b32_e32 v102, v93
	v_add_f32_dpp v8, v8, v8 row_ror:8 row_mask:0xf bank_mask:0xf bound_ctrl:1
	v_add_f32_dpp v6, v6, v6 row_ror:8 row_mask:0xf bank_mask:0xf bound_ctrl:1
	v_pk_fma_f32 v[18:19], v[18:19], v[94:95], v[20:21]
	v_add_f32_dpp v8, v8, v8 row_ror:4 row_mask:0xf bank_mask:0xf bound_ctrl:1
	v_add_f32_dpp v6, v6, v6 row_ror:4 row_mask:0xf bank_mask:0xf bound_ctrl:1
	v_add_f32_e32 v20, v22, v23
	v_add_f32_dpp v8, v8, v8 row_ror:2 row_mask:0xf bank_mask:0xf bound_ctrl:1
	v_add_f32_dpp v6, v6, v6 row_ror:2 row_mask:0xf bank_mask:0xf bound_ctrl:1
	v_add_f32_e32 v18, v18, v19
	v_add_f32_dpp v8, v8, v8 row_ror:1 row_mask:0xf bank_mask:0xf bound_ctrl:1
	v_pk_mul_f32 v[98:99], v[42:43], v[8:9] op_sel_hi:[1,0]
	v_pk_mul_f32 v[8:9], v[44:45], v[8:9] op_sel_hi:[1,0]
	v_add_f32_dpp v6, v6, v6 row_ror:1 row_mask:0xf bank_mask:0xf bound_ctrl:1
	v_pk_fma_f32 v[8:9], v[60:61], v[92:93], v[8:9] op_sel_hi:[1,0,1]
	v_pk_fma_f32 v[98:99], v[58:59], v[92:93], v[98:99] op_sel_hi:[1,0,1]
	s_waitcnt vmcnt(4)
	v_pk_fma_f32 v[92:93], v[206:207], v[16:17], v[8:9]
	v_pk_mul_f32 v[8:9], v[42:43], v[6:7] op_sel_hi:[1,0]
	v_pk_fma_f32 v[98:99], v[204:205], v[14:15], v[98:99]
	v_pk_fma_f32 v[8:9], v[58:59], v[102:103], v[8:9] op_sel_hi:[1,0,1]
	ds_write2st64_b32 v113, v20, v18 offset0:64 offset1:65
	v_pk_fma_f32 v[100:101], v[204:205], v[10:11], v[8:9]
	v_pk_mul_f32 v[2:3], v[44:45], v[6:7] op_sel_hi:[1,0]
	ds_read_b128 v[34:37], v118 offset:35840
	global_load_dwordx4 v[192:195], v118, s[56:57]
	s_add_u32 s56, s56, s58
	s_addc_u32 s57, s57, s59
	ds_read_b128 v[22:25], v118 offset:36352
	ds_read_b128 v[26:29], v118 offset:36608
	ds_read_b128 v[30:33], v118 offset:36864
	ds_read2_b32 v[90:91], v114 offset0:128 offset1:132
	v_pk_fma_f32 v[2:3], v[60:61], v[102:103], v[2:3] op_sel_hi:[1,0,1]
	v_pk_mul_f32 v[50:51], v[48:49], v[86:87]
	v_pk_fma_f32 v[60:61], v[206:207], v[12:13], v[2:3]
	v_pk_mul_f32 v[2:3], v[64:65], v[92:93]
	v_pk_mul_f32 v[4:5], v[64:65], v[60:61]
	v_pk_fma_f32 v[2:3], v[62:63], v[98:99], v[2:3]
	v_pk_fma_f32 v[4:5], v[62:63], v[100:101], v[4:5]
	s_waitcnt lgkmcnt(4)
	v_pk_mul_f32 v[62:63], v[36:37], v[92:93]
	v_pk_mul_f32 v[36:37], v[36:37], v[60:61]
	v_pk_fma_f32 v[62:63], v[34:35], v[98:99], v[62:63]
	v_pk_fma_f32 v[34:35], v[34:35], v[100:101], v[36:37]
	v_add_f32_e32 v36, v62, v63
	v_add_f32_e32 v34, v34, v35
	s_waitcnt lgkmcnt(0)
	v_mov_b32_e32 v62, v91
	v_add_f32_dpp v36, v36, v36 row_ror:8 row_mask:0xf bank_mask:0xf bound_ctrl:1
	v_add_f32_dpp v34, v34, v34 row_ror:8 row_mask:0xf bank_mask:0xf bound_ctrl:1
	v_pk_mul_f32 v[48:49], v[48:49], v[96:97]
	v_add_f32_dpp v36, v36, v36 row_ror:4 row_mask:0xf bank_mask:0xf bound_ctrl:1
	v_add_f32_dpp v34, v34, v34 row_ror:4 row_mask:0xf bank_mask:0xf bound_ctrl:1
	v_pk_fma_f32 v[50:51], v[46:47], v[84:85], v[50:51]
	v_add_f32_dpp v36, v36, v36 row_ror:2 row_mask:0xf bank_mask:0xf bound_ctrl:1
	v_add_f32_dpp v34, v34, v34 row_ror:2 row_mask:0xf bank_mask:0xf bound_ctrl:1
	v_pk_fma_f32 v[46:47], v[46:47], v[88:89], v[48:49]
	v_add_f32_dpp v36, v36, v36 row_ror:1 row_mask:0xf bank_mask:0xf bound_ctrl:1
	v_add_f32_dpp v34, v34, v34 row_ror:1 row_mask:0xf bank_mask:0xf bound_ctrl:1
	v_pk_mul_f32 v[64:65], v[22:23], v[36:37] op_sel_hi:[1,0]
	v_pk_mul_f32 v[22:23], v[22:23], v[34:35] op_sel_hi:[1,0]
	v_pk_fma_f32 v[64:65], v[26:27], v[90:91], v[64:65] op_sel_hi:[1,0,1]
	v_pk_fma_f32 v[22:23], v[26:27], v[62:63], v[22:23] op_sel_hi:[1,0,1]
	s_waitcnt vmcnt(4)
	v_pk_fma_f32 v[64:65], v[208:209], v[98:99], v[64:65]
	v_pk_mul_f32 v[36:37], v[24:25], v[36:37] op_sel_hi:[1,0]
	v_pk_fma_f32 v[18:19], v[208:209], v[100:101], v[22:23]
	v_pk_mul_f32 v[22:23], v[24:25], v[34:35] op_sel_hi:[1,0]
	v_pk_mul_f32 v[38:39], v[68:69], v[16:17]
	v_pk_mul_f32 v[40:41], v[68:69], v[12:13]
	v_pk_fma_f32 v[36:37], v[28:29], v[90:91], v[36:37] op_sel_hi:[1,0,1]
	v_pk_fma_f32 v[22:23], v[28:29], v[62:63], v[22:23] op_sel_hi:[1,0,1]
	v_add_f32_e32 v48, v50, v51
	v_add_f32_e32 v46, v46, v47
	v_pk_fma_f32 v[38:39], v[66:67], v[14:15], v[38:39]
	v_pk_fma_f32 v[40:41], v[66:67], v[10:11], v[40:41]
	v_pk_fma_f32 v[36:37], v[210:211], v[92:93], v[36:37]
	v_pk_fma_f32 v[20:21], v[210:211], v[60:61], v[22:23]
	ds_write2st64_b32 v113, v48, v46 offset0:72 offset1:73
	v_add_f32_e32 v38, v38, v39
	v_add_f32_e32 v39, v40, v41
	v_pk_mul_f32 v[22:23], v[32:33], v[36:37]
	v_pk_mul_f32 v[24:25], v[32:33], v[20:21]
	ds_read_b128 v[78:81], v118 offset:37120
	global_load_dwordx4 v[196:199], v118, s[56:57]
	s_add_u32 s56, s56, s58
	s_addc_u32 s57, s57, s59
	ds_read_b128 v[50:53], v118 offset:37632
	ds_read_b128 v[70:73], v118 offset:37888
	ds_read_b128 v[74:77], v118 offset:38144
	ds_read2_b32 v[94:95], v114 offset0:160 offset1:164
	ds_write2st64_b32 v113, v38, v39 offset0:80 offset1:81
	v_add_f32_e32 v2, v2, v3
	v_add_f32_e32 v3, v4, v5
	v_pk_fma_f32 v[22:23], v[30:31], v[64:65], v[22:23]
	v_pk_fma_f32 v[24:25], v[30:31], v[18:19], v[24:25]
	ds_read_b128 v[86:89], v118 offset:38400
	global_load_dwordx4 v[200:203], v118, s[56:57]
	s_add_u32 s56, s56, s58
	s_addc_u32 s57, s57, s59
	ds_read_b128 v[54:57], v118 offset:38912
	ds_read_b128 v[66:69], v118 offset:39168
	ds_read_b128 v[82:85], v118 offset:39424
	ds_read2_b32 v[96:97], v114 offset0:192 offset1:196
	ds_write2st64_b32 v113, v2, v3 offset0:88 offset1:89
	v_add_f32_e32 v22, v22, v23
	v_add_f32_e32 v23, v24, v25
	ds_read_b128 v[42:45], v118 offset:39680
	global_load_dwordx4 v[204:207], v118, s[56:57]
	s_add_u32 s56, s56, s58
	s_addc_u32 s57, s57, s59
	ds_read_b128 v[10:13], v118 offset:40192
	ds_read_b128 v[6:9], v118 offset:40448
	ds_read_b128 v[14:17], v118 offset:40704
	ds_read2_b32 v[58:59], v114 offset0:224 offset1:228
	ds_write2st64_b32 v113, v22, v23 offset0:96 offset1:97
	s_waitcnt lgkmcnt(13)
	v_pk_mul_f32 v[22:23], v[80:81], v[36:37]
	v_pk_mul_f32 v[24:25], v[80:81], v[20:21]
	v_pk_fma_f32 v[22:23], v[78:79], v[64:65], v[22:23]
	v_pk_fma_f32 v[24:25], v[78:79], v[18:19], v[24:25]
	v_add_f32_e32 v22, v22, v23
	v_add_f32_e32 v23, v24, v25
	v_mov_b32_e32 v26, v95
	v_add_f32_dpp v22, v22, v22 row_ror:8 row_mask:0xf bank_mask:0xf bound_ctrl:1
	v_add_f32_dpp v23, v23, v23 row_ror:8 row_mask:0xf bank_mask:0xf bound_ctrl:1
	s_waitcnt lgkmcnt(7)
	v_mov_b32_e32 v32, v97
	v_add_f32_dpp v22, v22, v22 row_ror:4 row_mask:0xf bank_mask:0xf bound_ctrl:1
	v_add_f32_dpp v23, v23, v23 row_ror:4 row_mask:0xf bank_mask:0xf bound_ctrl:1
	s_nop 0
	v_add_f32_dpp v22, v22, v22 row_ror:2 row_mask:0xf bank_mask:0xf bound_ctrl:1
	v_add_f32_dpp v23, v23, v23 row_ror:2 row_mask:0xf bank_mask:0xf bound_ctrl:1
	s_nop 0
	v_add_f32_dpp v22, v22, v22 row_ror:1 row_mask:0xf bank_mask:0xf bound_ctrl:1
	v_add_f32_dpp v24, v23, v23 row_ror:1 row_mask:0xf bank_mask:0xf bound_ctrl:1
	v_pk_mul_f32 v[28:29], v[50:51], v[22:23] op_sel_hi:[1,0]
	v_pk_mul_f32 v[22:23], v[52:53], v[22:23] op_sel_hi:[1,0]
	v_pk_mul_f32 v[30:31], v[50:51], v[24:25] op_sel_hi:[1,0]
	v_pk_mul_f32 v[24:25], v[52:53], v[24:25] op_sel_hi:[1,0]
	v_pk_fma_f32 v[22:23], v[72:73], v[94:95], v[22:23] op_sel_hi:[1,0,1]
	v_pk_fma_f32 v[24:25], v[72:73], v[26:27], v[24:25] op_sel_hi:[1,0,1]
	v_pk_fma_f32 v[28:29], v[70:71], v[94:95], v[28:29] op_sel_hi:[1,0,1]
	s_waitcnt vmcnt(6)
	v_pk_fma_f32 v[22:23], v[214:215], v[36:37], v[22:23]
	v_pk_fma_f32 v[30:31], v[70:71], v[26:27], v[30:31] op_sel_hi:[1,0,1]
	v_pk_fma_f32 v[26:27], v[214:215], v[20:21], v[24:25]
	v_pk_fma_f32 v[28:29], v[212:213], v[64:65], v[28:29]
	v_pk_fma_f32 v[18:19], v[212:213], v[18:19], v[30:31]
	v_pk_mul_f32 v[20:21], v[76:77], v[22:23]
	v_pk_mul_f32 v[24:25], v[76:77], v[26:27]
	v_pk_fma_f32 v[20:21], v[74:75], v[28:29], v[20:21]
	v_pk_fma_f32 v[24:25], v[74:75], v[18:19], v[24:25]
	v_add_f32_e32 v20, v20, v21
	v_add_f32_e32 v21, v24, v25
	ds_write2st64_b32 v113, v20, v21 offset0:104 offset1:105
	ds_read_b32 v249, v246
	v_pk_mul_f32 v[20:21], v[88:89], v[22:23]
	v_pk_mul_f32 v[24:25], v[88:89], v[26:27]
	v_pk_fma_f32 v[20:21], v[86:87], v[28:29], v[20:21]
	v_pk_fma_f32 v[24:25], v[86:87], v[18:19], v[24:25]
	v_add_f32_e32 v20, v20, v21
	v_add_f32_e32 v21, v24, v25
	s_nop 0
	v_add_f32_dpp v20, v20, v20 row_ror:8 row_mask:0xf bank_mask:0xf bound_ctrl:1
	v_add_f32_dpp v21, v21, v21 row_ror:8 row_mask:0xf bank_mask:0xf bound_ctrl:1
	s_nop 0
	v_add_f32_dpp v20, v20, v20 row_ror:4 row_mask:0xf bank_mask:0xf bound_ctrl:1
	v_add_f32_dpp v21, v21, v21 row_ror:4 row_mask:0xf bank_mask:0xf bound_ctrl:1
	s_nop 0
	v_add_f32_dpp v20, v20, v20 row_ror:2 row_mask:0xf bank_mask:0xf bound_ctrl:1
	v_add_f32_dpp v21, v21, v21 row_ror:2 row_mask:0xf bank_mask:0xf bound_ctrl:1
	s_nop 0
	v_add_f32_dpp v20, v20, v20 row_ror:1 row_mask:0xf bank_mask:0xf bound_ctrl:1
	v_add_f32_dpp v30, v21, v21 row_ror:1 row_mask:0xf bank_mask:0xf bound_ctrl:1
	v_pk_mul_f32 v[24:25], v[54:55], v[20:21] op_sel_hi:[1,0]
	v_pk_mul_f32 v[20:21], v[56:57], v[20:21] op_sel_hi:[1,0]
	v_pk_fma_f32 v[24:25], v[66:67], v[96:97], v[24:25] op_sel_hi:[1,0,1]
	v_pk_fma_f32 v[20:21], v[68:69], v[96:97], v[20:21] op_sel_hi:[1,0,1]
	s_waitcnt vmcnt(5)
	v_pk_fma_f32 v[24:25], v[216:217], v[28:29], v[24:25]
	v_pk_fma_f32 v[22:23], v[218:219], v[22:23], v[20:21]
	v_pk_mul_f32 v[20:21], v[54:55], v[30:31] op_sel_hi:[1,0]
	s_nop 0
	v_pk_fma_f32 v[20:21], v[66:67], v[32:33], v[20:21] op_sel_hi:[1,0,1]
	s_nop 0
	v_pk_fma_f32 v[20:21], v[216:217], v[18:19], v[20:21]
	v_pk_mul_f32 v[18:19], v[56:57], v[30:31] op_sel_hi:[1,0]
	s_nop 0
	v_pk_fma_f32 v[18:19], v[68:69], v[32:33], v[18:19] op_sel_hi:[1,0,1]
	s_nop 0
	v_pk_fma_f32 v[18:19], v[218:219], v[26:27], v[18:19]
	v_pk_mul_f32 v[26:27], v[84:85], v[22:23]
	v_pk_mul_f32 v[28:29], v[84:85], v[18:19]
	v_pk_fma_f32 v[26:27], v[82:83], v[24:25], v[26:27]
	v_pk_fma_f32 v[28:29], v[82:83], v[20:21], v[28:29]
	v_add_f32_e32 v26, v26, v27
	v_add_f32_e32 v27, v28, v29
	ds_write2st64_b32 v113, v26, v27 offset0:112 offset1:113
	s_add_i32 s64, s4, 4
	s_waitcnt lgkmcnt(1)
	v_cmp_gt_u32_e32 vcc, s64, v249
	s_nop 0
	s_cbranch_vccnz .Lsflag_slow_4
.Lsflag_go_4:
	ds_read_b128 v[224:227], v118
	ds_read_b128 v[228:231], v118 offset:512
	ds_read_b128 v[232:235], v118 offset:768
	ds_read_b128 v[236:239], v118 offset:1024
	s_waitcnt lgkmcnt(5)
	v_pk_mul_f32 v[26:27], v[44:45], v[22:23]
	v_pk_mul_f32 v[28:29], v[44:45], v[18:19]
	v_pk_fma_f32 v[26:27], v[42:43], v[24:25], v[26:27]
	v_pk_fma_f32 v[30:31], v[42:43], v[20:21], v[28:29]
	v_add_f32_e32 v26, v26, v27
	s_nop 1
	v_add_f32_dpp v26, v26, v26 row_ror:8 row_mask:0xf bank_mask:0xf bound_ctrl:1
	s_nop 1
	v_add_f32_dpp v26, v26, v26 row_ror:4 row_mask:0xf bank_mask:0xf bound_ctrl:1
	s_nop 1
	v_add_f32_dpp v26, v26, v26 row_ror:2 row_mask:0xf bank_mask:0xf bound_ctrl:1
	s_nop 1
	v_add_f32_dpp v28, v26, v26 row_ror:1 row_mask:0xf bank_mask:0xf bound_ctrl:1
	v_add_f32_e32 v26, v30, v31
	s_waitcnt lgkmcnt(5)
	v_mov_b32_e32 v30, v59
	v_pk_mul_f32 v[32:33], v[10:11], v[28:29] op_sel_hi:[1,0]
	v_add_f32_dpp v26, v26, v26 row_ror:8 row_mask:0xf bank_mask:0xf bound_ctrl:1
	v_pk_fma_f32 v[32:33], v[6:7], v[58:59], v[32:33] op_sel_hi:[1,0,1]
	v_pk_mul_f32 v[28:29], v[12:13], v[28:29] op_sel_hi:[1,0]
	v_add_f32_dpp v26, v26, v26 row_ror:4 row_mask:0xf bank_mask:0xf bound_ctrl:1
	s_waitcnt vmcnt(4)
	v_pk_fma_f32 v[24:25], v[220:221], v[24:25], v[32:33]
	v_pk_fma_f32 v[28:29], v[8:9], v[58:59], v[28:29] op_sel_hi:[1,0,1]
	v_add_f32_dpp v26, v26, v26 row_ror:2 row_mask:0xf bank_mask:0xf bound_ctrl:1
	v_pk_fma_f32 v[22:23], v[222:223], v[22:23], v[28:29]
	s_nop 0
	v_add_f32_dpp v26, v26, v26 row_ror:1 row_mask:0xf bank_mask:0xf bound_ctrl:1
	v_pk_mul_f32 v[10:11], v[10:11], v[26:27] op_sel_hi:[1,0]
	s_nop 0
	v_pk_fma_f32 v[6:7], v[6:7], v[30:31], v[10:11] op_sel_hi:[1,0,1]
	s_nop 0
	v_pk_fma_f32 v[6:7], v[220:221], v[20:21], v[6:7]
	v_pk_mul_f32 v[2:3], v[12:13], v[26:27] op_sel_hi:[1,0]
	s_nop 0
	v_pk_fma_f32 v[2:3], v[8:9], v[30:31], v[2:3] op_sel_hi:[1,0,1]
	s_nop 0
	v_pk_fma_f32 v[8:9], v[222:223], v[18:19], v[2:3]
	v_pk_mul_f32 v[2:3], v[16:17], v[22:23]
	v_pk_mul_f32 v[4:5], v[16:17], v[8:9]
	v_pk_fma_f32 v[2:3], v[14:15], v[24:25], v[2:3]
	v_pk_fma_f32 v[4:5], v[14:15], v[6:7], v[4:5]
	v_add_f32_e32 v2, v2, v3
	v_add_f32_e32 v3, v4, v5
	ds_write2st64_b32 v113, v2, v3 offset0:120 offset1:121
	v_mov_b32_e32 v248, s64
	ds_write_b32 v247, v248
	s_cmpk_gt_u32 s4, 0x1fb
	s_cbranch_scc0 .LBB0_833
	s_branch .LBB0_834
